# rename-safe N=1 handoff without the s_setprio 2 raise for the post-barrier MFMA
# speedup vs baseline: 1.0009x; 1.0009x over previous
; #define PG8_STAGE(bufoff, gbase, voff) do { _Pragma("unroll") for (int _i = 0; _i < 2; ++_i) \
;         asm volatile("s_mov_b32 m0, %2\n\ts_nop 0\n\tglobal_load_lds_dwordx4 %0, %1" :: "v"((voff)[_i]), "s"((const char*)(gbase)), "s"(ldsbase + (unsigned)(bufoff) + ldsw + (unsigned)_i * 8192u) : "memory", "m0"); } while (0)
; #define PG8_LDA(dst, b, h) do { _Pragma("unroll") for (int m = 0; m < 4; ++m) _Pragma("unroll") for (int k = 0; k < 2; ++k) dst[m][k] = *(const PG8_LAS bf16x8*)(lds + PG8_SA(b, h) + aoff + m * 2048 + k * 1024); } while (0)
; #define PG8_LDB(dst, b, h) do { _Pragma("unroll") for (int n = 0; n < 2; ++n) _Pragma("unroll") for (int k = 0; k < 2; ++k) dst[n][k] = *(const PG8_LAS bf16x8*)(lds + PG8_SB(b, h) + boff + n * 2048 + k * 1024); } while (0)
; #define PG8_MMA(ai, bj, At, Bt) do { __builtin_amdgcn_s_setprio(1); _Pragma("unroll") for (int m = 0; m < 4; ++m) _Pragma("unroll") for (int n = 0; n < 2; ++n) _Pragma("unroll") for (int k = 0; k < 2; ++k) \
;         acc[ai][bj][m][n] = __builtin_amdgcn_mfma_f32_16x16x32_bf16(Bt[n][k], At[m][k], acc[ai][bj][m][n], 0, 0, 0); __builtin_amdgcn_s_setprio(0); } while (0)
; template <class Epi, class Sched, bool ALIGN_EPI = false, bool SP2 = false>
; __device__ __forceinline__ void gemm_phase(PG8_LAS unsigned char* lds, const Gemm g, const Sched& S, const Epi& E) {
;     ...
;             const bool last = (t == nt - 2);
;             const char* a1 = cA + (size_t)(t + 1) * kstep;
;             const char* a2 = last ? nA : cA + (size_t)(t + 2) * kstep; const char* b2 = last ? nB : cB + (size_t)(t + 2) * kstep;
;             const char* a3 = a2 + kstep; const char* b3 = b2 + kstep;
;             if (last && has_next) S.a_ready(nxt);
;             if constexpr (epi_has_mid<Epi>::value) { if (t == Epi::MID_T) E.mid(acc, cur, wr, wc, fr, fq); }
;             if constexpr (SP2) {
;             PG8_LDB(B0, 0, 0); PG8_LDB(B1, 0, 1); PG8_SCHED; PG8_LDA(At, 0, 0); PG8_STAGE(PG8_SA(1, 1), a1 + hstep, voffA);
;             PG8_WAIT_V(8); PG8_WAIT_L(0); PG8_BAR; PG8_MMA(0, 0, At, B0); PG8_MMA(0, 1, At, B1); PG8_BAR; PG8_SCHED;
;             PG8_LDA(At, 0, 1); PG8_STAGE(PG8_SB(0, 0), b2, voffB); PG8_STAGE(PG8_SB(0, 1), b2 + hstep, voffB); PG8_STAGE(PG8_SA(0, 0), a2, voffA);
;             PG8_WAIT_V(8); PG8_WAIT_L(0); PG8_BAR; PG8_MMA(1, 0, At, B0); PG8_MMA(1, 1, At, B1); PG8_BAR; PG8_SCHED;
.LBB0_138:
	ds_read_b128 v[148:151], v142
	ds_read_b128 v[152:155], v142 offset:1024
	ds_read_b128 v[156:159], v142 offset:2048
	ds_read_b128 v[160:163], v142 offset:3072
	ds_read_b128 v[164:167], v143
	ds_read_b128 v[168:171], v143 offset:1024
	ds_read_b128 v[172:175], v143 offset:2048
	ds_read_b128 v[176:179], v143 offset:3072
	s_add_u32 s62, s66, 0x100
	s_addc_u32 s63, s67, 0
	s_cmp_eq_u32 s96, 60
	s_cselect_b32 s86, s92, s62
	s_cselect_b32 s87, s13, s63
	s_cselect_b32 s84, s93, s94
	s_cselect_b32 s85, s11, s95
	s_add_u32 s76, s86, 0x80
	s_addc_u32 s77, s87, 0
	ds_read_b128 v[180:183], v144
	ds_read_b128 v[184:187], v144 offset:1024
	ds_read_b128 v[188:191], v144 offset:2048
	ds_read_b128 v[192:195], v144 offset:3072
	ds_read_b128 v[196:199], v144 offset:4096
	ds_read_b128 v[200:203], v144 offset:5120
	ds_read_b128 v[204:207], v144 offset:6144
	ds_read_b128 v[208:211], v144 offset:7168
	s_add_u32 s66, s66, 0x100080
	s_addc_u32 s67, s67, 0
	s_mov_b32 m0, s83
	s_nop 0
	global_load_lds_dwordx4 v136, s[66:67]
	s_nop 0
	s_mov_b32 m0, s88
	s_nop 0
	global_load_lds_dwordx4 v138, s[66:67]
	s_waitcnt vmcnt(8)
	s_waitcnt lgkmcnt(0)
	s_barrier
	s_setprio 1
	s_waitcnt lgkmcnt(7)
	v_mfma_f32_16x16x32_bf16 v[126:129], v[148:151], v[180:183], v[126:129]
	v_mfma_f32_16x16x32_bf16 v[122:125], v[156:159], v[180:183], v[122:125]
	s_waitcnt lgkmcnt(5)
	v_mfma_f32_16x16x32_bf16 v[110:113], v[148:151], v[188:191], v[110:113]
	v_mfma_f32_16x16x32_bf16 v[106:109], v[156:159], v[188:191], v[106:109]
	s_waitcnt lgkmcnt(3)
	v_mfma_f32_16x16x32_bf16 v[94:97], v[148:151], v[196:199], v[94:97]
	v_mfma_f32_16x16x32_bf16 v[90:93], v[156:159], v[196:199], v[90:93]
	s_waitcnt lgkmcnt(1)
	v_mfma_f32_16x16x32_bf16 v[78:81], v[148:151], v[204:207], v[78:81]
	v_mfma_f32_16x16x32_bf16 v[74:77], v[156:159], v[204:207], v[74:77]
	v_mfma_f32_16x16x32_bf16 v[126:129], v[152:155], v[184:187], v[126:129]
	v_mfma_f32_16x16x32_bf16 v[122:125], v[160:163], v[184:187], v[122:125]
	v_mfma_f32_16x16x32_bf16 v[110:113], v[152:155], v[192:195], v[110:113]
	v_mfma_f32_16x16x32_bf16 v[106:109], v[160:163], v[192:195], v[106:109]
	v_mfma_f32_16x16x32_bf16 v[94:97], v[152:155], v[200:203], v[94:97]
	v_mfma_f32_16x16x32_bf16 v[90:93], v[160:163], v[200:203], v[90:93]
	s_waitcnt lgkmcnt(0)
	v_mfma_f32_16x16x32_bf16 v[78:81], v[152:155], v[208:211], v[78:81]
	v_mfma_f32_16x16x32_bf16 v[74:77], v[160:163], v[208:211], v[74:77]
	s_setprio 0
	s_setprio 1
	v_mfma_f32_16x16x32_bf16 v[118:121], v[164:167], v[180:183], v[118:121]
	v_mfma_f32_16x16x32_bf16 v[114:117], v[172:175], v[180:183], v[114:117]
	v_mfma_f32_16x16x32_bf16 v[102:105], v[164:167], v[188:191], v[102:105]
	v_mfma_f32_16x16x32_bf16 v[98:101], v[172:175], v[188:191], v[98:101]
	v_mfma_f32_16x16x32_bf16 v[86:89], v[164:167], v[196:199], v[86:89]
	v_mfma_f32_16x16x32_bf16 v[82:85], v[172:175], v[196:199], v[82:85]
	v_mfma_f32_16x16x32_bf16 v[70:73], v[164:167], v[204:207], v[70:73]
	v_mfma_f32_16x16x32_bf16 v[66:69], v[172:175], v[204:207], v[66:69]
	v_mfma_f32_16x16x32_bf16 v[118:121], v[168:171], v[184:187], v[118:121]
	v_mfma_f32_16x16x32_bf16 v[114:117], v[176:179], v[184:187], v[114:117]
	v_mfma_f32_16x16x32_bf16 v[102:105], v[168:171], v[192:195], v[102:105]
	v_mfma_f32_16x16x32_bf16 v[98:101], v[176:179], v[192:195], v[98:101]
	v_mfma_f32_16x16x32_bf16 v[86:89], v[168:171], v[200:203], v[86:89]
	v_mfma_f32_16x16x32_bf16 v[82:85], v[176:179], v[200:203], v[82:85]
	v_mfma_f32_16x16x32_bf16 v[70:73], v[168:171], v[208:211], v[70:73]
	s_barrier
	v_mfma_f32_16x16x32_bf16 v[66:69], v[176:179], v[208:211], v[66:69]
	s_setprio 0
	ds_read_b128 v[180:183], v144 offset:16384
	ds_read_b128 v[184:187], v144 offset:17408
	ds_read_b128 v[188:191], v144 offset:18432
	ds_read_b128 v[192:195], v144 offset:19456
	ds_read_b128 v[196:199], v144 offset:20480
	ds_read_b128 v[200:203], v144 offset:21504
	ds_read_b128 v[204:207], v144 offset:22528
	ds_read_b128 v[252:255], v144 offset:23552
	s_mov_b32 m0, s55
	s_nop 0
	global_load_lds_dwordx4 v137, s[84:85]
	s_add_u32 s66, s84, 0x100000
	s_mov_b32 m0, s56
	s_nop 0
	global_load_lds_dwordx4 v139, s[84:85]
	s_addc_u32 s67, s85, 0
	s_mov_b32 m0, s57
	s_nop 0
	global_load_lds_dwordx4 v137, s[66:67]
	s_nop 0
	s_mov_b32 m0, s58
	s_nop 0
	global_load_lds_dwordx4 v139, s[66:67]
	s_nop 0
	s_mov_b32 m0, s54
	s_nop 0
	global_load_lds_dwordx4 v136, s[86:87]
	s_nop 0
	s_mov_b32 m0, s59
	s_nop 0
	global_load_lds_dwordx4 v138, s[86:87]
	s_waitcnt vmcnt(8)
	s_waitcnt lgkmcnt(0)
	s_barrier
	s_setprio 1
	s_waitcnt lgkmcnt(7)
	v_mfma_f32_16x16x32_bf16 v[62:65], v[148:151], v[180:183], v[62:65]
	v_mfma_f32_16x16x32_bf16 v[58:61], v[156:159], v[180:183], v[58:61]
	s_waitcnt lgkmcnt(5)
	v_mfma_f32_16x16x32_bf16 v[46:49], v[148:151], v[188:191], v[46:49]
	v_mfma_f32_16x16x32_bf16 v[42:45], v[156:159], v[188:191], v[42:45]
	s_waitcnt lgkmcnt(3)
	v_mfma_f32_16x16x32_bf16 v[30:33], v[148:151], v[196:199], v[30:33]
	v_mfma_f32_16x16x32_bf16 v[26:29], v[156:159], v[196:199], v[26:29]
	s_waitcnt lgkmcnt(1)
	v_mfma_f32_16x16x32_bf16 v[14:17], v[148:151], v[204:207], v[14:17]
	v_mfma_f32_16x16x32_bf16 v[10:13], v[156:159], v[204:207], v[10:13]
	v_mfma_f32_16x16x32_bf16 v[62:65], v[152:155], v[184:187], v[62:65]
	v_mfma_f32_16x16x32_bf16 v[58:61], v[160:163], v[184:187], v[58:61]
	v_mfma_f32_16x16x32_bf16 v[46:49], v[152:155], v[192:195], v[46:49]
	v_mfma_f32_16x16x32_bf16 v[42:45], v[160:163], v[192:195], v[42:45]
	v_mfma_f32_16x16x32_bf16 v[30:33], v[152:155], v[200:203], v[30:33]
	v_mfma_f32_16x16x32_bf16 v[26:29], v[160:163], v[200:203], v[26:29]
	s_waitcnt lgkmcnt(0)
	v_mfma_f32_16x16x32_bf16 v[14:17], v[152:155], v[252:255], v[14:17]
	v_mfma_f32_16x16x32_bf16 v[10:13], v[160:163], v[252:255], v[10:13]
	s_setprio 0
	s_setprio 1
	v_mfma_f32_16x16x32_bf16 v[54:57], v[164:167], v[180:183], v[54:57]
	v_mfma_f32_16x16x32_bf16 v[50:53], v[172:175], v[180:183], v[50:53]
	v_mfma_f32_16x16x32_bf16 v[38:41], v[164:167], v[188:191], v[38:41]
	v_mfma_f32_16x16x32_bf16 v[34:37], v[172:175], v[188:191], v[34:37]
	v_mfma_f32_16x16x32_bf16 v[22:25], v[164:167], v[196:199], v[22:25]
	v_mfma_f32_16x16x32_bf16 v[18:21], v[172:175], v[196:199], v[18:21]
	v_mfma_f32_16x16x32_bf16 v[6:9], v[164:167], v[204:207], v[6:9]
	v_mfma_f32_16x16x32_bf16 v[2:5], v[172:175], v[204:207], v[2:5]
	v_mfma_f32_16x16x32_bf16 v[54:57], v[168:171], v[184:187], v[54:57]
	v_mfma_f32_16x16x32_bf16 v[50:53], v[176:179], v[184:187], v[50:53]
	v_mfma_f32_16x16x32_bf16 v[38:41], v[168:171], v[192:195], v[38:41]
	v_mfma_f32_16x16x32_bf16 v[34:37], v[176:179], v[192:195], v[34:37]
	v_mfma_f32_16x16x32_bf16 v[22:25], v[168:171], v[200:203], v[22:25]
	v_mfma_f32_16x16x32_bf16 v[18:21], v[176:179], v[200:203], v[18:21]
	v_mfma_f32_16x16x32_bf16 v[6:9], v[168:171], v[252:255], v[6:9]
	s_barrier
; #define PG8_STAGE(bufoff, gbase, voff) do { _Pragma("unroll") for (int _i = 0; _i < 2; ++_i) \
;         asm volatile("s_mov_b32 m0, %2\n\ts_nop 0\n\tglobal_load_lds_dwordx4 %0, %1" :: "v"((voff)[_i]), "s"((const char*)(gbase)), "s"(ldsbase + (unsigned)(bufoff) + ldsw + (unsigned)_i * 8192u) : "memory", "m0"); } while (0)
; #define PG8_LDA(dst, b, h) do { _Pragma("unroll") for (int m = 0; m < 4; ++m) _Pragma("unroll") for (int k = 0; k < 2; ++k) dst[m][k] = *(const PG8_LAS bf16x8*)(lds + PG8_SA(b, h) + aoff + m * 2048 + k * 1024); } while (0)
; #define PG8_LDB(dst, b, h) do { _Pragma("unroll") for (int n = 0; n < 2; ++n) _Pragma("unroll") for (int k = 0; k < 2; ++k) dst[n][k] = *(const PG8_LAS bf16x8*)(lds + PG8_SB(b, h) + boff + n * 2048 + k * 1024); } while (0)
; #define PG8_MMA(ai, bj, At, Bt) do { __builtin_amdgcn_s_setprio(1); _Pragma("unroll") for (int m = 0; m < 4; ++m) _Pragma("unroll") for (int n = 0; n < 2; ++n) _Pragma("unroll") for (int k = 0; k < 2; ++k) \
;         acc[ai][bj][m][n] = __builtin_amdgcn_mfma_f32_16x16x32_bf16(Bt[n][k], At[m][k], acc[ai][bj][m][n], 0, 0, 0); __builtin_amdgcn_s_setprio(0); } while (0)
; #define PG8_WAIT_V(n) asm volatile("s_waitcnt vmcnt(" #n ")" ::: "memory")
; #define PG8_WAIT_L(n) asm volatile("s_waitcnt lgkmcnt(" #n ")" ::: "memory")
; #define PG8_BAR __builtin_amdgcn_s_barrier()
; #define PG8_SCHED __builtin_amdgcn_sched_barrier(0)
; template <class Epi, class Sched, bool ALIGN_EPI = false, bool SP2 = false>
; __device__ __forceinline__ void gemm_phase(PG8_LAS unsigned char* lds, const Gemm g, const Sched& S, const Epi& E) {
;     ...
;             PG8_LDB(B0, 1, 0); PG8_LDB(B1, 1, 1); PG8_SCHED; PG8_LDA(At, 1, 0); PG8_STAGE(PG8_SA(0, 1), a2 + hstep, voffA);
;             PG8_WAIT_V(8); PG8_WAIT_L(0); PG8_BAR; PG8_MMA(0, 0, At, B0); PG8_MMA(0, 1, At, B1); PG8_BAR; PG8_SCHED;
;             PG8_LDA(At, 1, 1); PG8_STAGE(PG8_SB(1, 0), b3, voffB); PG8_STAGE(PG8_SB(1, 1), b3 + hstep, voffB); PG8_STAGE(PG8_SA(1, 0), a3, voffA);
;             PG8_WAIT_V(8); PG8_WAIT_L(0); PG8_BAR; PG8_MMA(1, 0, At, B0); PG8_MMA(1, 1, At, B1); PG8_BAR; PG8_SCHED;
	v_mfma_f32_16x16x32_bf16 v[2:5], v[176:179], v[252:255], v[2:5]
	s_setprio 0
	ds_read_b128 v[148:151], v145
	ds_read_b128 v[152:155], v145 offset:1024
	ds_read_b128 v[156:159], v145 offset:2048
	ds_read_b128 v[160:163], v145 offset:3072
	ds_read_b128 v[164:167], v146
	ds_read_b128 v[168:171], v146 offset:1024
	ds_read_b128 v[172:175], v146 offset:2048
	ds_read_b128 v[248:251], v146 offset:3072
	ds_read_b128 v[180:183], v144 offset:32768
	ds_read_b128 v[184:187], v144 offset:33792
	ds_read_b128 v[188:191], v144 offset:34816
	ds_read_b128 v[192:195], v144 offset:35840
	ds_read_b128 v[196:199], v144 offset:36864
	ds_read_b128 v[200:203], v144 offset:37888
	ds_read_b128 v[204:207], v144 offset:38912
	ds_read_b128 v[208:211], v144 offset:39936
	s_add_u32 s66, s86, 0x100000
	s_addc_u32 s67, s87, 0
	s_mov_b32 m0, s60
	s_nop 0
	global_load_lds_dwordx4 v136, s[66:67]
	s_nop 0
	s_mov_b32 m0, s61
	s_nop 0
	global_load_lds_dwordx4 v138, s[66:67]
	s_waitcnt vmcnt(8)
	s_waitcnt lgkmcnt(0)
	s_barrier
	s_setprio 1
	s_waitcnt lgkmcnt(7)
	v_mfma_f32_16x16x32_bf16 v[126:129], v[148:151], v[180:183], v[126:129]
	v_mfma_f32_16x16x32_bf16 v[122:125], v[156:159], v[180:183], v[122:125]
	s_waitcnt lgkmcnt(5)
	v_mfma_f32_16x16x32_bf16 v[110:113], v[148:151], v[188:191], v[110:113]
	v_mfma_f32_16x16x32_bf16 v[106:109], v[156:159], v[188:191], v[106:109]
	s_waitcnt lgkmcnt(3)
	v_mfma_f32_16x16x32_bf16 v[94:97], v[148:151], v[196:199], v[94:97]
	v_mfma_f32_16x16x32_bf16 v[90:93], v[156:159], v[196:199], v[90:93]
	s_waitcnt lgkmcnt(1)
	v_mfma_f32_16x16x32_bf16 v[78:81], v[148:151], v[204:207], v[78:81]
	v_mfma_f32_16x16x32_bf16 v[74:77], v[156:159], v[204:207], v[74:77]
	v_mfma_f32_16x16x32_bf16 v[126:129], v[152:155], v[184:187], v[126:129]
	v_mfma_f32_16x16x32_bf16 v[122:125], v[160:163], v[184:187], v[122:125]
	v_mfma_f32_16x16x32_bf16 v[110:113], v[152:155], v[192:195], v[110:113]
	v_mfma_f32_16x16x32_bf16 v[106:109], v[160:163], v[192:195], v[106:109]
	v_mfma_f32_16x16x32_bf16 v[94:97], v[152:155], v[200:203], v[94:97]
	v_mfma_f32_16x16x32_bf16 v[90:93], v[160:163], v[200:203], v[90:93]
	s_waitcnt lgkmcnt(0)
	v_mfma_f32_16x16x32_bf16 v[78:81], v[152:155], v[208:211], v[78:81]
	v_mfma_f32_16x16x32_bf16 v[74:77], v[160:163], v[208:211], v[74:77]
	s_setprio 0
	s_setprio 1
	v_mfma_f32_16x16x32_bf16 v[118:121], v[164:167], v[180:183], v[118:121]
	v_mfma_f32_16x16x32_bf16 v[114:117], v[172:175], v[180:183], v[114:117]
	v_mfma_f32_16x16x32_bf16 v[102:105], v[164:167], v[188:191], v[102:105]
	v_mfma_f32_16x16x32_bf16 v[98:101], v[172:175], v[188:191], v[98:101]
	v_mfma_f32_16x16x32_bf16 v[86:89], v[164:167], v[196:199], v[86:89]
	v_mfma_f32_16x16x32_bf16 v[82:85], v[172:175], v[196:199], v[82:85]
	v_mfma_f32_16x16x32_bf16 v[70:73], v[164:167], v[204:207], v[70:73]
	v_mfma_f32_16x16x32_bf16 v[66:69], v[172:175], v[204:207], v[66:69]
	v_mfma_f32_16x16x32_bf16 v[118:121], v[168:171], v[184:187], v[118:121]
	v_mfma_f32_16x16x32_bf16 v[114:117], v[248:251], v[184:187], v[114:117]
	v_mfma_f32_16x16x32_bf16 v[102:105], v[168:171], v[192:195], v[102:105]
	v_mfma_f32_16x16x32_bf16 v[98:101], v[248:251], v[192:195], v[98:101]
	v_mfma_f32_16x16x32_bf16 v[86:89], v[168:171], v[200:203], v[86:89]
	v_mfma_f32_16x16x32_bf16 v[82:85], v[248:251], v[200:203], v[82:85]
	v_mfma_f32_16x16x32_bf16 v[70:73], v[168:171], v[208:211], v[70:73]
	s_barrier
	v_mfma_f32_16x16x32_bf16 v[66:69], v[248:251], v[208:211], v[66:69]
	s_setprio 0
	ds_read_b128 v[180:183], v144 offset:49152
	ds_read_b128 v[184:187], v144 offset:50176
	ds_read_b128 v[188:191], v144 offset:51200
	ds_read_b128 v[192:195], v144 offset:52224
	ds_read_b128 v[196:199], v144 offset:53248
	ds_read_b128 v[200:203], v144 offset:54272
	ds_read_b128 v[204:207], v144 offset:55296
	ds_read_b128 v[252:255], v144 offset:56320
	s_add_u32 s66, s84, 0x80
	s_addc_u32 s67, s85, 0
	s_mov_b32 m0, s64
	s_nop 0
	global_load_lds_dwordx4 v137, s[66:67]
	s_nop 0
	s_mov_b32 m0, s65
	s_nop 0
	global_load_lds_dwordx4 v139, s[66:67]
	s_add_u32 s66, s84, 0x100080
	s_addc_u32 s67, s85, 0
	s_mov_b32 m0, s70
	s_nop 0
	global_load_lds_dwordx4 v137, s[66:67]
	s_nop 0
	s_mov_b32 m0, s71
	s_nop 0
	global_load_lds_dwordx4 v139, s[66:67]
	s_nop 0
	s_mov_b32 m0, s68
	s_nop 0
	global_load_lds_dwordx4 v136, s[76:77]
	s_nop 0
	s_mov_b32 m0, s69
	s_nop 0
	global_load_lds_dwordx4 v138, s[76:77]
	s_waitcnt vmcnt(8)
	s_waitcnt lgkmcnt(0)
	s_barrier
	s_setprio 1
	s_waitcnt lgkmcnt(7)
	v_mfma_f32_16x16x32_bf16 v[62:65], v[148:151], v[180:183], v[62:65]
	v_mfma_f32_16x16x32_bf16 v[58:61], v[156:159], v[180:183], v[58:61]
	s_waitcnt lgkmcnt(5)
	v_mfma_f32_16x16x32_bf16 v[46:49], v[148:151], v[188:191], v[46:49]
	v_mfma_f32_16x16x32_bf16 v[42:45], v[156:159], v[188:191], v[42:45]
	s_waitcnt lgkmcnt(3)
	v_mfma_f32_16x16x32_bf16 v[30:33], v[148:151], v[196:199], v[30:33]
	v_mfma_f32_16x16x32_bf16 v[26:29], v[156:159], v[196:199], v[26:29]
	s_waitcnt lgkmcnt(1)
	v_mfma_f32_16x16x32_bf16 v[14:17], v[148:151], v[204:207], v[14:17]
	v_mfma_f32_16x16x32_bf16 v[10:13], v[156:159], v[204:207], v[10:13]
	v_mfma_f32_16x16x32_bf16 v[62:65], v[152:155], v[184:187], v[62:65]
	v_mfma_f32_16x16x32_bf16 v[58:61], v[160:163], v[184:187], v[58:61]
	v_mfma_f32_16x16x32_bf16 v[46:49], v[152:155], v[192:195], v[46:49]
	v_mfma_f32_16x16x32_bf16 v[42:45], v[160:163], v[192:195], v[42:45]
	v_mfma_f32_16x16x32_bf16 v[30:33], v[152:155], v[200:203], v[30:33]
	v_mfma_f32_16x16x32_bf16 v[26:29], v[160:163], v[200:203], v[26:29]
	s_waitcnt lgkmcnt(0)
	v_mfma_f32_16x16x32_bf16 v[14:17], v[152:155], v[252:255], v[14:17]
	v_mfma_f32_16x16x32_bf16 v[10:13], v[160:163], v[252:255], v[10:13]
	s_setprio 0
	s_setprio 1
	v_mfma_f32_16x16x32_bf16 v[54:57], v[164:167], v[180:183], v[54:57]
	v_mfma_f32_16x16x32_bf16 v[50:53], v[172:175], v[180:183], v[50:53]
	v_mfma_f32_16x16x32_bf16 v[38:41], v[164:167], v[188:191], v[38:41]
	v_mfma_f32_16x16x32_bf16 v[34:37], v[172:175], v[188:191], v[34:37]
	v_mfma_f32_16x16x32_bf16 v[22:25], v[164:167], v[196:199], v[22:25]
	v_mfma_f32_16x16x32_bf16 v[18:21], v[172:175], v[196:199], v[18:21]
	v_mfma_f32_16x16x32_bf16 v[6:9], v[164:167], v[204:207], v[6:9]
	v_mfma_f32_16x16x32_bf16 v[2:5], v[172:175], v[204:207], v[2:5]
	v_mfma_f32_16x16x32_bf16 v[54:57], v[168:171], v[184:187], v[54:57]
	v_mfma_f32_16x16x32_bf16 v[50:53], v[248:251], v[184:187], v[50:53]
	v_mfma_f32_16x16x32_bf16 v[38:41], v[168:171], v[192:195], v[38:41]
	v_mfma_f32_16x16x32_bf16 v[34:37], v[248:251], v[192:195], v[34:37]
	v_mfma_f32_16x16x32_bf16 v[22:25], v[168:171], v[200:203], v[22:25]
	v_mfma_f32_16x16x32_bf16 v[18:21], v[248:251], v[200:203], v[18:21]
	v_mfma_f32_16x16x32_bf16 v[6:9], v[168:171], v[252:255], v[6:9]
	s_barrier
; __device__ __forceinline__ unsigned cvt_pk_bf16(float lo, float hi) { unsigned r; asm volatile("v_cvt_pk_bf16_f32 %0, %1, %2" : "=v"(r) : "v"(lo), "v"(hi)); return r; }
; __device__ __forceinline__ float silu_f(float x) { return x * sigmoid_f(x); }
;     __device__ __forceinline__ void operator()(const f32x4 (&acc)[2][2][4][2], const Unit& u, int wr, int wc, int fr, int fq) const {
;     ...
;             for (int m = 0; m < 4; ++m) { bf16_t* rowp = O + (size_t)(row0 + ai * HALF + m * 16) * ldc + col0;
;                 const f32x4 g0 = acc[ai][0][m][0], g1 = acc[ai][0][m][1], u0 = acc[ai][1][m][0], u1 = acc[ai][1][m][1];
;                 f32x4 v0, v1;
; #pragma unroll
;                 for (int j = 0; j < 4; ++j) { v0[j] = silu_f(g0[j]) * u0[j]; v1[j] = silu_f(g1[j]) * u1[j]; }
;                 u32x4 w; w.x = cvt_pk_bf16(v0[0], v0[1]); w.y = cvt_pk_bf16(v0[2], v0[3]); w.z = cvt_pk_bf16(v1[0], v1[1]); w.w = cvt_pk_bf16(v1[2], v1[3]);
;                 *(u32x4*)rowp = w; }
	v_mfma_f32_16x16x32_bf16 v[2:5], v[248:251], v[252:255], v[2:5]
	s_setprio 0
	s_add_i32 s96, s96, 2
	s_add_u32 s94, s94, 0x100
	s_addc_u32 s95, s95, 0
	s_cmp_gt_u32 s96, 61
	s_mov_b64 s[66:67], s[62:63]
	s_cbranch_scc0 .LBB0_138
	v_mul_f32_e32 v134, 0xbfb8aa3b, v126
	v_exp_f32_e32 v150, v134
	v_mul_f32_e32 v134, 0xbfb8aa3b, v122
	v_exp_f32_e32 v151, v134
	v_lshl_or_b32 v148, s91, 7, v141
	v_add_f32_e32 v150, 1.0, v150
	v_rcp_f32_e32 v152, v150
	v_add_f32_e32 v150, 1.0, v151
	v_rcp_f32_e32 v153, v150
	v_lshl_add_u32 v147, s82, 8, v140
	v_mul_f32_e32 v126, v126, v152
	v_mul_f32_e32 v118, v126, v118
	v_mul_f32_e32 v126, 0xbfb8aa3b, v127
	v_exp_f32_e32 v126, v126
	v_mul_f32_e32 v152, 0xbfb8aa3b, v123
	v_exp_f32_e32 v152, v152
	v_mul_f32_e32 v122, v122, v153
	v_mul_f32_e32 v122, v122, v114
	v_add_f32_e32 v114, 1.0, v126
	v_rcp_f32_e32 v114, v114
	v_add_f32_e32 v126, 1.0, v152
	v_mul_f32_e32 v152, 0xbfb8aa3b, v128
	v_rcp_f32_e32 v126, v126
	v_exp_f32_e32 v152, v152
	v_mul_f32_e32 v114, v127, v114
	v_mul_f32_e32 v119, v114, v119
	v_mul_f32_e32 v114, v123, v126
	v_add_f32_e32 v123, 1.0, v152
	v_rcp_f32_e32 v123, v123
	v_mul_f32_e32 v126, 0xbfb8aa3b, v124
	v_exp_f32_e32 v126, v126
	v_mul_f32_e32 v127, v114, v115
	v_mul_f32_e32 v114, v128, v123
	v_mul_f32_e32 v115, 0xbfb8aa3b, v129
	v_mul_f32_e32 v123, v114, v120
	v_exp_f32_e32 v115, v115
	v_mul_f32_e32 v120, 0xbfb8aa3b, v125
	v_exp_f32_e32 v120, v120
	v_add_f32_e32 v114, 1.0, v126
	v_rcp_f32_e32 v114, v114
	v_add_f32_e32 v115, 1.0, v115
	v_rcp_f32_e32 v115, v115
	v_add_f32_e32 v120, 1.0, v120
	v_rcp_f32_e32 v120, v120
	v_mul_f32_e32 v114, v124, v114
	v_mul_f32_e32 v124, v114, v116
	v_mul_f32_e32 v114, v129, v115
	v_ashrrev_i32_e32 v149, 31, v148
	v_mov_b64_e32 v[134:135], s[72:73]
	v_mul_f32_e32 v126, v114, v121
	v_mul_f32_e32 v114, v125, v120
	v_mad_i64_i32 v[150:151], s[62:63], v147, s90, v[134:135]
	v_mul_f32_e32 v125, v114, v117
	v_lshlrev_b64 v[114:115], 1, v[148:149]
	v_lshl_add_u64 v[120:121], v[150:151], 0, v[114:115]
	v_cvt_pk_bf16_f32 v116, v118, v119
	v_cvt_pk_bf16_f32 v117, v123, v126
	v_cvt_pk_bf16_f32 v118, v122, v127
	v_cvt_pk_bf16_f32 v119, v124, v125
	global_store_dwordx4 v[120:121], v[116:119], off
	s_and_b64 vcc, exec, s[0:1]
	s_mov_b32 s91, s10
	v_mul_f32_e32 v116, 0xbfb8aa3b, v110
	v_exp_f32_e32 v116, v116
	v_mul_f32_e32 v117, 0xbfb8aa3b, v106
	v_exp_f32_e32 v117, v117
	v_or_b32_e32 v118, 16, v147
	v_add_f32_e32 v116, 1.0, v116
	v_rcp_f32_e32 v119, v116
	v_add_f32_e32 v116, 1.0, v117
	v_rcp_f32_e32 v120, v116
	v_mad_i64_i32 v[116:117], s[62:63], v118, s90, v[134:135]
	v_mul_f32_e32 v110, v110, v119
	v_mul_f32_e32 v110, v110, v102
	v_mul_f32_e32 v102, v106, v120
	v_mul_f32_e32 v106, 0xbfb8aa3b, v111
	v_exp_f32_e32 v106, v106
	v_mul_f32_e32 v118, 0xbfb8aa3b, v107
	v_mul_f32_e32 v119, v102, v98
	v_exp_f32_e32 v118, v118
	v_add_f32_e32 v98, 1.0, v106
	v_rcp_f32_e32 v98, v98
	v_mul_f32_e32 v106, 0xbfb8aa3b, v112
	v_exp_f32_e32 v106, v106
	v_add_f32_e32 v102, 1.0, v118
	v_mul_f32_e32 v98, v111, v98
	v_rcp_f32_e32 v102, v102
	v_mul_f32_e32 v98, v98, v103
	v_add_f32_e32 v103, 1.0, v106
	v_rcp_f32_e32 v103, v103
	v_mul_f32_e32 v102, v107, v102
	v_mul_f32_e32 v106, 0xbfb8aa3b, v108
	v_mul_f32_e32 v107, v102, v99
	v_mul_f32_e32 v99, v112, v103
	v_exp_f32_e32 v106, v106
	v_mul_f32_e32 v99, v99, v104
	v_mul_f32_e32 v103, 0xbfb8aa3b, v113
	v_mul_f32_e32 v104, 0xbfb8aa3b, v109
	v_exp_f32_e32 v103, v103
	v_exp_f32_e32 v104, v104
	v_add_f32_e32 v102, 1.0, v106
	v_rcp_f32_e32 v102, v102
	v_add_f32_e32 v103, 1.0, v103
	v_add_f32_e32 v104, 1.0, v104
	v_rcp_f32_e32 v103, v103
	v_rcp_f32_e32 v104, v104
	v_mul_f32_e32 v102, v108, v102
	v_mul_f32_e32 v106, v102, v100
	v_mul_f32_e32 v100, v113, v103
	v_mul_f32_e32 v102, v109, v104
	v_mul_f32_e32 v100, v100, v105
	v_mul_f32_e32 v101, v102, v101
	v_lshl_add_u64 v[102:103], v[116:117], 0, v[114:115]
	v_cvt_pk_bf16_f32 v98, v110, v98
	v_cvt_pk_bf16_f32 v99, v99, v100
	v_cvt_pk_bf16_f32 v100, v119, v107
	v_cvt_pk_bf16_f32 v101, v106, v101
	global_store_dwordx4 v[102:103], v[98:101], off
	s_mov_b32 s82, s12
	s_mov_b64 s[66:67], s[14:15]
	v_mul_f32_e32 v98, 0xbfb8aa3b, v94
	v_exp_f32_e32 v98, v98
	v_mul_f32_e32 v99, 0xbfb8aa3b, v90
	v_exp_f32_e32 v99, v99
	v_or_b32_e32 v100, 32, v147
	v_add_f32_e32 v98, 1.0, v98
	v_rcp_f32_e32 v101, v98
	v_add_f32_e32 v98, 1.0, v99
	v_rcp_f32_e32 v102, v98
	v_mad_i64_i32 v[98:99], s[62:63], v100, s90, v[134:135]
	v_mul_f32_e32 v94, v94, v101
	v_mul_f32_e32 v94, v94, v86
	v_mul_f32_e32 v86, v90, v102
	v_mul_f32_e32 v90, 0xbfb8aa3b, v95
	v_exp_f32_e32 v90, v90
	v_mul_f32_e32 v100, 0xbfb8aa3b, v91
	v_mul_f32_e32 v101, v86, v82
	v_exp_f32_e32 v100, v100
	v_add_f32_e32 v82, 1.0, v90
	v_rcp_f32_e32 v82, v82
	v_mul_f32_e32 v90, 0xbfb8aa3b, v96
	v_exp_f32_e32 v90, v90
	v_add_f32_e32 v86, 1.0, v100
	v_mul_f32_e32 v82, v95, v82
	v_rcp_f32_e32 v86, v86
	v_mul_f32_e32 v82, v82, v87
	v_add_f32_e32 v87, 1.0, v90
	v_rcp_f32_e32 v87, v87
	v_mul_f32_e32 v86, v91, v86
	v_mul_f32_e32 v90, 0xbfb8aa3b, v92
	v_mul_f32_e32 v91, v86, v83
	v_mul_f32_e32 v83, v96, v87
	v_exp_f32_e32 v90, v90
	v_mul_f32_e32 v83, v83, v88
	v_mul_f32_e32 v87, 0xbfb8aa3b, v97
	v_mul_f32_e32 v88, 0xbfb8aa3b, v93
	v_exp_f32_e32 v87, v87
	v_exp_f32_e32 v88, v88
	v_add_f32_e32 v86, 1.0, v90
	v_rcp_f32_e32 v86, v86
	v_add_f32_e32 v87, 1.0, v87
	v_add_f32_e32 v88, 1.0, v88
	v_rcp_f32_e32 v87, v87
	v_rcp_f32_e32 v88, v88
	v_mul_f32_e32 v86, v92, v86
	v_mul_f32_e32 v90, v86, v84
	v_mul_f32_e32 v84, v97, v87
	v_mul_f32_e32 v86, v93, v88
	v_mul_f32_e32 v84, v84, v89
	v_mul_f32_e32 v85, v86, v85
	v_lshl_add_u64 v[86:87], v[98:99], 0, v[114:115]
	v_cvt_pk_bf16_f32 v82, v94, v82
; __device__ __forceinline__ unsigned cvt_pk_bf16(float lo, float hi) { unsigned r; asm volatile("v_cvt_pk_bf16_f32 %0, %1, %2" : "=v"(r) : "v"(lo), "v"(hi)); return r; }
; __device__ __forceinline__ float silu_f(float x) { return x * sigmoid_f(x); }
;     __device__ __forceinline__ void operator()(const f32x4 (&acc)[2][2][4][2], const Unit& u, int wr, int wc, int fr, int fq) const {
;     ...
;             for (int m = 0; m < 4; ++m) { bf16_t* rowp = O + (size_t)(row0 + ai * HALF + m * 16) * ldc + col0;
;                 const f32x4 g0 = acc[ai][0][m][0], g1 = acc[ai][0][m][1], u0 = acc[ai][1][m][0], u1 = acc[ai][1][m][1];
;                 f32x4 v0, v1;
; #pragma unroll
;                 for (int j = 0; j < 4; ++j) { v0[j] = silu_f(g0[j]) * u0[j]; v1[j] = silu_f(g1[j]) * u1[j]; }
;                 u32x4 w; w.x = cvt_pk_bf16(v0[0], v0[1]); w.y = cvt_pk_bf16(v0[2], v0[3]); w.z = cvt_pk_bf16(v1[0], v1[1]); w.w = cvt_pk_bf16(v1[2], v1[3]);
;                 *(u32x4*)rowp = w; }
	v_cvt_pk_bf16_f32 v83, v83, v84
	v_cvt_pk_bf16_f32 v84, v101, v91
	v_cvt_pk_bf16_f32 v85, v90, v85
	global_store_dwordx4 v[86:87], v[82:85], off
	s_nop 1
	v_mul_f32_e32 v82, 0xbfb8aa3b, v78
	v_exp_f32_e32 v82, v82
	v_mul_f32_e32 v83, 0xbfb8aa3b, v74
	v_exp_f32_e32 v83, v83
	v_or_b32_e32 v84, 48, v147
	v_add_f32_e32 v82, 1.0, v82
	v_rcp_f32_e32 v85, v82
	v_add_f32_e32 v82, 1.0, v83
	v_rcp_f32_e32 v86, v82
	v_mad_i64_i32 v[82:83], s[62:63], v84, s90, v[134:135]
	v_mul_f32_e32 v78, v78, v85
	v_mul_f32_e32 v78, v78, v70
	v_mul_f32_e32 v70, v74, v86
	v_mul_f32_e32 v74, 0xbfb8aa3b, v79
	v_exp_f32_e32 v74, v74
	v_mul_f32_e32 v84, 0xbfb8aa3b, v75
	v_mul_f32_e32 v85, v70, v66
	v_exp_f32_e32 v84, v84
	v_add_f32_e32 v66, 1.0, v74
	v_rcp_f32_e32 v66, v66
	v_mul_f32_e32 v74, 0xbfb8aa3b, v80
	v_exp_f32_e32 v74, v74
	v_add_f32_e32 v70, 1.0, v84
	v_mul_f32_e32 v66, v79, v66
	v_rcp_f32_e32 v70, v70
	v_mul_f32_e32 v66, v66, v71
	v_add_f32_e32 v71, 1.0, v74
	v_rcp_f32_e32 v71, v71
	v_mul_f32_e32 v70, v75, v70
	v_mul_f32_e32 v74, 0xbfb8aa3b, v76
	v_mul_f32_e32 v75, v70, v67
	v_mul_f32_e32 v67, v80, v71
	v_exp_f32_e32 v74, v74
	v_mul_f32_e32 v67, v67, v72
	v_mul_f32_e32 v71, 0xbfb8aa3b, v81
	v_mul_f32_e32 v72, 0xbfb8aa3b, v77
	v_exp_f32_e32 v71, v71
	v_exp_f32_e32 v72, v72
	v_add_f32_e32 v70, 1.0, v74
	v_rcp_f32_e32 v70, v70
	v_add_f32_e32 v71, 1.0, v71
	v_add_f32_e32 v72, 1.0, v72
	v_rcp_f32_e32 v71, v71
	v_rcp_f32_e32 v72, v72
	v_mul_f32_e32 v70, v76, v70
	v_mul_f32_e32 v74, v70, v68
	v_mul_f32_e32 v68, v81, v71
	v_mul_f32_e32 v70, v77, v72
	v_mul_f32_e32 v68, v68, v73
	v_mul_f32_e32 v69, v70, v69
	v_lshl_add_u64 v[70:71], v[82:83], 0, v[114:115]
	v_cvt_pk_bf16_f32 v66, v78, v66
	v_cvt_pk_bf16_f32 v67, v67, v68
	v_cvt_pk_bf16_f32 v68, v85, v75
	v_cvt_pk_bf16_f32 v69, v74, v69
	global_store_dwordx4 v[70:71], v[66:69], off
	s_nop 1
	v_mul_f32_e32 v66, 0xbfb8aa3b, v62
	v_exp_f32_e32 v66, v66
	v_mul_f32_e32 v67, 0xbfb8aa3b, v58
	v_exp_f32_e32 v67, v67
	v_add_u32_e32 v68, 0x80, v147
	v_add_f32_e32 v66, 1.0, v66
	v_rcp_f32_e32 v69, v66
	v_add_f32_e32 v66, 1.0, v67
	v_rcp_f32_e32 v70, v66
	v_mad_i64_i32 v[66:67], s[62:63], v68, s90, v[134:135]
	v_mul_f32_e32 v62, v62, v69
	v_mul_f32_e32 v62, v62, v54
	v_mul_f32_e32 v54, v58, v70
	v_mul_f32_e32 v58, 0xbfb8aa3b, v63
	v_exp_f32_e32 v58, v58
	v_mul_f32_e32 v68, 0xbfb8aa3b, v59
	v_mul_f32_e32 v69, v54, v50
	v_exp_f32_e32 v68, v68
	v_add_f32_e32 v50, 1.0, v58
	v_rcp_f32_e32 v50, v50
	v_mul_f32_e32 v58, 0xbfb8aa3b, v64
	v_exp_f32_e32 v58, v58
	v_add_f32_e32 v54, 1.0, v68
	v_mul_f32_e32 v50, v63, v50
	v_rcp_f32_e32 v54, v54
	v_mul_f32_e32 v50, v50, v55
	v_add_f32_e32 v55, 1.0, v58
	v_rcp_f32_e32 v55, v55
	v_mul_f32_e32 v54, v59, v54
	v_mul_f32_e32 v58, 0xbfb8aa3b, v60
	v_mul_f32_e32 v59, v54, v51
	v_mul_f32_e32 v51, v64, v55
	v_exp_f32_e32 v58, v58
	v_mul_f32_e32 v51, v51, v56
	v_mul_f32_e32 v55, 0xbfb8aa3b, v65
	v_mul_f32_e32 v56, 0xbfb8aa3b, v61
	v_exp_f32_e32 v55, v55
	v_exp_f32_e32 v56, v56
	v_add_f32_e32 v54, 1.0, v58
	v_rcp_f32_e32 v54, v54
	v_add_f32_e32 v55, 1.0, v55
	v_add_f32_e32 v56, 1.0, v56
	v_rcp_f32_e32 v55, v55
	v_rcp_f32_e32 v56, v56
	v_mul_f32_e32 v54, v60, v54
	v_mul_f32_e32 v58, v54, v52
	v_mul_f32_e32 v52, v65, v55
	v_mul_f32_e32 v54, v61, v56
	v_mul_f32_e32 v52, v52, v57
	v_mul_f32_e32 v53, v54, v53
	v_lshl_add_u64 v[54:55], v[66:67], 0, v[114:115]
	v_cvt_pk_bf16_f32 v50, v62, v50
	v_cvt_pk_bf16_f32 v51, v51, v52
	v_cvt_pk_bf16_f32 v52, v69, v59
	v_cvt_pk_bf16_f32 v53, v58, v53
	global_store_dwordx4 v[54:55], v[50:53], off
	s_nop 1
	v_mul_f32_e32 v50, 0xbfb8aa3b, v46
	v_exp_f32_e32 v50, v50
	v_mul_f32_e32 v51, 0xbfb8aa3b, v42
	v_exp_f32_e32 v51, v51
	v_add_u32_e32 v52, 0x90, v147
	v_add_f32_e32 v50, 1.0, v50
	v_rcp_f32_e32 v53, v50
	v_add_f32_e32 v50, 1.0, v51
	v_rcp_f32_e32 v54, v50
	v_mad_i64_i32 v[50:51], s[62:63], v52, s90, v[134:135]
	v_mul_f32_e32 v46, v46, v53
	v_mul_f32_e32 v46, v46, v38
	v_mul_f32_e32 v38, v42, v54
	v_mul_f32_e32 v42, 0xbfb8aa3b, v47
	v_exp_f32_e32 v42, v42
	v_mul_f32_e32 v52, 0xbfb8aa3b, v43
	v_mul_f32_e32 v53, v38, v34
	v_exp_f32_e32 v52, v52
	v_add_f32_e32 v34, 1.0, v42
	v_rcp_f32_e32 v34, v34
	v_mul_f32_e32 v42, 0xbfb8aa3b, v48
	v_exp_f32_e32 v42, v42
	v_add_f32_e32 v38, 1.0, v52
	v_mul_f32_e32 v34, v47, v34
	v_rcp_f32_e32 v38, v38
	v_mul_f32_e32 v34, v34, v39
	v_add_f32_e32 v39, 1.0, v42
; __device__ __forceinline__ unsigned cvt_pk_bf16(float lo, float hi) { unsigned r; asm volatile("v_cvt_pk_bf16_f32 %0, %1, %2" : "=v"(r) : "v"(lo), "v"(hi)); return r; }
; __device__ __forceinline__ float silu_f(float x) { return x * sigmoid_f(x); }
; #define PG8_WAIT_V(n) asm volatile("s_waitcnt vmcnt(" #n ")" ::: "memory")
; #define PG8_BAR __builtin_amdgcn_s_barrier()
;     __device__ __forceinline__ void operator()(const f32x4 (&acc)[2][2][4][2], const Unit& u, int wr, int wc, int fr, int fq) const {
;     ...
;             for (int m = 0; m < 4; ++m) { bf16_t* rowp = O + (size_t)(row0 + ai * HALF + m * 16) * ldc + col0;
;                 const f32x4 g0 = acc[ai][0][m][0], g1 = acc[ai][0][m][1], u0 = acc[ai][1][m][0], u1 = acc[ai][1][m][1];
;                 f32x4 v0, v1;
; #pragma unroll
;                 for (int j = 0; j < 4; ++j) { v0[j] = silu_f(g0[j]) * u0[j]; v1[j] = silu_f(g1[j]) * u1[j]; }
;                 u32x4 w; w.x = cvt_pk_bf16(v0[0], v0[1]); w.y = cvt_pk_bf16(v0[2], v0[3]); w.z = cvt_pk_bf16(v1[0], v1[1]); w.w = cvt_pk_bf16(v1[2], v1[3]);
;                 *(u32x4*)rowp = w; }
; template <class Epi, class Sched, bool ALIGN_EPI = false, bool SP2 = false>
; __device__ __forceinline__ void gemm_phase(PG8_LAS unsigned char* lds, const Gemm g, const Sched& S, const Epi& E) {
;     ...
;     PG8_WAIT_V(0);
;     if constexpr (!ALIGN_EPI) { if (wr == 0) PG8_BAR; }
;     PG8_BAR;
	v_rcp_f32_e32 v39, v39
	v_mul_f32_e32 v38, v43, v38
	v_mul_f32_e32 v42, 0xbfb8aa3b, v44
	v_mul_f32_e32 v43, v38, v35
	v_mul_f32_e32 v35, v48, v39
	v_exp_f32_e32 v42, v42
	v_mul_f32_e32 v35, v35, v40
	v_mul_f32_e32 v39, 0xbfb8aa3b, v49
	v_mul_f32_e32 v40, 0xbfb8aa3b, v45
	v_exp_f32_e32 v39, v39
	v_exp_f32_e32 v40, v40
	v_add_f32_e32 v38, 1.0, v42
	v_rcp_f32_e32 v38, v38
	v_add_f32_e32 v39, 1.0, v39
	v_add_f32_e32 v40, 1.0, v40
	v_rcp_f32_e32 v39, v39
	v_rcp_f32_e32 v40, v40
	v_mul_f32_e32 v38, v44, v38
	v_mul_f32_e32 v42, v38, v36
	v_mul_f32_e32 v36, v49, v39
	v_mul_f32_e32 v38, v45, v40
	v_mul_f32_e32 v36, v36, v41
	v_mul_f32_e32 v37, v38, v37
	v_lshl_add_u64 v[38:39], v[50:51], 0, v[114:115]
	v_cvt_pk_bf16_f32 v34, v46, v34
	v_cvt_pk_bf16_f32 v35, v35, v36
	v_cvt_pk_bf16_f32 v36, v53, v43
	v_cvt_pk_bf16_f32 v37, v42, v37
	global_store_dwordx4 v[38:39], v[34:37], off
	s_nop 1
	v_mul_f32_e32 v34, 0xbfb8aa3b, v30
	v_exp_f32_e32 v34, v34
	v_mul_f32_e32 v35, 0xbfb8aa3b, v26
	v_exp_f32_e32 v35, v35
	v_add_u32_e32 v36, 0xa0, v147
	v_add_f32_e32 v34, 1.0, v34
	v_rcp_f32_e32 v37, v34
	v_add_f32_e32 v34, 1.0, v35
	v_rcp_f32_e32 v38, v34
	v_mad_i64_i32 v[34:35], s[62:63], v36, s90, v[134:135]
	v_mul_f32_e32 v30, v30, v37
	v_mul_f32_e32 v30, v30, v22
	v_mul_f32_e32 v22, v26, v38
	v_mul_f32_e32 v26, 0xbfb8aa3b, v31
	v_exp_f32_e32 v26, v26
	v_mul_f32_e32 v36, 0xbfb8aa3b, v27
	v_mul_f32_e32 v37, v22, v18
	v_exp_f32_e32 v36, v36
	v_add_f32_e32 v18, 1.0, v26
	v_rcp_f32_e32 v18, v18
	v_mul_f32_e32 v26, 0xbfb8aa3b, v32
	v_exp_f32_e32 v26, v26
	v_add_f32_e32 v22, 1.0, v36
	v_mul_f32_e32 v18, v31, v18
	v_rcp_f32_e32 v22, v22
	v_mul_f32_e32 v18, v18, v23
	v_add_f32_e32 v23, 1.0, v26
	v_rcp_f32_e32 v23, v23
	v_mul_f32_e32 v22, v27, v22
	v_mul_f32_e32 v26, 0xbfb8aa3b, v28
	v_mul_f32_e32 v27, v22, v19
	v_mul_f32_e32 v19, v32, v23
	v_exp_f32_e32 v26, v26
	v_mul_f32_e32 v19, v19, v24
	v_mul_f32_e32 v23, 0xbfb8aa3b, v33
	v_mul_f32_e32 v24, 0xbfb8aa3b, v29
	v_exp_f32_e32 v23, v23
	v_exp_f32_e32 v24, v24
	v_add_f32_e32 v22, 1.0, v26
	v_rcp_f32_e32 v22, v22
	v_add_f32_e32 v23, 1.0, v23
	v_add_f32_e32 v24, 1.0, v24
	v_rcp_f32_e32 v23, v23
	v_rcp_f32_e32 v24, v24
	v_mul_f32_e32 v22, v28, v22
	v_mul_f32_e32 v26, v22, v20
	v_mul_f32_e32 v20, v33, v23
	v_mul_f32_e32 v22, v29, v24
	v_mul_f32_e32 v20, v20, v25
	v_mul_f32_e32 v21, v22, v21
	v_lshl_add_u64 v[22:23], v[34:35], 0, v[114:115]
	v_cvt_pk_bf16_f32 v18, v30, v18
	v_cvt_pk_bf16_f32 v19, v19, v20
	v_cvt_pk_bf16_f32 v20, v37, v27
	v_cvt_pk_bf16_f32 v21, v26, v21
	global_store_dwordx4 v[22:23], v[18:21], off
	s_nop 1
	v_mul_f32_e32 v18, 0xbfb8aa3b, v14
	v_exp_f32_e32 v18, v18
	v_mul_f32_e32 v19, 0xbfb8aa3b, v10
	v_exp_f32_e32 v19, v19
	v_add_u32_e32 v20, 0xb0, v147
	v_add_f32_e32 v18, 1.0, v18
	v_rcp_f32_e32 v21, v18
	v_add_f32_e32 v18, 1.0, v19
	v_rcp_f32_e32 v22, v18
	v_mad_i64_i32 v[18:19], s[62:63], v20, s90, v[134:135]
	v_mul_f32_e32 v14, v14, v21
	v_mul_f32_e32 v14, v14, v6
	v_mul_f32_e32 v6, v10, v22
	v_mul_f32_e32 v10, 0xbfb8aa3b, v15
	v_exp_f32_e32 v10, v10
	v_mul_f32_e32 v20, 0xbfb8aa3b, v11
	v_mul_f32_e32 v21, v6, v2
	v_exp_f32_e32 v20, v20
	v_add_f32_e32 v2, 1.0, v10
	v_rcp_f32_e32 v2, v2
	v_mul_f32_e32 v10, 0xbfb8aa3b, v16
	v_exp_f32_e32 v10, v10
	v_add_f32_e32 v6, 1.0, v20
	v_mul_f32_e32 v2, v15, v2
	v_rcp_f32_e32 v6, v6
	v_mul_f32_e32 v2, v2, v7
	v_add_f32_e32 v7, 1.0, v10
	v_rcp_f32_e32 v7, v7
	v_mul_f32_e32 v6, v11, v6
	v_mul_f32_e32 v10, 0xbfb8aa3b, v12
	v_mul_f32_e32 v11, v6, v3
	v_mul_f32_e32 v3, v16, v7
	v_exp_f32_e32 v10, v10
	v_mul_f32_e32 v3, v3, v8
	v_mul_f32_e32 v7, 0xbfb8aa3b, v17
	v_mul_f32_e32 v8, 0xbfb8aa3b, v13
	v_exp_f32_e32 v7, v7
	v_exp_f32_e32 v8, v8
	v_add_f32_e32 v6, 1.0, v10
	v_rcp_f32_e32 v6, v6
	v_add_f32_e32 v7, 1.0, v7
	v_add_f32_e32 v8, 1.0, v8
	v_rcp_f32_e32 v7, v7
	v_rcp_f32_e32 v8, v8
	v_mul_f32_e32 v6, v12, v6
	v_mul_f32_e32 v10, v6, v4
	v_mul_f32_e32 v4, v17, v7
	v_mul_f32_e32 v6, v13, v8
	v_mul_f32_e32 v4, v4, v9
	v_mul_f32_e32 v5, v6, v5
	v_lshl_add_u64 v[6:7], v[18:19], 0, v[114:115]
	s_mov_b64 s[62:63], s[16:17]
	v_cvt_pk_bf16_f32 v2, v14, v2
	v_cvt_pk_bf16_f32 v3, v3, v4
	v_cvt_pk_bf16_f32 v4, v21, v11
	v_cvt_pk_bf16_f32 v5, v10, v5
	global_store_dwordx4 v[6:7], v[2:5], off
	s_cbranch_vccz .LBB0_135
	s_waitcnt vmcnt(0)
	s_cmpk_gt_u32 s3, 0xff
	s_cbranch_scc1 .LBB0_142
	s_barrier

; #define PG8_STAGE(bufoff, gbase, voff) do { _Pragma("unroll") for (int _i = 0; _i < 2; ++_i) \
;         asm volatile("s_mov_b32 m0, %2\n\ts_nop 0\n\tglobal_load_lds_dwordx4 %0, %1" :: "v"((voff)[_i]), "s"((const char*)(gbase)), "s"(ldsbase + (unsigned)(bufoff) + ldsw + (unsigned)_i * 8192u) : "memory", "m0"); } while (0)
; #define PG8_LDA(dst, b, h) do { _Pragma("unroll") for (int m = 0; m < 4; ++m) _Pragma("unroll") for (int k = 0; k < 2; ++k) dst[m][k] = *(const PG8_LAS bf16x8*)(lds + PG8_SA(b, h) + aoff + m * 2048 + k * 1024); } while (0)
; #define PG8_WAIT_V(n) asm volatile("s_waitcnt vmcnt(" #n ")" ::: "memory")
; #define PG8_WAIT_L(n) asm volatile("s_waitcnt lgkmcnt(" #n ")" ::: "memory")
; template <class Epi, class Sched, bool ALIGN_EPI = false, bool SP2 = false>
; __device__ __forceinline__ void gemm_phase(PG8_LAS unsigned char* lds, const Gemm g, const Sched& S, const Epi& E) {
;     ...
;             const char* a1 = cA + (size_t)(t + 1) * kstep;
;             const char* a2 = last ? nA : cA + (size_t)(t + 2) * kstep; const char* b2 = last ? nB : cB + (size_t)(t + 2) * kstep;
;             const char* a3 = a2 + kstep; const char* b3 = b2 + kstep;
;             if (last && has_next) S.a_ready(nxt);
;             if constexpr (epi_has_mid<Epi>::value) { if (t == Epi::MID_T) E.mid(acc, cur, wr, wc, fr, fq); }
;             if constexpr (SP2) {
;             PG8_LDB(B0, 0, 0); PG8_LDB(B1, 0, 1); PG8_SCHED; PG8_LDA(At, 0, 0); PG8_STAGE(PG8_SA(1, 1), a1 + hstep, voffA);
;             PG8_WAIT_V(8); PG8_WAIT_L(0); PG8_BAR; PG8_MMA(0, 0, At, B0); PG8_MMA(0, 1, At, B1); PG8_BAR; PG8_SCHED;
;             PG8_LDA(At, 0, 1); PG8_STAGE(PG8_SB(0, 0), b2, voffB); PG8_STAGE(PG8_SB(0, 1), b2 + hstep, voffB); PG8_STAGE(PG8_SA(0, 0), a2, voffA);
;             PG8_WAIT_V(8); PG8_WAIT_L(0); PG8_BAR; PG8_MMA(1, 0, At, B0); PG8_MMA(1, 1, At, B1); PG8_BAR; PG8_SCHED;
;             PG8_LDB(B0, 1, 0); PG8_LDB(B1, 1, 1); PG8_SCHED; PG8_LDA(At, 1, 0); PG8_STAGE(PG8_SA(0, 1), a2 + hstep, voffA);
;             PG8_WAIT_V(8); PG8_WAIT_L(0); PG8_BAR; PG8_MMA(0, 0, At, B0); PG8_MMA(0, 1, At, B1); PG8_BAR; PG8_SCHED;
;             PG8_LDA(At, 1, 1); PG8_STAGE(PG8_SB(1, 0), b3, voffB); PG8_STAGE(PG8_SB(1, 1), b3 + hstep, voffB); PG8_STAGE(PG8_SA(1, 0), a3, voffA);
;             PG8_WAIT_V(8); PG8_WAIT_L(0); PG8_BAR; PG8_MMA(1, 0, At, B0); PG8_MMA(1, 1, At, B1); PG8_BAR; PG8_SCHED;
.LBB0_234:
	ds_read_b128 v[134:137], v145
	ds_read_b128 v[152:155], v145 offset:1024
	ds_read_b128 v[156:159], v145 offset:2048
	ds_read_b128 v[160:163], v145 offset:3072
	ds_read_b128 v[164:167], v146
	ds_read_b128 v[168:171], v146 offset:1024
	ds_read_b128 v[172:175], v146 offset:2048
	ds_read_b128 v[176:179], v146 offset:3072
	s_cmpk_eq_i32 s57, 0xa8
	s_cselect_b32 s76, s4, s53
	s_cselect_b32 s77, s5, s54
	s_cselect_b32 s66, s46, s55
	s_cselect_b32 s67, s47, s56
	s_add_u32 s62, s76, 0x80
	s_addc_u32 s63, s77, 0
	ds_read_b128 v[180:183], v147
	ds_read_b128 v[184:187], v147 offset:1024
	ds_read_b128 v[188:191], v147 offset:2048
	ds_read_b128 v[192:195], v147 offset:3072
	ds_read_b128 v[196:199], v147 offset:4096
	ds_read_b128 v[200:203], v147 offset:5120
	ds_read_b128 v[204:207], v147 offset:6144
	ds_read_b128 v[208:211], v147 offset:7168
	s_mov_b32 m0, s94
	s_nop 0
	global_load_lds_dwordx4 v1, s[50:51]
	s_nop 0
	s_mov_b32 m0, s95
	s_nop 0
	global_load_lds_dwordx4 v141, s[50:51]
	s_waitcnt vmcnt(8)
	s_waitcnt lgkmcnt(0)
	s_barrier
	s_setprio 1
	s_waitcnt lgkmcnt(7)
	v_mfma_f32_16x16x32_bf16 v[126:129], v[134:137], v[180:183], v[126:129]
	v_mfma_f32_16x16x32_bf16 v[122:125], v[156:159], v[180:183], v[122:125]
	s_waitcnt lgkmcnt(5)
	v_mfma_f32_16x16x32_bf16 v[110:113], v[134:137], v[188:191], v[110:113]
	v_mfma_f32_16x16x32_bf16 v[106:109], v[156:159], v[188:191], v[106:109]
	s_waitcnt lgkmcnt(3)
	v_mfma_f32_16x16x32_bf16 v[94:97], v[134:137], v[196:199], v[94:97]
	v_mfma_f32_16x16x32_bf16 v[90:93], v[156:159], v[196:199], v[90:93]
	s_waitcnt lgkmcnt(1)
	v_mfma_f32_16x16x32_bf16 v[78:81], v[134:137], v[204:207], v[78:81]
	v_mfma_f32_16x16x32_bf16 v[74:77], v[156:159], v[204:207], v[74:77]
	v_mfma_f32_16x16x32_bf16 v[126:129], v[152:155], v[184:187], v[126:129]
	v_mfma_f32_16x16x32_bf16 v[122:125], v[160:163], v[184:187], v[122:125]
	v_mfma_f32_16x16x32_bf16 v[110:113], v[152:155], v[192:195], v[110:113]
	v_mfma_f32_16x16x32_bf16 v[106:109], v[160:163], v[192:195], v[106:109]
	v_mfma_f32_16x16x32_bf16 v[94:97], v[152:155], v[200:203], v[94:97]
	v_mfma_f32_16x16x32_bf16 v[90:93], v[160:163], v[200:203], v[90:93]
	s_waitcnt lgkmcnt(0)
	v_mfma_f32_16x16x32_bf16 v[78:81], v[152:155], v[208:211], v[78:81]
	v_mfma_f32_16x16x32_bf16 v[74:77], v[160:163], v[208:211], v[74:77]
	s_setprio 0
	s_setprio 1
	v_mfma_f32_16x16x32_bf16 v[118:121], v[164:167], v[180:183], v[118:121]
	v_mfma_f32_16x16x32_bf16 v[114:117], v[172:175], v[180:183], v[114:117]
	v_mfma_f32_16x16x32_bf16 v[102:105], v[164:167], v[188:191], v[102:105]
	v_mfma_f32_16x16x32_bf16 v[98:101], v[172:175], v[188:191], v[98:101]
	v_mfma_f32_16x16x32_bf16 v[86:89], v[164:167], v[196:199], v[86:89]
	v_mfma_f32_16x16x32_bf16 v[82:85], v[172:175], v[196:199], v[82:85]
	v_mfma_f32_16x16x32_bf16 v[70:73], v[164:167], v[204:207], v[70:73]
	v_mfma_f32_16x16x32_bf16 v[66:69], v[172:175], v[204:207], v[66:69]
	v_mfma_f32_16x16x32_bf16 v[118:121], v[168:171], v[184:187], v[118:121]
	v_mfma_f32_16x16x32_bf16 v[114:117], v[176:179], v[184:187], v[114:117]
	v_mfma_f32_16x16x32_bf16 v[102:105], v[168:171], v[192:195], v[102:105]
	v_mfma_f32_16x16x32_bf16 v[98:101], v[176:179], v[192:195], v[98:101]
	v_mfma_f32_16x16x32_bf16 v[86:89], v[168:171], v[200:203], v[86:89]
	v_mfma_f32_16x16x32_bf16 v[82:85], v[176:179], v[200:203], v[82:85]
	v_mfma_f32_16x16x32_bf16 v[70:73], v[168:171], v[208:211], v[70:73]
	s_barrier
	v_mfma_f32_16x16x32_bf16 v[66:69], v[176:179], v[208:211], v[66:69]
	s_setprio 0
	ds_read_b128 v[180:183], v147 offset:16384
	ds_read_b128 v[184:187], v147 offset:17408
	ds_read_b128 v[188:191], v147 offset:18432
	ds_read_b128 v[192:195], v147 offset:19456
	ds_read_b128 v[196:199], v147 offset:20480
	ds_read_b128 v[200:203], v147 offset:21504
	ds_read_b128 v[204:207], v147 offset:22528
	ds_read_b128 v[252:255], v147 offset:23552
	s_mov_b32 m0, s64
	s_nop 0
	global_load_lds_dwordx4 v140, s[66:67]
	s_add_u32 s58, s66, 0x2b0000
	s_mov_b32 m0, s65
	s_nop 0
	global_load_lds_dwordx4 v142, s[66:67]
	s_addc_u32 s59, s67, 0
	s_mov_b32 m0, s82
	s_nop 0
	global_load_lds_dwordx4 v140, s[58:59]
	s_nop 0
	s_mov_b32 m0, s83
	s_nop 0
	global_load_lds_dwordx4 v142, s[58:59]
	s_nop 0
	s_mov_b32 m0, s35
	s_nop 0
	global_load_lds_dwordx4 v1, s[76:77]
	s_nop 0
	s_mov_b32 m0, s84
	s_nop 0
	global_load_lds_dwordx4 v141, s[76:77]
	s_waitcnt vmcnt(8)
	s_waitcnt lgkmcnt(0)
	s_barrier
	s_setprio 1
	s_waitcnt lgkmcnt(7)
	v_mfma_f32_16x16x32_bf16 v[62:65], v[134:137], v[180:183], v[62:65]
	v_mfma_f32_16x16x32_bf16 v[58:61], v[156:159], v[180:183], v[58:61]
	s_waitcnt lgkmcnt(5)
	v_mfma_f32_16x16x32_bf16 v[46:49], v[134:137], v[188:191], v[46:49]
	v_mfma_f32_16x16x32_bf16 v[42:45], v[156:159], v[188:191], v[42:45]
	s_waitcnt lgkmcnt(3)
	v_mfma_f32_16x16x32_bf16 v[30:33], v[134:137], v[196:199], v[30:33]
	v_mfma_f32_16x16x32_bf16 v[26:29], v[156:159], v[196:199], v[26:29]
	s_waitcnt lgkmcnt(1)
	v_mfma_f32_16x16x32_bf16 v[14:17], v[134:137], v[204:207], v[14:17]
	v_mfma_f32_16x16x32_bf16 v[10:13], v[156:159], v[204:207], v[10:13]
	v_mfma_f32_16x16x32_bf16 v[62:65], v[152:155], v[184:187], v[62:65]
	v_mfma_f32_16x16x32_bf16 v[58:61], v[160:163], v[184:187], v[58:61]
	v_mfma_f32_16x16x32_bf16 v[46:49], v[152:155], v[192:195], v[46:49]
	v_mfma_f32_16x16x32_bf16 v[42:45], v[160:163], v[192:195], v[42:45]
	v_mfma_f32_16x16x32_bf16 v[30:33], v[152:155], v[200:203], v[30:33]
	v_mfma_f32_16x16x32_bf16 v[26:29], v[160:163], v[200:203], v[26:29]
	s_waitcnt lgkmcnt(0)
	v_mfma_f32_16x16x32_bf16 v[14:17], v[152:155], v[252:255], v[14:17]
	v_mfma_f32_16x16x32_bf16 v[10:13], v[160:163], v[252:255], v[10:13]
	s_setprio 0
	s_setprio 1
	v_mfma_f32_16x16x32_bf16 v[54:57], v[164:167], v[180:183], v[54:57]
	v_mfma_f32_16x16x32_bf16 v[50:53], v[172:175], v[180:183], v[50:53]
	v_mfma_f32_16x16x32_bf16 v[38:41], v[164:167], v[188:191], v[38:41]
	v_mfma_f32_16x16x32_bf16 v[34:37], v[172:175], v[188:191], v[34:37]
	v_mfma_f32_16x16x32_bf16 v[22:25], v[164:167], v[196:199], v[22:25]
	v_mfma_f32_16x16x32_bf16 v[18:21], v[172:175], v[196:199], v[18:21]
	v_mfma_f32_16x16x32_bf16 v[6:9], v[164:167], v[204:207], v[6:9]
	v_mfma_f32_16x16x32_bf16 v[2:5], v[172:175], v[204:207], v[2:5]
	v_mfma_f32_16x16x32_bf16 v[54:57], v[168:171], v[184:187], v[54:57]
	v_mfma_f32_16x16x32_bf16 v[50:53], v[176:179], v[184:187], v[50:53]
	v_mfma_f32_16x16x32_bf16 v[38:41], v[168:171], v[192:195], v[38:41]
	v_mfma_f32_16x16x32_bf16 v[34:37], v[176:179], v[192:195], v[34:37]
	v_mfma_f32_16x16x32_bf16 v[22:25], v[168:171], v[200:203], v[22:25]
	v_mfma_f32_16x16x32_bf16 v[18:21], v[176:179], v[200:203], v[18:21]
	v_mfma_f32_16x16x32_bf16 v[6:9], v[168:171], v[252:255], v[6:9]
	s_barrier
; #define PG8_STAGE(bufoff, gbase, voff) do { _Pragma("unroll") for (int _i = 0; _i < 2; ++_i) \
;         asm volatile("s_mov_b32 m0, %2\n\ts_nop 0\n\tglobal_load_lds_dwordx4 %0, %1" :: "v"((voff)[_i]), "s"((const char*)(gbase)), "s"(ldsbase + (unsigned)(bufoff) + ldsw + (unsigned)_i * 8192u) : "memory", "m0"); } while (0)
; #define PG8_LDA(dst, b, h) do { _Pragma("unroll") for (int m = 0; m < 4; ++m) _Pragma("unroll") for (int k = 0; k < 2; ++k) dst[m][k] = *(const PG8_LAS bf16x8*)(lds + PG8_SA(b, h) + aoff + m * 2048 + k * 1024); } while (0)
; #define PG8_LDB(dst, b, h) do { _Pragma("unroll") for (int n = 0; n < 2; ++n) _Pragma("unroll") for (int k = 0; k < 2; ++k) dst[n][k] = *(const PG8_LAS bf16x8*)(lds + PG8_SB(b, h) + boff + n * 2048 + k * 1024); } while (0)
; #define PG8_MMA(ai, bj, At, Bt) do { __builtin_amdgcn_s_setprio(1); _Pragma("unroll") for (int m = 0; m < 4; ++m) _Pragma("unroll") for (int n = 0; n < 2; ++n) _Pragma("unroll") for (int k = 0; k < 2; ++k) \
;         acc[ai][bj][m][n] = __builtin_amdgcn_mfma_f32_16x16x32_bf16(Bt[n][k], At[m][k], acc[ai][bj][m][n], 0, 0, 0); __builtin_amdgcn_s_setprio(0); } while (0)
; #define PG8_WAIT_V(n) asm volatile("s_waitcnt vmcnt(" #n ")" ::: "memory")
; #define PG8_WAIT_L(n) asm volatile("s_waitcnt lgkmcnt(" #n ")" ::: "memory")
; #define PG8_BAR __builtin_amdgcn_s_barrier()
; #define PG8_SCHED __builtin_amdgcn_sched_barrier(0)
; template <class Epi, class Sched, bool ALIGN_EPI = false, bool SP2 = false>
; __device__ __forceinline__ void gemm_phase(PG8_LAS unsigned char* lds, const Gemm g, const Sched& S, const Epi& E) {
;     ...
;             PG8_LDB(B0, 1, 0); PG8_LDB(B1, 1, 1); PG8_SCHED; PG8_LDA(At, 1, 0); PG8_STAGE(PG8_SA(0, 1), a2 + hstep, voffA);
;             PG8_WAIT_V(8); PG8_WAIT_L(0); PG8_BAR; PG8_MMA(0, 0, At, B0); PG8_MMA(0, 1, At, B1); PG8_BAR; PG8_SCHED;
	v_mfma_f32_16x16x32_bf16 v[2:5], v[176:179], v[252:255], v[2:5]
	s_setprio 0
	ds_read_b128 v[134:137], v148
	ds_read_b128 v[152:155], v148 offset:1024
	ds_read_b128 v[156:159], v148 offset:2048
	ds_read_b128 v[160:163], v148 offset:3072
	ds_read_b128 v[164:167], v149
	ds_read_b128 v[168:171], v149 offset:1024
	ds_read_b128 v[172:175], v149 offset:2048
	ds_read_b128 v[248:251], v149 offset:3072
	ds_read_b128 v[180:183], v147 offset:32768
	ds_read_b128 v[184:187], v147 offset:33792
	ds_read_b128 v[188:191], v147 offset:34816
	ds_read_b128 v[192:195], v147 offset:35840
	ds_read_b128 v[196:199], v147 offset:36864
	ds_read_b128 v[200:203], v147 offset:37888
	ds_read_b128 v[204:207], v147 offset:38912
	ds_read_b128 v[208:211], v147 offset:39936
	s_add_u32 s58, s76, 0x2b0000
	s_addc_u32 s59, s77, 0
	s_mov_b32 m0, s85
	s_nop 0
	global_load_lds_dwordx4 v1, s[58:59]
	s_nop 0
	s_mov_b32 m0, s86
	s_nop 0
	global_load_lds_dwordx4 v141, s[58:59]
	s_waitcnt vmcnt(8)
	s_waitcnt lgkmcnt(0)
	s_barrier
	s_setprio 1
	s_waitcnt lgkmcnt(7)
	v_mfma_f32_16x16x32_bf16 v[126:129], v[134:137], v[180:183], v[126:129]
	v_mfma_f32_16x16x32_bf16 v[122:125], v[156:159], v[180:183], v[122:125]
	s_waitcnt lgkmcnt(5)
	v_mfma_f32_16x16x32_bf16 v[110:113], v[134:137], v[188:191], v[110:113]
	v_mfma_f32_16x16x32_bf16 v[106:109], v[156:159], v[188:191], v[106:109]
	s_waitcnt lgkmcnt(3)
	v_mfma_f32_16x16x32_bf16 v[94:97], v[134:137], v[196:199], v[94:97]
	v_mfma_f32_16x16x32_bf16 v[90:93], v[156:159], v[196:199], v[90:93]
	s_waitcnt lgkmcnt(1)
	v_mfma_f32_16x16x32_bf16 v[78:81], v[134:137], v[204:207], v[78:81]
	v_mfma_f32_16x16x32_bf16 v[74:77], v[156:159], v[204:207], v[74:77]
	v_mfma_f32_16x16x32_bf16 v[126:129], v[152:155], v[184:187], v[126:129]
	v_mfma_f32_16x16x32_bf16 v[122:125], v[160:163], v[184:187], v[122:125]
	v_mfma_f32_16x16x32_bf16 v[110:113], v[152:155], v[192:195], v[110:113]
	v_mfma_f32_16x16x32_bf16 v[106:109], v[160:163], v[192:195], v[106:109]
	v_mfma_f32_16x16x32_bf16 v[94:97], v[152:155], v[200:203], v[94:97]
	v_mfma_f32_16x16x32_bf16 v[90:93], v[160:163], v[200:203], v[90:93]
	s_waitcnt lgkmcnt(0)
	v_mfma_f32_16x16x32_bf16 v[78:81], v[152:155], v[208:211], v[78:81]
	v_mfma_f32_16x16x32_bf16 v[74:77], v[160:163], v[208:211], v[74:77]
	s_setprio 0
	s_setprio 1
	v_mfma_f32_16x16x32_bf16 v[118:121], v[164:167], v[180:183], v[118:121]
	v_mfma_f32_16x16x32_bf16 v[114:117], v[172:175], v[180:183], v[114:117]
	v_mfma_f32_16x16x32_bf16 v[102:105], v[164:167], v[188:191], v[102:105]
	v_mfma_f32_16x16x32_bf16 v[98:101], v[172:175], v[188:191], v[98:101]
	v_mfma_f32_16x16x32_bf16 v[86:89], v[164:167], v[196:199], v[86:89]
	v_mfma_f32_16x16x32_bf16 v[82:85], v[172:175], v[196:199], v[82:85]
	v_mfma_f32_16x16x32_bf16 v[70:73], v[164:167], v[204:207], v[70:73]
	v_mfma_f32_16x16x32_bf16 v[66:69], v[172:175], v[204:207], v[66:69]
	v_mfma_f32_16x16x32_bf16 v[118:121], v[168:171], v[184:187], v[118:121]
	v_mfma_f32_16x16x32_bf16 v[114:117], v[248:251], v[184:187], v[114:117]
	v_mfma_f32_16x16x32_bf16 v[102:105], v[168:171], v[192:195], v[102:105]
	v_mfma_f32_16x16x32_bf16 v[98:101], v[248:251], v[192:195], v[98:101]
	v_mfma_f32_16x16x32_bf16 v[86:89], v[168:171], v[200:203], v[86:89]
	v_mfma_f32_16x16x32_bf16 v[82:85], v[248:251], v[200:203], v[82:85]
	v_mfma_f32_16x16x32_bf16 v[70:73], v[168:171], v[208:211], v[70:73]
	s_barrier
; #define PG8_STAGE(bufoff, gbase, voff) do { _Pragma("unroll") for (int _i = 0; _i < 2; ++_i) \
;         asm volatile("s_mov_b32 m0, %2\n\ts_nop 0\n\tglobal_load_lds_dwordx4 %0, %1" :: "v"((voff)[_i]), "s"((const char*)(gbase)), "s"(ldsbase + (unsigned)(bufoff) + ldsw + (unsigned)_i * 8192u) : "memory", "m0"); } while (0)
; #define PG8_LDA(dst, b, h) do { _Pragma("unroll") for (int m = 0; m < 4; ++m) _Pragma("unroll") for (int k = 0; k < 2; ++k) dst[m][k] = *(const PG8_LAS bf16x8*)(lds + PG8_SA(b, h) + aoff + m * 2048 + k * 1024); } while (0)
; #define PG8_MMA(ai, bj, At, Bt) do { __builtin_amdgcn_s_setprio(1); _Pragma("unroll") for (int m = 0; m < 4; ++m) _Pragma("unroll") for (int n = 0; n < 2; ++n) _Pragma("unroll") for (int k = 0; k < 2; ++k) \
;         acc[ai][bj][m][n] = __builtin_amdgcn_mfma_f32_16x16x32_bf16(Bt[n][k], At[m][k], acc[ai][bj][m][n], 0, 0, 0); __builtin_amdgcn_s_setprio(0); } while (0)
; #define PG8_WAIT_V(n) asm volatile("s_waitcnt vmcnt(" #n ")" ::: "memory")
; #define PG8_WAIT_L(n) asm volatile("s_waitcnt lgkmcnt(" #n ")" ::: "memory")
; #define PG8_BAR __builtin_amdgcn_s_barrier()
; #define PG8_SCHED __builtin_amdgcn_sched_barrier(0)
; template <class Epi, class Sched, bool ALIGN_EPI = false, bool SP2 = false>
; __device__ __forceinline__ void gemm_phase(PG8_LAS unsigned char* lds, const Gemm g, const Sched& S, const Epi& E) {
;     ...
;         for (int t = 0; t < nt; t += 2) {
;             const bool last = (t == nt - 2);
;             const char* a1 = cA + (size_t)(t + 1) * kstep;
;             const char* a2 = last ? nA : cA + (size_t)(t + 2) * kstep; const char* b2 = last ? nB : cB + (size_t)(t + 2) * kstep;
;             const char* a3 = a2 + kstep; const char* b3 = b2 + kstep;
;             if (last && has_next) S.a_ready(nxt);
;     ...
;             PG8_LDA(At, 1, 1); PG8_STAGE(PG8_SB(1, 0), b3, voffB); PG8_STAGE(PG8_SB(1, 1), b3 + hstep, voffB); PG8_STAGE(PG8_SA(1, 0), a3, voffA);
;             PG8_WAIT_V(8); PG8_WAIT_L(0); PG8_BAR; PG8_MMA(1, 0, At, B0); PG8_MMA(1, 1, At, B1); PG8_BAR; PG8_SCHED;
;     ...
;         if constexpr (ALIGN_EPI) { if (wr == 0) PG8_BAR; }
	v_mfma_f32_16x16x32_bf16 v[66:69], v[248:251], v[208:211], v[66:69]
	s_setprio 0
	ds_read_b128 v[180:183], v147 offset:49152
	ds_read_b128 v[184:187], v147 offset:50176
	ds_read_b128 v[188:191], v147 offset:51200
	ds_read_b128 v[192:195], v147 offset:52224
	ds_read_b128 v[196:199], v147 offset:53248
	ds_read_b128 v[200:203], v147 offset:54272
	ds_read_b128 v[204:207], v147 offset:55296
	ds_read_b128 v[252:255], v147 offset:56320
	s_add_u32 s58, s66, 0x80
	s_addc_u32 s59, s67, 0
	s_mov_b32 m0, s88
	s_nop 0
	global_load_lds_dwordx4 v140, s[58:59]
	s_nop 0
	s_mov_b32 m0, s89
	s_nop 0
	global_load_lds_dwordx4 v142, s[58:59]
	s_add_u32 s58, s66, 0x2b0080
	s_addc_u32 s59, s67, 0
	s_mov_b32 m0, s92
	s_nop 0
	global_load_lds_dwordx4 v140, s[58:59]
	s_nop 0
	s_mov_b32 m0, s93
	s_nop 0
	global_load_lds_dwordx4 v142, s[58:59]
	s_nop 0
	s_mov_b32 m0, s90
	s_nop 0
	global_load_lds_dwordx4 v1, s[62:63]
	s_nop 0
	s_mov_b32 m0, s91
	s_nop 0
	global_load_lds_dwordx4 v141, s[62:63]
	s_waitcnt vmcnt(8)
	s_waitcnt lgkmcnt(0)
	s_barrier
	s_setprio 1
	s_waitcnt lgkmcnt(7)
	v_mfma_f32_16x16x32_bf16 v[62:65], v[134:137], v[180:183], v[62:65]
	v_mfma_f32_16x16x32_bf16 v[58:61], v[156:159], v[180:183], v[58:61]
	s_waitcnt lgkmcnt(5)
	v_mfma_f32_16x16x32_bf16 v[46:49], v[134:137], v[188:191], v[46:49]
	v_mfma_f32_16x16x32_bf16 v[42:45], v[156:159], v[188:191], v[42:45]
	s_waitcnt lgkmcnt(3)
	v_mfma_f32_16x16x32_bf16 v[30:33], v[134:137], v[196:199], v[30:33]
	v_mfma_f32_16x16x32_bf16 v[26:29], v[156:159], v[196:199], v[26:29]
	s_waitcnt lgkmcnt(1)
	v_mfma_f32_16x16x32_bf16 v[14:17], v[134:137], v[204:207], v[14:17]
	v_mfma_f32_16x16x32_bf16 v[10:13], v[156:159], v[204:207], v[10:13]
	v_mfma_f32_16x16x32_bf16 v[62:65], v[152:155], v[184:187], v[62:65]
	v_mfma_f32_16x16x32_bf16 v[58:61], v[160:163], v[184:187], v[58:61]
	v_mfma_f32_16x16x32_bf16 v[46:49], v[152:155], v[192:195], v[46:49]
	v_mfma_f32_16x16x32_bf16 v[42:45], v[160:163], v[192:195], v[42:45]
	v_mfma_f32_16x16x32_bf16 v[30:33], v[152:155], v[200:203], v[30:33]
	v_mfma_f32_16x16x32_bf16 v[26:29], v[160:163], v[200:203], v[26:29]
	s_waitcnt lgkmcnt(0)
	v_mfma_f32_16x16x32_bf16 v[14:17], v[152:155], v[252:255], v[14:17]
	v_mfma_f32_16x16x32_bf16 v[10:13], v[160:163], v[252:255], v[10:13]
	s_setprio 0
	s_setprio 1
	v_mfma_f32_16x16x32_bf16 v[54:57], v[164:167], v[180:183], v[54:57]
	v_mfma_f32_16x16x32_bf16 v[50:53], v[172:175], v[180:183], v[50:53]
	v_mfma_f32_16x16x32_bf16 v[38:41], v[164:167], v[188:191], v[38:41]
	v_mfma_f32_16x16x32_bf16 v[34:37], v[172:175], v[188:191], v[34:37]
	v_mfma_f32_16x16x32_bf16 v[22:25], v[164:167], v[196:199], v[22:25]
	v_mfma_f32_16x16x32_bf16 v[18:21], v[172:175], v[196:199], v[18:21]
	v_mfma_f32_16x16x32_bf16 v[6:9], v[164:167], v[204:207], v[6:9]
	v_mfma_f32_16x16x32_bf16 v[2:5], v[172:175], v[204:207], v[2:5]
	v_mfma_f32_16x16x32_bf16 v[54:57], v[168:171], v[184:187], v[54:57]
	v_mfma_f32_16x16x32_bf16 v[50:53], v[248:251], v[184:187], v[50:53]
	v_mfma_f32_16x16x32_bf16 v[38:41], v[168:171], v[192:195], v[38:41]
	v_mfma_f32_16x16x32_bf16 v[34:37], v[248:251], v[192:195], v[34:37]
	v_mfma_f32_16x16x32_bf16 v[22:25], v[168:171], v[200:203], v[22:25]
	v_mfma_f32_16x16x32_bf16 v[18:21], v[248:251], v[200:203], v[18:21]
	v_mfma_f32_16x16x32_bf16 v[6:9], v[168:171], v[252:255], v[6:9]
	s_barrier
	v_mfma_f32_16x16x32_bf16 v[2:5], v[248:251], v[252:255], v[2:5]
	s_setprio 0
	s_add_i32 s57, s57, 2
	s_add_u32 s53, s53, 0x100
	s_addc_u32 s54, s54, 0
	s_add_u32 s55, s55, 0x100
	s_addc_u32 s56, s56, 0
	s_add_u32 s50, s50, 0x100
	s_addc_u32 s51, s51, 0
	s_cmpk_gt_u32 s57, 0xa9
	s_cbranch_scc0 .LBB0_234
	s_and_b64 vcc, exec, s[16:17]
	s_cbranch_vccz .LBB0_237
	s_barrier

; #define PG8_STAGE(bufoff, gbase, voff) do { _Pragma("unroll") for (int _i = 0; _i < 2; ++_i) \
;         asm volatile("s_mov_b32 m0, %2\n\ts_nop 0\n\tglobal_load_lds_dwordx4 %0, %1" :: "v"((voff)[_i]), "s"((const char*)(gbase)), "s"(ldsbase + (unsigned)(bufoff) + ldsw + (unsigned)_i * 8192u) : "memory", "m0"); } while (0)
; #define PG8_LDA(dst, b, h) do { _Pragma("unroll") for (int m = 0; m < 4; ++m) _Pragma("unroll") for (int k = 0; k < 2; ++k) dst[m][k] = *(const PG8_LAS bf16x8*)(lds + PG8_SA(b, h) + aoff + m * 2048 + k * 1024); } while (0)
; #define PG8_WAIT_V(n) asm volatile("s_waitcnt vmcnt(" #n ")" ::: "memory")
; #define PG8_WAIT_L(n) asm volatile("s_waitcnt lgkmcnt(" #n ")" ::: "memory")
; template <class Epi, class Sched, bool ALIGN_EPI = false, bool SP2 = false>
; __device__ __forceinline__ void gemm_phase(PG8_LAS unsigned char* lds, const Gemm g, const Sched& S, const Epi& E) {
;     ...
;             const char* a1 = cA + (size_t)(t + 1) * kstep;
;             const char* a2 = last ? nA : cA + (size_t)(t + 2) * kstep; const char* b2 = last ? nB : cB + (size_t)(t + 2) * kstep;
;             const char* a3 = a2 + kstep; const char* b3 = b2 + kstep;
;             if (last && has_next) S.a_ready(nxt);
;             if constexpr (epi_has_mid<Epi>::value) { if (t == Epi::MID_T) E.mid(acc, cur, wr, wc, fr, fq); }
;             if constexpr (SP2) {
;             PG8_LDB(B0, 0, 0); PG8_LDB(B1, 0, 1); PG8_SCHED; PG8_LDA(At, 0, 0); PG8_STAGE(PG8_SA(1, 1), a1 + hstep, voffA);
;             PG8_WAIT_V(8); PG8_WAIT_L(0); PG8_BAR; PG8_MMA(0, 0, At, B0); PG8_MMA(0, 1, At, B1); PG8_BAR; PG8_SCHED;
;             PG8_LDA(At, 0, 1); PG8_STAGE(PG8_SB(0, 0), b2, voffB); PG8_STAGE(PG8_SB(0, 1), b2 + hstep, voffB); PG8_STAGE(PG8_SA(0, 0), a2, voffA);
;             PG8_WAIT_V(8); PG8_WAIT_L(0); PG8_BAR; PG8_MMA(1, 0, At, B0); PG8_MMA(1, 1, At, B1); PG8_BAR; PG8_SCHED;
;             PG8_LDB(B0, 1, 0); PG8_LDB(B1, 1, 1); PG8_SCHED; PG8_LDA(At, 1, 0); PG8_STAGE(PG8_SA(0, 1), a2 + hstep, voffA);
;             PG8_WAIT_V(8); PG8_WAIT_L(0); PG8_BAR; PG8_MMA(0, 0, At, B0); PG8_MMA(0, 1, At, B1); PG8_BAR; PG8_SCHED;
;             PG8_LDA(At, 1, 1); PG8_STAGE(PG8_SB(1, 0), b3, voffB); PG8_STAGE(PG8_SB(1, 1), b3 + hstep, voffB); PG8_STAGE(PG8_SA(1, 0), a3, voffA);
;             PG8_WAIT_V(8); PG8_WAIT_L(0); PG8_BAR; PG8_MMA(1, 0, At, B0); PG8_MMA(1, 1, At, B1); PG8_BAR; PG8_SCHED;
.LBB0_325:
	v_add_u32_e32 v138, 0x10000, v151
	ds_read_b128 v[154:157], v138
	ds_read_b128 v[158:161], v138 offset:1024
	ds_read_b128 v[162:165], v138 offset:2048
	ds_read_b128 v[166:169], v138 offset:3072
	v_add_u32_e32 v138, 0x14000, v151
	s_add_u32 s8, s82, 0x100
	ds_read_b128 v[170:173], v138
	ds_read_b128 v[174:177], v138 offset:1024
	ds_read_b128 v[178:181], v138 offset:2048
	ds_read_b128 v[182:185], v138 offset:3072
	s_addc_u32 s9, s83, 0
	s_and_b64 s[60:61], s[62:63], exec
	s_cselect_b32 s84, s54, s8
	s_cselect_b32 s85, s19, s9
	s_cselect_b32 s63, s17, s57
	s_cselect_b32 s62, s55, s56
	s_add_u32 s66, s84, 0x80
	s_addc_u32 s67, s85, 0
	s_add_u32 s76, s62, 0x80
	s_addc_u32 s77, s63, 0
	ds_read_b128 v[186:189], v152
	ds_read_b128 v[190:193], v152 offset:1024
	ds_read_b128 v[194:197], v152 offset:2048
	ds_read_b128 v[198:201], v152 offset:3072
	ds_read_b128 v[202:205], v152 offset:4096
	ds_read_b128 v[206:209], v152 offset:5120
	ds_read_b128 v[210:213], v152 offset:6144
	ds_read_b128 v[214:217], v152 offset:7168
	s_add_u32 s60, s82, 0x100080
	s_addc_u32 s61, s83, 0
	s_mov_b32 m0, s97
	s_nop 0
	global_load_lds_dwordx4 v141, s[60:61]
	s_nop 0
	s_mov_b32 m0, s70
	s_nop 0
	global_load_lds_dwordx4 v143, s[60:61]
	s_waitcnt vmcnt(8)
	s_waitcnt lgkmcnt(0)
	s_barrier
	s_setprio 1
	s_waitcnt lgkmcnt(7)
	v_mfma_f32_16x16x32_bf16 v[126:129], v[154:157], v[186:189], v[126:129]
	v_mfma_f32_16x16x32_bf16 v[122:125], v[162:165], v[186:189], v[122:125]
	s_waitcnt lgkmcnt(5)
	v_mfma_f32_16x16x32_bf16 v[110:113], v[154:157], v[194:197], v[110:113]
	v_mfma_f32_16x16x32_bf16 v[106:109], v[162:165], v[194:197], v[106:109]
	s_waitcnt lgkmcnt(3)
	v_mfma_f32_16x16x32_bf16 v[94:97], v[154:157], v[202:205], v[94:97]
	v_mfma_f32_16x16x32_bf16 v[90:93], v[162:165], v[202:205], v[90:93]
	s_waitcnt lgkmcnt(1)
	v_mfma_f32_16x16x32_bf16 v[78:81], v[154:157], v[210:213], v[78:81]
	v_mfma_f32_16x16x32_bf16 v[74:77], v[162:165], v[210:213], v[74:77]
	v_mfma_f32_16x16x32_bf16 v[126:129], v[158:161], v[190:193], v[126:129]
	v_mfma_f32_16x16x32_bf16 v[122:125], v[166:169], v[190:193], v[122:125]
	v_mfma_f32_16x16x32_bf16 v[110:113], v[158:161], v[198:201], v[110:113]
	v_mfma_f32_16x16x32_bf16 v[106:109], v[166:169], v[198:201], v[106:109]
	v_mfma_f32_16x16x32_bf16 v[94:97], v[158:161], v[206:209], v[94:97]
	v_mfma_f32_16x16x32_bf16 v[90:93], v[166:169], v[206:209], v[90:93]
	s_waitcnt lgkmcnt(0)
	v_mfma_f32_16x16x32_bf16 v[78:81], v[158:161], v[214:217], v[78:81]
	v_mfma_f32_16x16x32_bf16 v[74:77], v[166:169], v[214:217], v[74:77]
	s_setprio 0
	s_setprio 1
	v_mfma_f32_16x16x32_bf16 v[118:121], v[170:173], v[186:189], v[118:121]
	v_mfma_f32_16x16x32_bf16 v[114:117], v[178:181], v[186:189], v[114:117]
	v_mfma_f32_16x16x32_bf16 v[102:105], v[170:173], v[194:197], v[102:105]
	v_mfma_f32_16x16x32_bf16 v[98:101], v[178:181], v[194:197], v[98:101]
	v_mfma_f32_16x16x32_bf16 v[86:89], v[170:173], v[202:205], v[86:89]
	v_mfma_f32_16x16x32_bf16 v[82:85], v[178:181], v[202:205], v[82:85]
	v_mfma_f32_16x16x32_bf16 v[70:73], v[170:173], v[210:213], v[70:73]
	v_mfma_f32_16x16x32_bf16 v[66:69], v[178:181], v[210:213], v[66:69]
	v_mfma_f32_16x16x32_bf16 v[118:121], v[174:177], v[190:193], v[118:121]
	v_mfma_f32_16x16x32_bf16 v[114:117], v[182:185], v[190:193], v[114:117]
	v_mfma_f32_16x16x32_bf16 v[102:105], v[174:177], v[198:201], v[102:105]
	v_mfma_f32_16x16x32_bf16 v[98:101], v[182:185], v[198:201], v[98:101]
	v_mfma_f32_16x16x32_bf16 v[86:89], v[174:177], v[206:209], v[86:89]
	v_mfma_f32_16x16x32_bf16 v[82:85], v[182:185], v[206:209], v[82:85]
	v_mfma_f32_16x16x32_bf16 v[70:73], v[174:177], v[214:217], v[70:73]
	s_barrier
	v_mfma_f32_16x16x32_bf16 v[66:69], v[182:185], v[214:217], v[66:69]
	s_setprio 0
	ds_read_b128 v[186:189], v152 offset:16384
	ds_read_b128 v[190:193], v152 offset:17408
	ds_read_b128 v[194:197], v152 offset:18432
	ds_read_b128 v[198:201], v152 offset:19456
	ds_read_b128 v[202:205], v152 offset:20480
	ds_read_b128 v[206:209], v152 offset:21504
	ds_read_b128 v[210:213], v152 offset:22528
	ds_read_b128 v[252:255], v152 offset:23552
	s_mov_b32 m0, s68
	s_nop 0
	global_load_lds_dwordx4 v142, s[62:63]
	s_add_u32 s60, s62, 0x100000
	s_mov_b32 m0, s69
	s_nop 0
	global_load_lds_dwordx4 v144, s[62:63]
	s_addc_u32 s61, s63, 0
	s_mov_b32 m0, s81
	s_nop 0
	global_load_lds_dwordx4 v142, s[60:61]
	s_nop 0
	s_mov_b32 m0, s86
	s_nop 0
	global_load_lds_dwordx4 v144, s[60:61]
	s_nop 0
	s_mov_b32 m0, s65
	s_nop 0
	global_load_lds_dwordx4 v141, s[84:85]
	s_nop 0
	s_mov_b32 m0, s87
	s_nop 0
	global_load_lds_dwordx4 v143, s[84:85]
	s_waitcnt vmcnt(8)
	s_waitcnt lgkmcnt(0)
	s_barrier
; #define PG8_STAGE(bufoff, gbase, voff) do { _Pragma("unroll") for (int _i = 0; _i < 2; ++_i) \
;         asm volatile("s_mov_b32 m0, %2\n\ts_nop 0\n\tglobal_load_lds_dwordx4 %0, %1" :: "v"((voff)[_i]), "s"((const char*)(gbase)), "s"(ldsbase + (unsigned)(bufoff) + ldsw + (unsigned)_i * 8192u) : "memory", "m0"); } while (0)
; #define PG8_LDA(dst, b, h) do { _Pragma("unroll") for (int m = 0; m < 4; ++m) _Pragma("unroll") for (int k = 0; k < 2; ++k) dst[m][k] = *(const PG8_LAS bf16x8*)(lds + PG8_SA(b, h) + aoff + m * 2048 + k * 1024); } while (0)
; #define PG8_LDB(dst, b, h) do { _Pragma("unroll") for (int n = 0; n < 2; ++n) _Pragma("unroll") for (int k = 0; k < 2; ++k) dst[n][k] = *(const PG8_LAS bf16x8*)(lds + PG8_SB(b, h) + boff + n * 2048 + k * 1024); } while (0)
; #define PG8_MMA(ai, bj, At, Bt) do { __builtin_amdgcn_s_setprio(1); _Pragma("unroll") for (int m = 0; m < 4; ++m) _Pragma("unroll") for (int n = 0; n < 2; ++n) _Pragma("unroll") for (int k = 0; k < 2; ++k) \
;         acc[ai][bj][m][n] = __builtin_amdgcn_mfma_f32_16x16x32_bf16(Bt[n][k], At[m][k], acc[ai][bj][m][n], 0, 0, 0); __builtin_amdgcn_s_setprio(0); } while (0)
; #define PG8_WAIT_V(n) asm volatile("s_waitcnt vmcnt(" #n ")" ::: "memory")
; #define PG8_BAR __builtin_amdgcn_s_barrier()
; template <class Epi, class Sched, bool ALIGN_EPI = false, bool SP2 = false>
; __device__ __forceinline__ void gemm_phase(PG8_LAS unsigned char* lds, const Gemm g, const Sched& S, const Epi& E) {
;     ...
;             PG8_WAIT_V(8); PG8_WAIT_L(0); PG8_BAR; PG8_MMA(0, 0, At, B0); PG8_MMA(0, 1, At, B1); PG8_BAR; PG8_SCHED;
;             PG8_LDA(At, 0, 1); PG8_STAGE(PG8_SB(0, 0), b2, voffB); PG8_STAGE(PG8_SB(0, 1), b2 + hstep, voffB); PG8_STAGE(PG8_SA(0, 0), a2, voffA);
;             PG8_WAIT_V(8); PG8_WAIT_L(0); PG8_BAR; PG8_MMA(1, 0, At, B0); PG8_MMA(1, 1, At, B1); PG8_BAR; PG8_SCHED;
;             PG8_LDB(B0, 1, 0); PG8_LDB(B1, 1, 1); PG8_SCHED; PG8_LDA(At, 1, 0); PG8_STAGE(PG8_SA(0, 1), a2 + hstep, voffA);
;             PG8_WAIT_V(8); PG8_WAIT_L(0); PG8_BAR; PG8_MMA(0, 0, At, B0); PG8_MMA(0, 1, At, B1); PG8_BAR; PG8_SCHED;
;             PG8_LDA(At, 1, 1); PG8_STAGE(PG8_SB(1, 0), b3, voffB); PG8_STAGE(PG8_SB(1, 1), b3 + hstep, voffB); PG8_STAGE(PG8_SA(1, 0), a3, voffA);
;             PG8_WAIT_V(8); PG8_WAIT_L(0); PG8_BAR; PG8_MMA(1, 0, At, B0); PG8_MMA(1, 1, At, B1); PG8_BAR; PG8_SCHED;
	s_setprio 1
	s_waitcnt lgkmcnt(7)
	v_mfma_f32_16x16x32_bf16 v[62:65], v[154:157], v[186:189], v[62:65]
	v_mfma_f32_16x16x32_bf16 v[58:61], v[162:165], v[186:189], v[58:61]
	s_waitcnt lgkmcnt(5)
	v_mfma_f32_16x16x32_bf16 v[46:49], v[154:157], v[194:197], v[46:49]
	v_mfma_f32_16x16x32_bf16 v[42:45], v[162:165], v[194:197], v[42:45]
	s_waitcnt lgkmcnt(3)
	v_mfma_f32_16x16x32_bf16 v[30:33], v[154:157], v[202:205], v[30:33]
	v_mfma_f32_16x16x32_bf16 v[26:29], v[162:165], v[202:205], v[26:29]
	s_waitcnt lgkmcnt(1)
	v_mfma_f32_16x16x32_bf16 v[14:17], v[154:157], v[210:213], v[14:17]
	v_mfma_f32_16x16x32_bf16 v[10:13], v[162:165], v[210:213], v[10:13]
	v_mfma_f32_16x16x32_bf16 v[62:65], v[158:161], v[190:193], v[62:65]
	v_mfma_f32_16x16x32_bf16 v[58:61], v[166:169], v[190:193], v[58:61]
	v_mfma_f32_16x16x32_bf16 v[46:49], v[158:161], v[198:201], v[46:49]
	v_mfma_f32_16x16x32_bf16 v[42:45], v[166:169], v[198:201], v[42:45]
	v_mfma_f32_16x16x32_bf16 v[30:33], v[158:161], v[206:209], v[30:33]
	v_mfma_f32_16x16x32_bf16 v[26:29], v[166:169], v[206:209], v[26:29]
	s_waitcnt lgkmcnt(0)
	v_mfma_f32_16x16x32_bf16 v[14:17], v[158:161], v[252:255], v[14:17]
	v_mfma_f32_16x16x32_bf16 v[10:13], v[166:169], v[252:255], v[10:13]
	s_setprio 0
	s_setprio 1
	v_mfma_f32_16x16x32_bf16 v[54:57], v[170:173], v[186:189], v[54:57]
	v_mfma_f32_16x16x32_bf16 v[50:53], v[178:181], v[186:189], v[50:53]
	v_mfma_f32_16x16x32_bf16 v[38:41], v[170:173], v[194:197], v[38:41]
	v_mfma_f32_16x16x32_bf16 v[34:37], v[178:181], v[194:197], v[34:37]
	v_mfma_f32_16x16x32_bf16 v[22:25], v[170:173], v[202:205], v[22:25]
	v_mfma_f32_16x16x32_bf16 v[18:21], v[178:181], v[202:205], v[18:21]
	v_mfma_f32_16x16x32_bf16 v[6:9], v[170:173], v[210:213], v[6:9]
	v_mfma_f32_16x16x32_bf16 v[2:5], v[178:181], v[210:213], v[2:5]
	v_mfma_f32_16x16x32_bf16 v[54:57], v[174:177], v[190:193], v[54:57]
	v_mfma_f32_16x16x32_bf16 v[50:53], v[182:185], v[190:193], v[50:53]
	v_mfma_f32_16x16x32_bf16 v[38:41], v[174:177], v[198:201], v[38:41]
	v_mfma_f32_16x16x32_bf16 v[34:37], v[182:185], v[198:201], v[34:37]
	v_mfma_f32_16x16x32_bf16 v[22:25], v[174:177], v[206:209], v[22:25]
	v_mfma_f32_16x16x32_bf16 v[18:21], v[182:185], v[206:209], v[18:21]
	v_mfma_f32_16x16x32_bf16 v[6:9], v[174:177], v[252:255], v[6:9]
	s_barrier
	v_mfma_f32_16x16x32_bf16 v[2:5], v[182:185], v[252:255], v[2:5]
	s_setprio 0
	v_add_u32_e32 v138, 0x18000, v151
	ds_read_b128 v[154:157], v138
	ds_read_b128 v[158:161], v138 offset:1024
	ds_read_b128 v[162:165], v138 offset:2048
	ds_read_b128 v[166:169], v138 offset:3072
	v_add_u32_e32 v138, 0x1c000, v151
	ds_read_b128 v[170:173], v138
	ds_read_b128 v[174:177], v138 offset:1024
	ds_read_b128 v[178:181], v138 offset:2048
	ds_read_b128 v[248:251], v138 offset:3072
	ds_read_b128 v[186:189], v152 offset:32768
	ds_read_b128 v[190:193], v152 offset:33792
	ds_read_b128 v[194:197], v152 offset:34816
	ds_read_b128 v[198:201], v152 offset:35840
	ds_read_b128 v[202:205], v152 offset:36864
	ds_read_b128 v[206:209], v152 offset:37888
	ds_read_b128 v[210:213], v152 offset:38912
	ds_read_b128 v[214:217], v152 offset:39936
	s_add_u32 s60, s84, 0x100000
	s_addc_u32 s61, s85, 0
	s_mov_b32 m0, s88
	s_nop 0
	global_load_lds_dwordx4 v141, s[60:61]
	s_nop 0
	s_mov_b32 m0, s89
	s_nop 0
	global_load_lds_dwordx4 v143, s[60:61]
	s_waitcnt vmcnt(8)
	s_waitcnt lgkmcnt(0)
	s_barrier
	s_setprio 1
	s_waitcnt lgkmcnt(7)
	v_mfma_f32_16x16x32_bf16 v[126:129], v[154:157], v[186:189], v[126:129]
	v_mfma_f32_16x16x32_bf16 v[122:125], v[162:165], v[186:189], v[122:125]
	s_waitcnt lgkmcnt(5)
	v_mfma_f32_16x16x32_bf16 v[110:113], v[154:157], v[194:197], v[110:113]
	v_mfma_f32_16x16x32_bf16 v[106:109], v[162:165], v[194:197], v[106:109]
	s_waitcnt lgkmcnt(3)
	v_mfma_f32_16x16x32_bf16 v[94:97], v[154:157], v[202:205], v[94:97]
	v_mfma_f32_16x16x32_bf16 v[90:93], v[162:165], v[202:205], v[90:93]
	s_waitcnt lgkmcnt(1)
	v_mfma_f32_16x16x32_bf16 v[78:81], v[154:157], v[210:213], v[78:81]
	v_mfma_f32_16x16x32_bf16 v[74:77], v[162:165], v[210:213], v[74:77]
	v_mfma_f32_16x16x32_bf16 v[126:129], v[158:161], v[190:193], v[126:129]
	v_mfma_f32_16x16x32_bf16 v[122:125], v[166:169], v[190:193], v[122:125]
	v_mfma_f32_16x16x32_bf16 v[110:113], v[158:161], v[198:201], v[110:113]
	v_mfma_f32_16x16x32_bf16 v[106:109], v[166:169], v[198:201], v[106:109]
	v_mfma_f32_16x16x32_bf16 v[94:97], v[158:161], v[206:209], v[94:97]
	v_mfma_f32_16x16x32_bf16 v[90:93], v[166:169], v[206:209], v[90:93]
	s_waitcnt lgkmcnt(0)
	v_mfma_f32_16x16x32_bf16 v[78:81], v[158:161], v[214:217], v[78:81]
	v_mfma_f32_16x16x32_bf16 v[74:77], v[166:169], v[214:217], v[74:77]
	s_setprio 0
	s_setprio 1
	v_mfma_f32_16x16x32_bf16 v[118:121], v[170:173], v[186:189], v[118:121]
	v_mfma_f32_16x16x32_bf16 v[114:117], v[178:181], v[186:189], v[114:117]
	v_mfma_f32_16x16x32_bf16 v[102:105], v[170:173], v[194:197], v[102:105]
	v_mfma_f32_16x16x32_bf16 v[98:101], v[178:181], v[194:197], v[98:101]
	v_mfma_f32_16x16x32_bf16 v[86:89], v[170:173], v[202:205], v[86:89]
	v_mfma_f32_16x16x32_bf16 v[82:85], v[178:181], v[202:205], v[82:85]
	v_mfma_f32_16x16x32_bf16 v[70:73], v[170:173], v[210:213], v[70:73]
	v_mfma_f32_16x16x32_bf16 v[66:69], v[178:181], v[210:213], v[66:69]
	v_mfma_f32_16x16x32_bf16 v[118:121], v[174:177], v[190:193], v[118:121]
	v_mfma_f32_16x16x32_bf16 v[114:117], v[248:251], v[190:193], v[114:117]
	v_mfma_f32_16x16x32_bf16 v[102:105], v[174:177], v[198:201], v[102:105]
	v_mfma_f32_16x16x32_bf16 v[98:101], v[248:251], v[198:201], v[98:101]
	v_mfma_f32_16x16x32_bf16 v[86:89], v[174:177], v[206:209], v[86:89]
	v_mfma_f32_16x16x32_bf16 v[82:85], v[248:251], v[206:209], v[82:85]
	v_mfma_f32_16x16x32_bf16 v[70:73], v[174:177], v[214:217], v[70:73]
	s_barrier
; #define PG8_STAGE(bufoff, gbase, voff) do { _Pragma("unroll") for (int _i = 0; _i < 2; ++_i) \
;         asm volatile("s_mov_b32 m0, %2\n\ts_nop 0\n\tglobal_load_lds_dwordx4 %0, %1" :: "v"((voff)[_i]), "s"((const char*)(gbase)), "s"(ldsbase + (unsigned)(bufoff) + ldsw + (unsigned)_i * 8192u) : "memory", "m0"); } while (0)
; #define PG8_LDA(dst, b, h) do { _Pragma("unroll") for (int m = 0; m < 4; ++m) _Pragma("unroll") for (int k = 0; k < 2; ++k) dst[m][k] = *(const PG8_LAS bf16x8*)(lds + PG8_SA(b, h) + aoff + m * 2048 + k * 1024); } while (0)
; #define PG8_MMA(ai, bj, At, Bt) do { __builtin_amdgcn_s_setprio(1); _Pragma("unroll") for (int m = 0; m < 4; ++m) _Pragma("unroll") for (int n = 0; n < 2; ++n) _Pragma("unroll") for (int k = 0; k < 2; ++k) \
;         acc[ai][bj][m][n] = __builtin_amdgcn_mfma_f32_16x16x32_bf16(Bt[n][k], At[m][k], acc[ai][bj][m][n], 0, 0, 0); __builtin_amdgcn_s_setprio(0); } while (0)
; #define PG8_WAIT_V(n) asm volatile("s_waitcnt vmcnt(" #n ")" ::: "memory")
; #define PG8_WAIT_L(n) asm volatile("s_waitcnt lgkmcnt(" #n ")" ::: "memory")
; #define PG8_BAR __builtin_amdgcn_s_barrier()
; #define PG8_SCHED __builtin_amdgcn_sched_barrier(0)
; template <class Epi, class Sched, bool ALIGN_EPI = false, bool SP2 = false>
; __device__ __forceinline__ void gemm_phase(PG8_LAS unsigned char* lds, const Gemm g, const Sched& S, const Epi& E) {
;     ...
;         for (int t = 0; t < nt; t += 2) {
;     ...
;             PG8_LDA(At, 1, 1); PG8_STAGE(PG8_SB(1, 0), b3, voffB); PG8_STAGE(PG8_SB(1, 1), b3 + hstep, voffB); PG8_STAGE(PG8_SA(1, 0), a3, voffA);
;             PG8_WAIT_V(8); PG8_WAIT_L(0); PG8_BAR; PG8_MMA(1, 0, At, B0); PG8_MMA(1, 1, At, B1); PG8_BAR; PG8_SCHED;
	v_mfma_f32_16x16x32_bf16 v[66:69], v[248:251], v[214:217], v[66:69]
	s_setprio 0
	ds_read_b128 v[186:189], v152 offset:49152
	ds_read_b128 v[190:193], v152 offset:50176
	ds_read_b128 v[194:197], v152 offset:51200
	ds_read_b128 v[198:201], v152 offset:52224
	ds_read_b128 v[202:205], v152 offset:53248
	ds_read_b128 v[206:209], v152 offset:54272
	ds_read_b128 v[210:213], v152 offset:55296
	ds_read_b128 v[252:255], v152 offset:56320
	s_mov_b32 m0, s90
	s_nop 0
	global_load_lds_dwordx4 v142, s[76:77]
	s_add_u32 s60, s62, 0x100080
	s_mov_b32 m0, s91
	s_nop 0
	global_load_lds_dwordx4 v144, s[76:77]
	s_addc_u32 s61, s63, 0
	s_mov_b32 m0, s95
	s_nop 0
	global_load_lds_dwordx4 v142, s[60:61]
	s_nop 0
	s_mov_b32 m0, s96
	s_nop 0
	global_load_lds_dwordx4 v144, s[60:61]
	s_nop 0
	s_mov_b32 m0, s92
	s_nop 0
	global_load_lds_dwordx4 v141, s[66:67]
	s_nop 0
	s_mov_b32 m0, s94
	s_nop 0
	global_load_lds_dwordx4 v143, s[66:67]
	s_waitcnt vmcnt(8)
	s_waitcnt lgkmcnt(0)
	s_barrier
	s_setprio 1
	s_waitcnt lgkmcnt(7)
	v_mfma_f32_16x16x32_bf16 v[62:65], v[154:157], v[186:189], v[62:65]
	v_mfma_f32_16x16x32_bf16 v[58:61], v[162:165], v[186:189], v[58:61]
	s_waitcnt lgkmcnt(5)
	v_mfma_f32_16x16x32_bf16 v[46:49], v[154:157], v[194:197], v[46:49]
	v_mfma_f32_16x16x32_bf16 v[42:45], v[162:165], v[194:197], v[42:45]
	s_waitcnt lgkmcnt(3)
	v_mfma_f32_16x16x32_bf16 v[30:33], v[154:157], v[202:205], v[30:33]
	v_mfma_f32_16x16x32_bf16 v[26:29], v[162:165], v[202:205], v[26:29]
	s_waitcnt lgkmcnt(1)
	v_mfma_f32_16x16x32_bf16 v[14:17], v[154:157], v[210:213], v[14:17]
	v_mfma_f32_16x16x32_bf16 v[10:13], v[162:165], v[210:213], v[10:13]
	v_mfma_f32_16x16x32_bf16 v[62:65], v[158:161], v[190:193], v[62:65]
	v_mfma_f32_16x16x32_bf16 v[58:61], v[166:169], v[190:193], v[58:61]
	v_mfma_f32_16x16x32_bf16 v[46:49], v[158:161], v[198:201], v[46:49]
	v_mfma_f32_16x16x32_bf16 v[42:45], v[166:169], v[198:201], v[42:45]
	v_mfma_f32_16x16x32_bf16 v[30:33], v[158:161], v[206:209], v[30:33]
	v_mfma_f32_16x16x32_bf16 v[26:29], v[166:169], v[206:209], v[26:29]
	s_waitcnt lgkmcnt(0)
	v_mfma_f32_16x16x32_bf16 v[14:17], v[158:161], v[252:255], v[14:17]
	v_mfma_f32_16x16x32_bf16 v[10:13], v[166:169], v[252:255], v[10:13]
	s_setprio 0
	s_setprio 1
	v_mfma_f32_16x16x32_bf16 v[54:57], v[170:173], v[186:189], v[54:57]
	v_mfma_f32_16x16x32_bf16 v[50:53], v[178:181], v[186:189], v[50:53]
	v_mfma_f32_16x16x32_bf16 v[38:41], v[170:173], v[194:197], v[38:41]
	v_mfma_f32_16x16x32_bf16 v[34:37], v[178:181], v[194:197], v[34:37]
	v_mfma_f32_16x16x32_bf16 v[22:25], v[170:173], v[202:205], v[22:25]
	v_mfma_f32_16x16x32_bf16 v[18:21], v[178:181], v[202:205], v[18:21]
	v_mfma_f32_16x16x32_bf16 v[6:9], v[170:173], v[210:213], v[6:9]
	v_mfma_f32_16x16x32_bf16 v[2:5], v[178:181], v[210:213], v[2:5]
	v_mfma_f32_16x16x32_bf16 v[54:57], v[174:177], v[190:193], v[54:57]
	v_mfma_f32_16x16x32_bf16 v[50:53], v[248:251], v[190:193], v[50:53]
	v_mfma_f32_16x16x32_bf16 v[38:41], v[174:177], v[198:201], v[38:41]
	v_mfma_f32_16x16x32_bf16 v[34:37], v[248:251], v[198:201], v[34:37]
	v_mfma_f32_16x16x32_bf16 v[22:25], v[174:177], v[206:209], v[22:25]
	v_mfma_f32_16x16x32_bf16 v[18:21], v[248:251], v[206:209], v[18:21]
	v_mfma_f32_16x16x32_bf16 v[6:9], v[174:177], v[252:255], v[6:9]
	s_barrier
	v_mfma_f32_16x16x32_bf16 v[2:5], v[248:251], v[252:255], v[2:5]
	s_setprio 0
	s_add_i32 s58, s58, 2
	s_add_u32 s56, s56, 0x100
	s_addc_u32 s57, s57, 0
	s_cmp_gt_u32 s58, 61
	s_cbranch_scc1 .LBB0_316
	s_mov_b64 s[82:83], s[8:9]
	s_branch .LBB0_320

; #define PG8_STAGE(bufoff, gbase, voff) do { _Pragma("unroll") for (int _i = 0; _i < 2; ++_i) \
;         asm volatile("s_mov_b32 m0, %2\n\ts_nop 0\n\tglobal_load_lds_dwordx4 %0, %1" :: "v"((voff)[_i]), "s"((const char*)(gbase)), "s"(ldsbase + (unsigned)(bufoff) + ldsw + (unsigned)_i * 8192u) : "memory", "m0"); } while (0)
; #define PG8_LDA(dst, b, h) do { _Pragma("unroll") for (int m = 0; m < 4; ++m) _Pragma("unroll") for (int k = 0; k < 2; ++k) dst[m][k] = *(const PG8_LAS bf16x8*)(lds + PG8_SA(b, h) + aoff + m * 2048 + k * 1024); } while (0)
; #define PG8_WAIT_V(n) asm volatile("s_waitcnt vmcnt(" #n ")" ::: "memory")
; #define PG8_WAIT_L(n) asm volatile("s_waitcnt lgkmcnt(" #n ")" ::: "memory")
; template <class Epi, class Sched, bool ALIGN_EPI = false, bool SP2 = false>
; __device__ __forceinline__ void gemm_phase(PG8_LAS unsigned char* lds, const Gemm g, const Sched& S, const Epi& E) {
;     ...
;             const char* a1 = cA + (size_t)(t + 1) * kstep;
;             const char* a2 = last ? nA : cA + (size_t)(t + 2) * kstep; const char* b2 = last ? nB : cB + (size_t)(t + 2) * kstep;
;             const char* a3 = a2 + kstep; const char* b3 = b2 + kstep;
;             if (last && has_next) S.a_ready(nxt);
;             if constexpr (epi_has_mid<Epi>::value) { if (t == Epi::MID_T) E.mid(acc, cur, wr, wc, fr, fq); }
;             if constexpr (SP2) {
;             PG8_LDB(B0, 0, 0); PG8_LDB(B1, 0, 1); PG8_SCHED; PG8_LDA(At, 0, 0); PG8_STAGE(PG8_SA(1, 1), a1 + hstep, voffA);
;             PG8_WAIT_V(8); PG8_WAIT_L(0); PG8_BAR; PG8_MMA(0, 0, At, B0); PG8_MMA(0, 1, At, B1); PG8_BAR; PG8_SCHED;
;             PG8_LDA(At, 0, 1); PG8_STAGE(PG8_SB(0, 0), b2, voffB); PG8_STAGE(PG8_SB(0, 1), b2 + hstep, voffB); PG8_STAGE(PG8_SA(0, 0), a2, voffA);
;             PG8_WAIT_V(8); PG8_WAIT_L(0); PG8_BAR; PG8_MMA(1, 0, At, B0); PG8_MMA(1, 1, At, B1); PG8_BAR; PG8_SCHED;
;             PG8_LDB(B0, 1, 0); PG8_LDB(B1, 1, 1); PG8_SCHED; PG8_LDA(At, 1, 0); PG8_STAGE(PG8_SA(0, 1), a2 + hstep, voffA);
;             PG8_WAIT_V(8); PG8_WAIT_L(0); PG8_BAR; PG8_MMA(0, 0, At, B0); PG8_MMA(0, 1, At, B1); PG8_BAR; PG8_SCHED;
;             PG8_LDA(At, 1, 1); PG8_STAGE(PG8_SB(1, 0), b3, voffB); PG8_STAGE(PG8_SB(1, 1), b3 + hstep, voffB); PG8_STAGE(PG8_SA(1, 0), a3, voffA);
;             PG8_WAIT_V(8); PG8_WAIT_L(0); PG8_BAR; PG8_MMA(1, 0, At, B0); PG8_MMA(1, 1, At, B1); PG8_BAR; PG8_SCHED;
.LBB0_620:
	v_add_u32_e32 v3, 0x10000, v199
	ds_read_b128 v[134:137], v3
	ds_read_b128 v[138:141], v3 offset:1024
	ds_read_b128 v[142:145], v3 offset:2048
	ds_read_b128 v[146:149], v3 offset:3072
	v_add_u32_e32 v3, 0x14000, v199
	s_add_u32 s44, s42, 0x100
	ds_read_b128 v[158:161], v3
	ds_read_b128 v[162:165], v3 offset:1024
	ds_read_b128 v[166:169], v3 offset:2048
	ds_read_b128 v[170:173], v3 offset:3072
	s_addc_u32 s45, s43, 0
	s_cmp_eq_u32 s92, 60
	s_cselect_b32 s56, s88, s44
	s_cselect_b32 s57, s23, s45
	s_cselect_b32 s47, s19, s91
	s_cselect_b32 s46, s89, s90
	s_add_u32 s50, s56, 0x80
	s_addc_u32 s51, s57, 0
	s_add_u32 s54, s46, 0x80
	s_addc_u32 s55, s47, 0
	ds_read_b128 v[174:177], v200
	ds_read_b128 v[178:181], v200 offset:1024
	ds_read_b128 v[182:185], v200 offset:2048
	ds_read_b128 v[186:189], v200 offset:3072
	ds_read_b128 v[190:193], v200 offset:4096
	ds_read_b128 v[202:205], v200 offset:5120
	ds_read_b128 v[206:209], v200 offset:6144
	ds_read_b128 v[210:213], v200 offset:7168
	s_add_u32 s42, s42, 0x100080
	s_addc_u32 s43, s43, 0
	s_mov_b32 m0, s85
	s_nop 0
	global_load_lds_dwordx4 v1, s[42:43]
	s_nop 0
	s_mov_b32 m0, s86
	s_nop 0
	global_load_lds_dwordx4 v195, s[42:43]
	s_waitcnt vmcnt(8)
	s_waitcnt lgkmcnt(0)
	s_barrier
	s_setprio 1
	s_waitcnt lgkmcnt(7)
	v_mfma_f32_16x16x32_bf16 v[130:133], v[134:137], v[174:177], v[130:133]
	v_mfma_f32_16x16x32_bf16 v[126:129], v[142:145], v[174:177], v[126:129]
	s_waitcnt lgkmcnt(5)
	v_mfma_f32_16x16x32_bf16 v[122:125], v[134:137], v[182:185], v[122:125]
	v_mfma_f32_16x16x32_bf16 v[118:121], v[142:145], v[182:185], v[118:121]
	s_waitcnt lgkmcnt(3)
	v_mfma_f32_16x16x32_bf16 v[114:117], v[134:137], v[190:193], v[114:117]
	v_mfma_f32_16x16x32_bf16 v[110:113], v[142:145], v[190:193], v[110:113]
	s_waitcnt lgkmcnt(1)
	v_mfma_f32_16x16x32_bf16 v[106:109], v[134:137], v[206:209], v[106:109]
	v_mfma_f32_16x16x32_bf16 v[102:105], v[142:145], v[206:209], v[102:105]
	v_mfma_f32_16x16x32_bf16 v[130:133], v[138:141], v[178:181], v[130:133]
	v_mfma_f32_16x16x32_bf16 v[126:129], v[146:149], v[178:181], v[126:129]
	v_mfma_f32_16x16x32_bf16 v[122:125], v[138:141], v[186:189], v[122:125]
	v_mfma_f32_16x16x32_bf16 v[118:121], v[146:149], v[186:189], v[118:121]
	v_mfma_f32_16x16x32_bf16 v[114:117], v[138:141], v[202:205], v[114:117]
	v_mfma_f32_16x16x32_bf16 v[110:113], v[146:149], v[202:205], v[110:113]
	s_waitcnt lgkmcnt(0)
	v_mfma_f32_16x16x32_bf16 v[106:109], v[138:141], v[210:213], v[106:109]
	v_mfma_f32_16x16x32_bf16 v[102:105], v[146:149], v[210:213], v[102:105]
	s_setprio 0
	s_setprio 1
	v_mfma_f32_16x16x32_bf16 v[66:69], v[158:161], v[174:177], v[66:69]
	v_mfma_f32_16x16x32_bf16 v[62:65], v[166:169], v[174:177], v[62:65]
	v_mfma_f32_16x16x32_bf16 v[58:61], v[158:161], v[182:185], v[58:61]
	v_mfma_f32_16x16x32_bf16 v[54:57], v[166:169], v[182:185], v[54:57]
	v_mfma_f32_16x16x32_bf16 v[50:53], v[158:161], v[190:193], v[50:53]
	v_mfma_f32_16x16x32_bf16 v[46:49], v[166:169], v[190:193], v[46:49]
	v_mfma_f32_16x16x32_bf16 v[42:45], v[158:161], v[206:209], v[42:45]
	v_mfma_f32_16x16x32_bf16 v[38:41], v[166:169], v[206:209], v[38:41]
	v_mfma_f32_16x16x32_bf16 v[66:69], v[162:165], v[178:181], v[66:69]
	v_mfma_f32_16x16x32_bf16 v[62:65], v[170:173], v[178:181], v[62:65]
	v_mfma_f32_16x16x32_bf16 v[58:61], v[162:165], v[186:189], v[58:61]
	v_mfma_f32_16x16x32_bf16 v[54:57], v[170:173], v[186:189], v[54:57]
	v_mfma_f32_16x16x32_bf16 v[50:53], v[162:165], v[202:205], v[50:53]
	v_mfma_f32_16x16x32_bf16 v[46:49], v[170:173], v[202:205], v[46:49]
	v_mfma_f32_16x16x32_bf16 v[42:45], v[162:165], v[210:213], v[42:45]
	s_barrier
	v_mfma_f32_16x16x32_bf16 v[38:41], v[170:173], v[210:213], v[38:41]
	s_setprio 0
	ds_read_b128 v[174:177], v200 offset:16384
	ds_read_b128 v[178:181], v200 offset:17408
	ds_read_b128 v[182:185], v200 offset:18432
	ds_read_b128 v[186:189], v200 offset:19456
	ds_read_b128 v[190:193], v200 offset:20480
	ds_read_b128 v[202:205], v200 offset:21504
	ds_read_b128 v[206:209], v200 offset:22528
	ds_read_b128 v[252:255], v200 offset:23552
	s_mov_b32 m0, s63
	s_nop 0
	global_load_lds_dwordx4 v194, s[46:47]
	s_add_u32 s42, s46, 0x100000
	s_mov_b32 m0, s64
	s_nop 0
	global_load_lds_dwordx4 v196, s[46:47]
	s_addc_u32 s43, s47, 0
	s_mov_b32 m0, s65
	s_nop 0
	global_load_lds_dwordx4 v194, s[42:43]
	s_nop 0
	s_mov_b32 m0, s66
	s_nop 0
	global_load_lds_dwordx4 v196, s[42:43]
	s_nop 0
	s_mov_b32 m0, s62
	s_nop 0
	global_load_lds_dwordx4 v1, s[56:57]
	s_nop 0
	s_mov_b32 m0, s67
	s_nop 0
	global_load_lds_dwordx4 v195, s[56:57]
	s_waitcnt vmcnt(8)
	s_waitcnt lgkmcnt(0)
	s_barrier
; #define PG8_STAGE(bufoff, gbase, voff) do { _Pragma("unroll") for (int _i = 0; _i < 2; ++_i) \
;         asm volatile("s_mov_b32 m0, %2\n\ts_nop 0\n\tglobal_load_lds_dwordx4 %0, %1" :: "v"((voff)[_i]), "s"((const char*)(gbase)), "s"(ldsbase + (unsigned)(bufoff) + ldsw + (unsigned)_i * 8192u) : "memory", "m0"); } while (0)
; #define PG8_LDA(dst, b, h) do { _Pragma("unroll") for (int m = 0; m < 4; ++m) _Pragma("unroll") for (int k = 0; k < 2; ++k) dst[m][k] = *(const PG8_LAS bf16x8*)(lds + PG8_SA(b, h) + aoff + m * 2048 + k * 1024); } while (0)
; #define PG8_LDB(dst, b, h) do { _Pragma("unroll") for (int n = 0; n < 2; ++n) _Pragma("unroll") for (int k = 0; k < 2; ++k) dst[n][k] = *(const PG8_LAS bf16x8*)(lds + PG8_SB(b, h) + boff + n * 2048 + k * 1024); } while (0)
; #define PG8_MMA(ai, bj, At, Bt) do { __builtin_amdgcn_s_setprio(1); _Pragma("unroll") for (int m = 0; m < 4; ++m) _Pragma("unroll") for (int n = 0; n < 2; ++n) _Pragma("unroll") for (int k = 0; k < 2; ++k) \
;         acc[ai][bj][m][n] = __builtin_amdgcn_mfma_f32_16x16x32_bf16(Bt[n][k], At[m][k], acc[ai][bj][m][n], 0, 0, 0); __builtin_amdgcn_s_setprio(0); } while (0)
; #define PG8_WAIT_V(n) asm volatile("s_waitcnt vmcnt(" #n ")" ::: "memory")
; #define PG8_BAR __builtin_amdgcn_s_barrier()
; template <class Epi, class Sched, bool ALIGN_EPI = false, bool SP2 = false>
; __device__ __forceinline__ void gemm_phase(PG8_LAS unsigned char* lds, const Gemm g, const Sched& S, const Epi& E) {
;     ...
;             PG8_WAIT_V(8); PG8_WAIT_L(0); PG8_BAR; PG8_MMA(0, 0, At, B0); PG8_MMA(0, 1, At, B1); PG8_BAR; PG8_SCHED;
;             PG8_LDA(At, 0, 1); PG8_STAGE(PG8_SB(0, 0), b2, voffB); PG8_STAGE(PG8_SB(0, 1), b2 + hstep, voffB); PG8_STAGE(PG8_SA(0, 0), a2, voffA);
;             PG8_WAIT_V(8); PG8_WAIT_L(0); PG8_BAR; PG8_MMA(1, 0, At, B0); PG8_MMA(1, 1, At, B1); PG8_BAR; PG8_SCHED;
;             PG8_LDB(B0, 1, 0); PG8_LDB(B1, 1, 1); PG8_SCHED; PG8_LDA(At, 1, 0); PG8_STAGE(PG8_SA(0, 1), a2 + hstep, voffA);
;             PG8_WAIT_V(8); PG8_WAIT_L(0); PG8_BAR; PG8_MMA(0, 0, At, B0); PG8_MMA(0, 1, At, B1); PG8_BAR; PG8_SCHED;
;             PG8_LDA(At, 1, 1); PG8_STAGE(PG8_SB(1, 0), b3, voffB); PG8_STAGE(PG8_SB(1, 1), b3 + hstep, voffB); PG8_STAGE(PG8_SA(1, 0), a3, voffA);
;             PG8_WAIT_V(8); PG8_WAIT_L(0); PG8_BAR; PG8_MMA(1, 0, At, B0); PG8_MMA(1, 1, At, B1); PG8_BAR; PG8_SCHED;
	s_setprio 1
	s_waitcnt lgkmcnt(7)
	v_mfma_f32_16x16x32_bf16 v[98:101], v[134:137], v[174:177], v[98:101]
	v_mfma_f32_16x16x32_bf16 v[94:97], v[142:145], v[174:177], v[94:97]
	s_waitcnt lgkmcnt(5)
	v_mfma_f32_16x16x32_bf16 v[90:93], v[134:137], v[182:185], v[90:93]
	v_mfma_f32_16x16x32_bf16 v[86:89], v[142:145], v[182:185], v[86:89]
	s_waitcnt lgkmcnt(3)
	v_mfma_f32_16x16x32_bf16 v[82:85], v[134:137], v[190:193], v[82:85]
	v_mfma_f32_16x16x32_bf16 v[78:81], v[142:145], v[190:193], v[78:81]
	s_waitcnt lgkmcnt(1)
	v_mfma_f32_16x16x32_bf16 v[74:77], v[134:137], v[206:209], v[74:77]
	v_mfma_f32_16x16x32_bf16 v[70:73], v[142:145], v[206:209], v[70:73]
	v_mfma_f32_16x16x32_bf16 v[98:101], v[138:141], v[178:181], v[98:101]
	v_mfma_f32_16x16x32_bf16 v[94:97], v[146:149], v[178:181], v[94:97]
	v_mfma_f32_16x16x32_bf16 v[90:93], v[138:141], v[186:189], v[90:93]
	v_mfma_f32_16x16x32_bf16 v[86:89], v[146:149], v[186:189], v[86:89]
	v_mfma_f32_16x16x32_bf16 v[82:85], v[138:141], v[202:205], v[82:85]
	v_mfma_f32_16x16x32_bf16 v[78:81], v[146:149], v[202:205], v[78:81]
	s_waitcnt lgkmcnt(0)
	v_mfma_f32_16x16x32_bf16 v[74:77], v[138:141], v[252:255], v[74:77]
	v_mfma_f32_16x16x32_bf16 v[70:73], v[146:149], v[252:255], v[70:73]
	s_setprio 0
	s_setprio 1
	v_mfma_f32_16x16x32_bf16 v[34:37], v[158:161], v[174:177], v[34:37]
	v_mfma_f32_16x16x32_bf16 v[30:33], v[166:169], v[174:177], v[30:33]
	v_mfma_f32_16x16x32_bf16 v[26:29], v[158:161], v[182:185], v[26:29]
	v_mfma_f32_16x16x32_bf16 v[22:25], v[166:169], v[182:185], v[22:25]
	v_mfma_f32_16x16x32_bf16 v[18:21], v[158:161], v[190:193], v[18:21]
	v_mfma_f32_16x16x32_bf16 v[14:17], v[166:169], v[190:193], v[14:17]
	v_mfma_f32_16x16x32_bf16 v[10:13], v[158:161], v[206:209], v[10:13]
	v_mfma_f32_16x16x32_bf16 v[4:7], v[166:169], v[206:209], v[6:9]
	v_mfma_f32_16x16x32_bf16 v[34:37], v[162:165], v[178:181], v[34:37]
	v_mfma_f32_16x16x32_bf16 v[30:33], v[170:173], v[178:181], v[30:33]
	v_mfma_f32_16x16x32_bf16 v[26:29], v[162:165], v[186:189], v[26:29]
	v_mfma_f32_16x16x32_bf16 v[22:25], v[170:173], v[186:189], v[22:25]
	v_mfma_f32_16x16x32_bf16 v[18:21], v[162:165], v[202:205], v[18:21]
	v_mfma_f32_16x16x32_bf16 v[14:17], v[170:173], v[202:205], v[14:17]
	v_mfma_f32_16x16x32_bf16 v[10:13], v[162:165], v[252:255], v[10:13]
	s_barrier
	v_mfma_f32_16x16x32_bf16 v[4:7], v[170:173], v[252:255], v[4:7]
	s_setprio 0
	v_add_u32_e32 v3, 0x18000, v199
	ds_read_b128 v[134:137], v3
	ds_read_b128 v[138:141], v3 offset:1024
	ds_read_b128 v[142:145], v3 offset:2048
	ds_read_b128 v[146:149], v3 offset:3072
	v_add_u32_e32 v3, 0x1c000, v199
	ds_read_b128 v[158:161], v3
	ds_read_b128 v[162:165], v3 offset:1024
	ds_read_b128 v[166:169], v3 offset:2048
	ds_read_b128 v[248:251], v3 offset:3072
	ds_read_b128 v[174:177], v200 offset:32768
	ds_read_b128 v[178:181], v200 offset:33792
	ds_read_b128 v[182:185], v200 offset:34816
	ds_read_b128 v[186:189], v200 offset:35840
	ds_read_b128 v[190:193], v200 offset:36864
	ds_read_b128 v[202:205], v200 offset:37888
	ds_read_b128 v[206:209], v200 offset:38912
	ds_read_b128 v[210:213], v200 offset:39936
	s_add_u32 s42, s56, 0x100000
	s_addc_u32 s43, s57, 0
	s_mov_b32 m0, s76
	s_nop 0
	global_load_lds_dwordx4 v1, s[42:43]
	s_nop 0
	s_mov_b32 m0, s77
	s_nop 0
	global_load_lds_dwordx4 v195, s[42:43]
	s_waitcnt vmcnt(8)
	s_waitcnt lgkmcnt(0)
	s_barrier
	s_setprio 1
	s_waitcnt lgkmcnt(7)
	v_mfma_f32_16x16x32_bf16 v[130:133], v[134:137], v[174:177], v[130:133]
	v_mfma_f32_16x16x32_bf16 v[126:129], v[142:145], v[174:177], v[126:129]
	s_waitcnt lgkmcnt(5)
	v_mfma_f32_16x16x32_bf16 v[122:125], v[134:137], v[182:185], v[122:125]
	v_mfma_f32_16x16x32_bf16 v[118:121], v[142:145], v[182:185], v[118:121]
	s_waitcnt lgkmcnt(3)
	v_mfma_f32_16x16x32_bf16 v[114:117], v[134:137], v[190:193], v[114:117]
	v_mfma_f32_16x16x32_bf16 v[110:113], v[142:145], v[190:193], v[110:113]
	s_waitcnt lgkmcnt(1)
	v_mfma_f32_16x16x32_bf16 v[106:109], v[134:137], v[206:209], v[106:109]
	v_mfma_f32_16x16x32_bf16 v[102:105], v[142:145], v[206:209], v[102:105]
	v_mfma_f32_16x16x32_bf16 v[130:133], v[138:141], v[178:181], v[130:133]
	v_mfma_f32_16x16x32_bf16 v[126:129], v[146:149], v[178:181], v[126:129]
	v_mfma_f32_16x16x32_bf16 v[122:125], v[138:141], v[186:189], v[122:125]
	v_mfma_f32_16x16x32_bf16 v[118:121], v[146:149], v[186:189], v[118:121]
	v_mfma_f32_16x16x32_bf16 v[114:117], v[138:141], v[202:205], v[114:117]
	v_mfma_f32_16x16x32_bf16 v[110:113], v[146:149], v[202:205], v[110:113]
	s_waitcnt lgkmcnt(0)
	v_mfma_f32_16x16x32_bf16 v[106:109], v[138:141], v[210:213], v[106:109]
	v_mfma_f32_16x16x32_bf16 v[102:105], v[146:149], v[210:213], v[102:105]
	s_setprio 0
	s_setprio 1
	v_mfma_f32_16x16x32_bf16 v[66:69], v[158:161], v[174:177], v[66:69]
	v_mfma_f32_16x16x32_bf16 v[62:65], v[166:169], v[174:177], v[62:65]
	v_mfma_f32_16x16x32_bf16 v[58:61], v[158:161], v[182:185], v[58:61]
	v_mfma_f32_16x16x32_bf16 v[54:57], v[166:169], v[182:185], v[54:57]
	v_mfma_f32_16x16x32_bf16 v[50:53], v[158:161], v[190:193], v[50:53]
	v_mfma_f32_16x16x32_bf16 v[46:49], v[166:169], v[190:193], v[46:49]
	v_mfma_f32_16x16x32_bf16 v[42:45], v[158:161], v[206:209], v[42:45]
	v_mfma_f32_16x16x32_bf16 v[38:41], v[166:169], v[206:209], v[38:41]
	v_mfma_f32_16x16x32_bf16 v[66:69], v[162:165], v[178:181], v[66:69]
	v_mfma_f32_16x16x32_bf16 v[62:65], v[248:251], v[178:181], v[62:65]
	v_mfma_f32_16x16x32_bf16 v[58:61], v[162:165], v[186:189], v[58:61]
	v_mfma_f32_16x16x32_bf16 v[54:57], v[248:251], v[186:189], v[54:57]
	v_mfma_f32_16x16x32_bf16 v[50:53], v[162:165], v[202:205], v[50:53]
	v_mfma_f32_16x16x32_bf16 v[46:49], v[248:251], v[202:205], v[46:49]
	v_mfma_f32_16x16x32_bf16 v[42:45], v[162:165], v[210:213], v[42:45]
	s_barrier
; #define PG8_STAGE(bufoff, gbase, voff) do { _Pragma("unroll") for (int _i = 0; _i < 2; ++_i) \
;         asm volatile("s_mov_b32 m0, %2\n\ts_nop 0\n\tglobal_load_lds_dwordx4 %0, %1" :: "v"((voff)[_i]), "s"((const char*)(gbase)), "s"(ldsbase + (unsigned)(bufoff) + ldsw + (unsigned)_i * 8192u) : "memory", "m0"); } while (0)
; #define PG8_LDA(dst, b, h) do { _Pragma("unroll") for (int m = 0; m < 4; ++m) _Pragma("unroll") for (int k = 0; k < 2; ++k) dst[m][k] = *(const PG8_LAS bf16x8*)(lds + PG8_SA(b, h) + aoff + m * 2048 + k * 1024); } while (0)
; #define PG8_MMA(ai, bj, At, Bt) do { __builtin_amdgcn_s_setprio(1); _Pragma("unroll") for (int m = 0; m < 4; ++m) _Pragma("unroll") for (int n = 0; n < 2; ++n) _Pragma("unroll") for (int k = 0; k < 2; ++k) \
;         acc[ai][bj][m][n] = __builtin_amdgcn_mfma_f32_16x16x32_bf16(Bt[n][k], At[m][k], acc[ai][bj][m][n], 0, 0, 0); __builtin_amdgcn_s_setprio(0); } while (0)
; #define PG8_WAIT_V(n) asm volatile("s_waitcnt vmcnt(" #n ")" ::: "memory")
; #define PG8_WAIT_L(n) asm volatile("s_waitcnt lgkmcnt(" #n ")" ::: "memory")
; #define PG8_BAR __builtin_amdgcn_s_barrier()
; #define PG8_SCHED __builtin_amdgcn_sched_barrier(0)
; template <class Epi, class Sched, bool ALIGN_EPI = false, bool SP2 = false>
; __device__ __forceinline__ void gemm_phase(PG8_LAS unsigned char* lds, const Gemm g, const Sched& S, const Epi& E) {
;     ...
;         for (int t = 0; t < nt; t += 2) {
;     ...
;             if constexpr (epi_has_mid<Epi>::value) { if (t == Epi::MID_T) E.mid(acc, cur, wr, wc, fr, fq); }
;     ...
;             PG8_LDA(At, 1, 1); PG8_STAGE(PG8_SB(1, 0), b3, voffB); PG8_STAGE(PG8_SB(1, 1), b3 + hstep, voffB); PG8_STAGE(PG8_SA(1, 0), a3, voffA);
;             PG8_WAIT_V(8); PG8_WAIT_L(0); PG8_BAR; PG8_MMA(1, 0, At, B0); PG8_MMA(1, 1, At, B1); PG8_BAR; PG8_SCHED;
	v_mfma_f32_16x16x32_bf16 v[38:41], v[248:251], v[210:213], v[38:41]
	s_setprio 0
	ds_read_b128 v[174:177], v200 offset:49152
	ds_read_b128 v[178:181], v200 offset:50176
	ds_read_b128 v[182:185], v200 offset:51200
	ds_read_b128 v[186:189], v200 offset:52224
	ds_read_b128 v[190:193], v200 offset:53248
	ds_read_b128 v[202:205], v200 offset:54272
	ds_read_b128 v[206:209], v200 offset:55296
	ds_read_b128 v[252:255], v200 offset:56320
	s_mov_b32 m0, s78
	s_nop 0
	global_load_lds_dwordx4 v194, s[54:55]
	s_add_u32 s42, s46, 0x100080
	s_mov_b32 m0, s79
	s_nop 0
	global_load_lds_dwordx4 v196, s[54:55]
	s_addc_u32 s43, s47, 0
	s_mov_b32 m0, s83
	s_nop 0
	global_load_lds_dwordx4 v194, s[42:43]
	s_nop 0
	s_mov_b32 m0, s84
	s_nop 0
	global_load_lds_dwordx4 v196, s[42:43]
	s_nop 0
	s_mov_b32 m0, s80
	s_nop 0
	global_load_lds_dwordx4 v1, s[50:51]
	s_nop 0
	s_mov_b32 m0, s82
	s_nop 0
	global_load_lds_dwordx4 v195, s[50:51]
	s_waitcnt vmcnt(8)
	s_waitcnt lgkmcnt(0)
	s_barrier
	s_setprio 1
	s_waitcnt lgkmcnt(7)
	v_mfma_f32_16x16x32_bf16 v[98:101], v[134:137], v[174:177], v[98:101]
	v_mfma_f32_16x16x32_bf16 v[94:97], v[142:145], v[174:177], v[94:97]
	s_waitcnt lgkmcnt(5)
	v_mfma_f32_16x16x32_bf16 v[90:93], v[134:137], v[182:185], v[90:93]
	v_mfma_f32_16x16x32_bf16 v[86:89], v[142:145], v[182:185], v[86:89]
	s_waitcnt lgkmcnt(3)
	v_mfma_f32_16x16x32_bf16 v[82:85], v[134:137], v[190:193], v[82:85]
	v_mfma_f32_16x16x32_bf16 v[78:81], v[142:145], v[190:193], v[78:81]
	s_waitcnt lgkmcnt(1)
	v_mfma_f32_16x16x32_bf16 v[74:77], v[134:137], v[206:209], v[74:77]
	v_mfma_f32_16x16x32_bf16 v[70:73], v[142:145], v[206:209], v[70:73]
	v_mfma_f32_16x16x32_bf16 v[98:101], v[138:141], v[178:181], v[98:101]
	v_mfma_f32_16x16x32_bf16 v[94:97], v[146:149], v[178:181], v[94:97]
	v_mfma_f32_16x16x32_bf16 v[90:93], v[138:141], v[186:189], v[90:93]
	v_mfma_f32_16x16x32_bf16 v[86:89], v[146:149], v[186:189], v[86:89]
	v_mfma_f32_16x16x32_bf16 v[82:85], v[138:141], v[202:205], v[82:85]
	v_mfma_f32_16x16x32_bf16 v[78:81], v[146:149], v[202:205], v[78:81]
	s_waitcnt lgkmcnt(0)
	v_mfma_f32_16x16x32_bf16 v[74:77], v[138:141], v[252:255], v[74:77]
	v_mfma_f32_16x16x32_bf16 v[70:73], v[146:149], v[252:255], v[70:73]
	s_setprio 0
	s_setprio 1
	v_mfma_f32_16x16x32_bf16 v[34:37], v[158:161], v[174:177], v[34:37]
	v_mfma_f32_16x16x32_bf16 v[30:33], v[166:169], v[174:177], v[30:33]
	v_mfma_f32_16x16x32_bf16 v[26:29], v[158:161], v[182:185], v[26:29]
	v_mfma_f32_16x16x32_bf16 v[22:25], v[166:169], v[182:185], v[22:25]
	v_mfma_f32_16x16x32_bf16 v[18:21], v[158:161], v[190:193], v[18:21]
	v_mfma_f32_16x16x32_bf16 v[14:17], v[166:169], v[190:193], v[14:17]
	v_mfma_f32_16x16x32_bf16 v[8:11], v[158:161], v[206:209], v[10:13]
	v_mfma_f32_16x16x32_bf16 v[4:7], v[166:169], v[206:209], v[4:7]
	v_mfma_f32_16x16x32_bf16 v[34:37], v[162:165], v[178:181], v[34:37]
	v_mfma_f32_16x16x32_bf16 v[30:33], v[248:251], v[178:181], v[30:33]
	v_mfma_f32_16x16x32_bf16 v[26:29], v[162:165], v[186:189], v[26:29]
	v_mfma_f32_16x16x32_bf16 v[22:25], v[248:251], v[186:189], v[22:25]
	v_mfma_f32_16x16x32_bf16 v[18:21], v[162:165], v[202:205], v[18:21]
	v_mfma_f32_16x16x32_bf16 v[14:17], v[248:251], v[202:205], v[14:17]
	v_mfma_f32_16x16x32_bf16 v[10:13], v[162:165], v[252:255], v[8:11]
	s_barrier
	v_mfma_f32_16x16x32_bf16 v[6:9], v[248:251], v[252:255], v[4:7]
	s_setprio 0
	s_add_i32 s92, s92, 2
	s_add_u32 s90, s90, 0x100
	s_addc_u32 s91, s91, 0
	s_cmp_gt_u32 s92, 61
	s_cbranch_scc1 .LBB0_622
	s_mov_b64 s[42:43], s[44:45]
	s_cmp_lg_u32 s92, 30
	s_cbranch_scc0 .LBB0_619
	s_branch .LBB0_620

; #define PG8_STAGE(bufoff, gbase, voff) do { _Pragma("unroll") for (int _i = 0; _i < 2; ++_i) \
;         asm volatile("s_mov_b32 m0, %2\n\ts_nop 0\n\tglobal_load_lds_dwordx4 %0, %1" :: "v"((voff)[_i]), "s"((const char*)(gbase)), "s"(ldsbase + (unsigned)(bufoff) + ldsw + (unsigned)_i * 8192u) : "memory", "m0"); } while (0)
; #define PG8_LDA(dst, b, h) do { _Pragma("unroll") for (int m = 0; m < 4; ++m) _Pragma("unroll") for (int k = 0; k < 2; ++k) dst[m][k] = *(const PG8_LAS bf16x8*)(lds + PG8_SA(b, h) + aoff + m * 2048 + k * 1024); } while (0)
; #define PG8_WAIT_V(n) asm volatile("s_waitcnt vmcnt(" #n ")" ::: "memory")
; #define PG8_WAIT_L(n) asm volatile("s_waitcnt lgkmcnt(" #n ")" ::: "memory")
; template <class Epi, class Sched, bool ALIGN_EPI = false, bool SP2 = false>
; __device__ __forceinline__ void gemm_phase(PG8_LAS unsigned char* lds, const Gemm g, const Sched& S, const Epi& E) {
;     ...
;             const char* a1 = cA + (size_t)(t + 1) * kstep;
;             const char* a2 = last ? nA : cA + (size_t)(t + 2) * kstep; const char* b2 = last ? nB : cB + (size_t)(t + 2) * kstep;
;             const char* a3 = a2 + kstep; const char* b3 = b2 + kstep;
;             if (last && has_next) S.a_ready(nxt);
;             if constexpr (epi_has_mid<Epi>::value) { if (t == Epi::MID_T) E.mid(acc, cur, wr, wc, fr, fq); }
;             if constexpr (SP2) {
;             PG8_LDB(B0, 0, 0); PG8_LDB(B1, 0, 1); PG8_SCHED; PG8_LDA(At, 0, 0); PG8_STAGE(PG8_SA(1, 1), a1 + hstep, voffA);
;             PG8_WAIT_V(8); PG8_WAIT_L(0); PG8_BAR; PG8_MMA(0, 0, At, B0); PG8_MMA(0, 1, At, B1); PG8_BAR; PG8_SCHED;
;             PG8_LDA(At, 0, 1); PG8_STAGE(PG8_SB(0, 0), b2, voffB); PG8_STAGE(PG8_SB(0, 1), b2 + hstep, voffB); PG8_STAGE(PG8_SA(0, 0), a2, voffA);
;             PG8_WAIT_V(8); PG8_WAIT_L(0); PG8_BAR; PG8_MMA(1, 0, At, B0); PG8_MMA(1, 1, At, B1); PG8_BAR; PG8_SCHED;
;             PG8_LDB(B0, 1, 0); PG8_LDB(B1, 1, 1); PG8_SCHED; PG8_LDA(At, 1, 0); PG8_STAGE(PG8_SA(0, 1), a2 + hstep, voffA);
;             PG8_WAIT_V(8); PG8_WAIT_L(0); PG8_BAR; PG8_MMA(0, 0, At, B0); PG8_MMA(0, 1, At, B1); PG8_BAR; PG8_SCHED;
;             PG8_LDA(At, 1, 1); PG8_STAGE(PG8_SB(1, 0), b3, voffB); PG8_STAGE(PG8_SB(1, 1), b3 + hstep, voffB); PG8_STAGE(PG8_SA(1, 0), a3, voffA);
;             PG8_WAIT_V(8); PG8_WAIT_L(0); PG8_BAR; PG8_MMA(1, 0, At, B0); PG8_MMA(1, 1, At, B1); PG8_BAR; PG8_SCHED;
.LBB0_698:
	ds_read_b128 v[134:137], v145
	ds_read_b128 v[152:155], v145 offset:1024
	ds_read_b128 v[156:159], v145 offset:2048
	ds_read_b128 v[160:163], v145 offset:3072
	ds_read_b128 v[164:167], v146
	ds_read_b128 v[168:171], v146 offset:1024
	ds_read_b128 v[172:175], v146 offset:2048
	ds_read_b128 v[176:179], v146 offset:3072
	s_cmp_eq_u32 s69, 60
	s_cselect_b32 s48, s41, s53
	s_cselect_b32 s49, s19, s58
	s_cselect_b32 s46, s52, s59
	s_cselect_b32 s47, s17, s68
	s_add_u32 s44, s48, 0x80
	s_addc_u32 s45, s49, 0
	ds_read_b128 v[180:183], v147
	ds_read_b128 v[184:187], v147 offset:1024
	ds_read_b128 v[188:191], v147 offset:2048
	ds_read_b128 v[192:195], v147 offset:3072
	ds_read_b128 v[196:199], v147 offset:4096
	ds_read_b128 v[200:203], v147 offset:5120
	ds_read_b128 v[204:207], v147 offset:6144
	ds_read_b128 v[208:211], v147 offset:7168
	s_mov_b32 m0, s67
	s_nop 0
	global_load_lds_dwordx4 v1, s[42:43]
	s_nop 0
	s_mov_b32 m0, s74
	s_nop 0
	global_load_lds_dwordx4 v141, s[42:43]
	s_waitcnt vmcnt(8)
	s_waitcnt lgkmcnt(0)
	s_barrier
	s_setprio 1
	s_waitcnt lgkmcnt(7)
	v_mfma_f32_16x16x32_bf16 v[126:129], v[134:137], v[180:183], v[126:129]
	v_mfma_f32_16x16x32_bf16 v[122:125], v[156:159], v[180:183], v[122:125]
	s_waitcnt lgkmcnt(5)
	v_mfma_f32_16x16x32_bf16 v[110:113], v[134:137], v[188:191], v[110:113]
	v_mfma_f32_16x16x32_bf16 v[106:109], v[156:159], v[188:191], v[106:109]
	s_waitcnt lgkmcnt(3)
	v_mfma_f32_16x16x32_bf16 v[94:97], v[134:137], v[196:199], v[94:97]
	v_mfma_f32_16x16x32_bf16 v[90:93], v[156:159], v[196:199], v[90:93]
	s_waitcnt lgkmcnt(1)
	v_mfma_f32_16x16x32_bf16 v[78:81], v[134:137], v[204:207], v[78:81]
	v_mfma_f32_16x16x32_bf16 v[74:77], v[156:159], v[204:207], v[74:77]
	v_mfma_f32_16x16x32_bf16 v[126:129], v[152:155], v[184:187], v[126:129]
	v_mfma_f32_16x16x32_bf16 v[122:125], v[160:163], v[184:187], v[122:125]
	v_mfma_f32_16x16x32_bf16 v[110:113], v[152:155], v[192:195], v[110:113]
	v_mfma_f32_16x16x32_bf16 v[106:109], v[160:163], v[192:195], v[106:109]
	v_mfma_f32_16x16x32_bf16 v[94:97], v[152:155], v[200:203], v[94:97]
	v_mfma_f32_16x16x32_bf16 v[90:93], v[160:163], v[200:203], v[90:93]
	s_waitcnt lgkmcnt(0)
	v_mfma_f32_16x16x32_bf16 v[78:81], v[152:155], v[208:211], v[78:81]
	v_mfma_f32_16x16x32_bf16 v[74:77], v[160:163], v[208:211], v[74:77]
	s_setprio 0
	s_setprio 1
	v_mfma_f32_16x16x32_bf16 v[118:121], v[164:167], v[180:183], v[118:121]
	v_mfma_f32_16x16x32_bf16 v[114:117], v[172:175], v[180:183], v[114:117]
	v_mfma_f32_16x16x32_bf16 v[102:105], v[164:167], v[188:191], v[102:105]
	v_mfma_f32_16x16x32_bf16 v[98:101], v[172:175], v[188:191], v[98:101]
	v_mfma_f32_16x16x32_bf16 v[86:89], v[164:167], v[196:199], v[86:89]
	v_mfma_f32_16x16x32_bf16 v[82:85], v[172:175], v[196:199], v[82:85]
	v_mfma_f32_16x16x32_bf16 v[70:73], v[164:167], v[204:207], v[70:73]
	v_mfma_f32_16x16x32_bf16 v[66:69], v[172:175], v[204:207], v[66:69]
	v_mfma_f32_16x16x32_bf16 v[118:121], v[168:171], v[184:187], v[118:121]
	v_mfma_f32_16x16x32_bf16 v[114:117], v[176:179], v[184:187], v[114:117]
	v_mfma_f32_16x16x32_bf16 v[102:105], v[168:171], v[192:195], v[102:105]
	v_mfma_f32_16x16x32_bf16 v[98:101], v[176:179], v[192:195], v[98:101]
	v_mfma_f32_16x16x32_bf16 v[86:89], v[168:171], v[200:203], v[86:89]
	v_mfma_f32_16x16x32_bf16 v[82:85], v[176:179], v[200:203], v[82:85]
	v_mfma_f32_16x16x32_bf16 v[70:73], v[168:171], v[208:211], v[70:73]
	s_barrier
	v_mfma_f32_16x16x32_bf16 v[66:69], v[176:179], v[208:211], v[66:69]
	s_setprio 0
	ds_read_b128 v[180:183], v147 offset:16384
	ds_read_b128 v[184:187], v147 offset:17408
	ds_read_b128 v[188:191], v147 offset:18432
	ds_read_b128 v[192:195], v147 offset:19456
	ds_read_b128 v[196:199], v147 offset:20480
	ds_read_b128 v[200:203], v147 offset:21504
	ds_read_b128 v[204:207], v147 offset:22528
	ds_read_b128 v[252:255], v147 offset:23552
	s_mov_b32 m0, s35
	s_nop 0
	global_load_lds_dwordx4 v140, s[46:47]
	s_add_u32 s70, s46, 0x100000
	s_mov_b32 m0, s50
	s_nop 0
	global_load_lds_dwordx4 v142, s[46:47]
	s_addc_u32 s71, s47, 0
	s_mov_b32 m0, s51
	s_nop 0
	global_load_lds_dwordx4 v140, s[70:71]
	s_nop 0
	s_mov_b32 m0, s54
	s_nop 0
	global_load_lds_dwordx4 v142, s[70:71]
	s_nop 0
	s_mov_b32 m0, s3
	s_nop 0
	global_load_lds_dwordx4 v1, s[48:49]
	s_nop 0
	s_mov_b32 m0, s55
	s_nop 0
	global_load_lds_dwordx4 v141, s[48:49]
	s_waitcnt vmcnt(8)
	s_waitcnt lgkmcnt(0)
	s_barrier
	s_setprio 1
	s_waitcnt lgkmcnt(7)
	v_mfma_f32_16x16x32_bf16 v[62:65], v[134:137], v[180:183], v[62:65]
	v_mfma_f32_16x16x32_bf16 v[58:61], v[156:159], v[180:183], v[58:61]
	s_waitcnt lgkmcnt(5)
	v_mfma_f32_16x16x32_bf16 v[46:49], v[134:137], v[188:191], v[46:49]
	v_mfma_f32_16x16x32_bf16 v[42:45], v[156:159], v[188:191], v[42:45]
	s_waitcnt lgkmcnt(3)
	v_mfma_f32_16x16x32_bf16 v[30:33], v[134:137], v[196:199], v[30:33]
	v_mfma_f32_16x16x32_bf16 v[26:29], v[156:159], v[196:199], v[26:29]
	s_waitcnt lgkmcnt(1)
	v_mfma_f32_16x16x32_bf16 v[14:17], v[134:137], v[204:207], v[14:17]
	v_mfma_f32_16x16x32_bf16 v[10:13], v[156:159], v[204:207], v[10:13]
	v_mfma_f32_16x16x32_bf16 v[62:65], v[152:155], v[184:187], v[62:65]
	v_mfma_f32_16x16x32_bf16 v[58:61], v[160:163], v[184:187], v[58:61]
	v_mfma_f32_16x16x32_bf16 v[46:49], v[152:155], v[192:195], v[46:49]
	v_mfma_f32_16x16x32_bf16 v[42:45], v[160:163], v[192:195], v[42:45]
	v_mfma_f32_16x16x32_bf16 v[30:33], v[152:155], v[200:203], v[30:33]
	v_mfma_f32_16x16x32_bf16 v[26:29], v[160:163], v[200:203], v[26:29]
	s_waitcnt lgkmcnt(0)
	v_mfma_f32_16x16x32_bf16 v[14:17], v[152:155], v[252:255], v[14:17]
	v_mfma_f32_16x16x32_bf16 v[10:13], v[160:163], v[252:255], v[10:13]
	s_setprio 0
	s_setprio 1
	v_mfma_f32_16x16x32_bf16 v[54:57], v[164:167], v[180:183], v[54:57]
	v_mfma_f32_16x16x32_bf16 v[50:53], v[172:175], v[180:183], v[50:53]
	v_mfma_f32_16x16x32_bf16 v[38:41], v[164:167], v[188:191], v[38:41]
	v_mfma_f32_16x16x32_bf16 v[34:37], v[172:175], v[188:191], v[34:37]
	v_mfma_f32_16x16x32_bf16 v[22:25], v[164:167], v[196:199], v[22:25]
	v_mfma_f32_16x16x32_bf16 v[18:21], v[172:175], v[196:199], v[18:21]
	v_mfma_f32_16x16x32_bf16 v[6:9], v[164:167], v[204:207], v[6:9]
	v_mfma_f32_16x16x32_bf16 v[2:5], v[172:175], v[204:207], v[2:5]
	v_mfma_f32_16x16x32_bf16 v[54:57], v[168:171], v[184:187], v[54:57]
	v_mfma_f32_16x16x32_bf16 v[50:53], v[176:179], v[184:187], v[50:53]
	v_mfma_f32_16x16x32_bf16 v[38:41], v[168:171], v[192:195], v[38:41]
	v_mfma_f32_16x16x32_bf16 v[34:37], v[176:179], v[192:195], v[34:37]
	v_mfma_f32_16x16x32_bf16 v[22:25], v[168:171], v[200:203], v[22:25]
	v_mfma_f32_16x16x32_bf16 v[18:21], v[176:179], v[200:203], v[18:21]
	v_mfma_f32_16x16x32_bf16 v[6:9], v[168:171], v[252:255], v[6:9]
	s_barrier
; #define PG8_STAGE(bufoff, gbase, voff) do { _Pragma("unroll") for (int _i = 0; _i < 2; ++_i) \
;         asm volatile("s_mov_b32 m0, %2\n\ts_nop 0\n\tglobal_load_lds_dwordx4 %0, %1" :: "v"((voff)[_i]), "s"((const char*)(gbase)), "s"(ldsbase + (unsigned)(bufoff) + ldsw + (unsigned)_i * 8192u) : "memory", "m0"); } while (0)
; #define PG8_LDA(dst, b, h) do { _Pragma("unroll") for (int m = 0; m < 4; ++m) _Pragma("unroll") for (int k = 0; k < 2; ++k) dst[m][k] = *(const PG8_LAS bf16x8*)(lds + PG8_SA(b, h) + aoff + m * 2048 + k * 1024); } while (0)
; #define PG8_LDB(dst, b, h) do { _Pragma("unroll") for (int n = 0; n < 2; ++n) _Pragma("unroll") for (int k = 0; k < 2; ++k) dst[n][k] = *(const PG8_LAS bf16x8*)(lds + PG8_SB(b, h) + boff + n * 2048 + k * 1024); } while (0)
; #define PG8_MMA(ai, bj, At, Bt) do { __builtin_amdgcn_s_setprio(1); _Pragma("unroll") for (int m = 0; m < 4; ++m) _Pragma("unroll") for (int n = 0; n < 2; ++n) _Pragma("unroll") for (int k = 0; k < 2; ++k) \
;         acc[ai][bj][m][n] = __builtin_amdgcn_mfma_f32_16x16x32_bf16(Bt[n][k], At[m][k], acc[ai][bj][m][n], 0, 0, 0); __builtin_amdgcn_s_setprio(0); } while (0)
; #define PG8_WAIT_V(n) asm volatile("s_waitcnt vmcnt(" #n ")" ::: "memory")
; #define PG8_WAIT_L(n) asm volatile("s_waitcnt lgkmcnt(" #n ")" ::: "memory")
; #define PG8_BAR __builtin_amdgcn_s_barrier()
; #define PG8_SCHED __builtin_amdgcn_sched_barrier(0)
; template <class Epi, class Sched, bool ALIGN_EPI = false, bool SP2 = false>
; __device__ __forceinline__ void gemm_phase(PG8_LAS unsigned char* lds, const Gemm g, const Sched& S, const Epi& E) {
;     ...
;         for (int t = 0; t < nt; t += 2) {
;     ...
;             PG8_LDB(B0, 1, 0); PG8_LDB(B1, 1, 1); PG8_SCHED; PG8_LDA(At, 1, 0); PG8_STAGE(PG8_SA(0, 1), a2 + hstep, voffA);
;             PG8_WAIT_V(8); PG8_WAIT_L(0); PG8_BAR; PG8_MMA(0, 0, At, B0); PG8_MMA(0, 1, At, B1); PG8_BAR; PG8_SCHED;
;             PG8_LDA(At, 1, 1); PG8_STAGE(PG8_SB(1, 0), b3, voffB); PG8_STAGE(PG8_SB(1, 1), b3 + hstep, voffB); PG8_STAGE(PG8_SA(1, 0), a3, voffA);
;             PG8_WAIT_V(8); PG8_WAIT_L(0); PG8_BAR; PG8_MMA(1, 0, At, B0); PG8_MMA(1, 1, At, B1); PG8_BAR; PG8_SCHED;
;     ...
;         if constexpr (ALIGN_EPI) { if (wr == 0) PG8_BAR; }
	v_mfma_f32_16x16x32_bf16 v[2:5], v[176:179], v[252:255], v[2:5]
	s_setprio 0
	ds_read_b128 v[134:137], v148
	ds_read_b128 v[152:155], v148 offset:1024
	ds_read_b128 v[156:159], v148 offset:2048
	ds_read_b128 v[160:163], v148 offset:3072
	ds_read_b128 v[164:167], v149
	ds_read_b128 v[168:171], v149 offset:1024
	ds_read_b128 v[172:175], v149 offset:2048
	ds_read_b128 v[248:251], v149 offset:3072
	ds_read_b128 v[180:183], v147 offset:32768
	ds_read_b128 v[184:187], v147 offset:33792
	ds_read_b128 v[188:191], v147 offset:34816
	ds_read_b128 v[192:195], v147 offset:35840
	ds_read_b128 v[196:199], v147 offset:36864
	ds_read_b128 v[200:203], v147 offset:37888
	ds_read_b128 v[204:207], v147 offset:38912
	ds_read_b128 v[208:211], v147 offset:39936
	s_add_u32 s48, s48, 0x100000
	s_addc_u32 s49, s49, 0
	s_mov_b32 m0, s56
	s_nop 0
	global_load_lds_dwordx4 v1, s[48:49]
	s_nop 0
	s_mov_b32 m0, s57
	s_nop 0
	global_load_lds_dwordx4 v141, s[48:49]
	s_waitcnt vmcnt(8)
	s_waitcnt lgkmcnt(0)
	s_barrier
	s_setprio 1
	s_waitcnt lgkmcnt(7)
	v_mfma_f32_16x16x32_bf16 v[126:129], v[134:137], v[180:183], v[126:129]
	v_mfma_f32_16x16x32_bf16 v[122:125], v[156:159], v[180:183], v[122:125]
	s_waitcnt lgkmcnt(5)
	v_mfma_f32_16x16x32_bf16 v[110:113], v[134:137], v[188:191], v[110:113]
	v_mfma_f32_16x16x32_bf16 v[106:109], v[156:159], v[188:191], v[106:109]
	s_waitcnt lgkmcnt(3)
	v_mfma_f32_16x16x32_bf16 v[94:97], v[134:137], v[196:199], v[94:97]
	v_mfma_f32_16x16x32_bf16 v[90:93], v[156:159], v[196:199], v[90:93]
	s_waitcnt lgkmcnt(1)
	v_mfma_f32_16x16x32_bf16 v[78:81], v[134:137], v[204:207], v[78:81]
	v_mfma_f32_16x16x32_bf16 v[74:77], v[156:159], v[204:207], v[74:77]
	v_mfma_f32_16x16x32_bf16 v[126:129], v[152:155], v[184:187], v[126:129]
	v_mfma_f32_16x16x32_bf16 v[122:125], v[160:163], v[184:187], v[122:125]
	v_mfma_f32_16x16x32_bf16 v[110:113], v[152:155], v[192:195], v[110:113]
	v_mfma_f32_16x16x32_bf16 v[106:109], v[160:163], v[192:195], v[106:109]
	v_mfma_f32_16x16x32_bf16 v[94:97], v[152:155], v[200:203], v[94:97]
	v_mfma_f32_16x16x32_bf16 v[90:93], v[160:163], v[200:203], v[90:93]
	s_waitcnt lgkmcnt(0)
	v_mfma_f32_16x16x32_bf16 v[78:81], v[152:155], v[208:211], v[78:81]
	v_mfma_f32_16x16x32_bf16 v[74:77], v[160:163], v[208:211], v[74:77]
	s_setprio 0
	s_setprio 1
	v_mfma_f32_16x16x32_bf16 v[118:121], v[164:167], v[180:183], v[118:121]
	v_mfma_f32_16x16x32_bf16 v[114:117], v[172:175], v[180:183], v[114:117]
	v_mfma_f32_16x16x32_bf16 v[102:105], v[164:167], v[188:191], v[102:105]
	v_mfma_f32_16x16x32_bf16 v[98:101], v[172:175], v[188:191], v[98:101]
	v_mfma_f32_16x16x32_bf16 v[86:89], v[164:167], v[196:199], v[86:89]
	v_mfma_f32_16x16x32_bf16 v[82:85], v[172:175], v[196:199], v[82:85]
	v_mfma_f32_16x16x32_bf16 v[70:73], v[164:167], v[204:207], v[70:73]
	v_mfma_f32_16x16x32_bf16 v[66:69], v[172:175], v[204:207], v[66:69]
	v_mfma_f32_16x16x32_bf16 v[118:121], v[168:171], v[184:187], v[118:121]
	v_mfma_f32_16x16x32_bf16 v[114:117], v[248:251], v[184:187], v[114:117]
	v_mfma_f32_16x16x32_bf16 v[102:105], v[168:171], v[192:195], v[102:105]
	v_mfma_f32_16x16x32_bf16 v[98:101], v[248:251], v[192:195], v[98:101]
	v_mfma_f32_16x16x32_bf16 v[86:89], v[168:171], v[200:203], v[86:89]
	v_mfma_f32_16x16x32_bf16 v[82:85], v[248:251], v[200:203], v[82:85]
	v_mfma_f32_16x16x32_bf16 v[70:73], v[168:171], v[208:211], v[70:73]
	s_barrier
	v_mfma_f32_16x16x32_bf16 v[66:69], v[248:251], v[208:211], v[66:69]
	s_setprio 0
	ds_read_b128 v[180:183], v147 offset:49152
	ds_read_b128 v[184:187], v147 offset:50176
	ds_read_b128 v[188:191], v147 offset:51200
	ds_read_b128 v[192:195], v147 offset:52224
	ds_read_b128 v[196:199], v147 offset:53248
	ds_read_b128 v[200:203], v147 offset:54272
	ds_read_b128 v[204:207], v147 offset:55296
	ds_read_b128 v[252:255], v147 offset:56320
	s_add_u32 s48, s46, 0x80
	s_addc_u32 s49, s47, 0
	s_mov_b32 m0, s61
	s_nop 0
	global_load_lds_dwordx4 v140, s[48:49]
	s_add_u32 s46, s46, 0x100080
	s_mov_b32 m0, s62
	s_nop 0
	global_load_lds_dwordx4 v142, s[48:49]
	s_addc_u32 s47, s47, 0
	s_mov_b32 m0, s65
	s_nop 0
	global_load_lds_dwordx4 v140, s[46:47]
	s_nop 0
	s_mov_b32 m0, s66
	s_nop 0
	global_load_lds_dwordx4 v142, s[46:47]
	s_nop 0
	s_mov_b32 m0, s63
	s_nop 0
	global_load_lds_dwordx4 v1, s[44:45]
	s_nop 0
	s_mov_b32 m0, s64
	s_nop 0
	global_load_lds_dwordx4 v141, s[44:45]
	s_waitcnt vmcnt(8)
	s_waitcnt lgkmcnt(0)
	s_barrier
	s_setprio 1
	s_waitcnt lgkmcnt(7)
	v_mfma_f32_16x16x32_bf16 v[62:65], v[134:137], v[180:183], v[62:65]
	v_mfma_f32_16x16x32_bf16 v[58:61], v[156:159], v[180:183], v[58:61]
	s_waitcnt lgkmcnt(5)
	v_mfma_f32_16x16x32_bf16 v[46:49], v[134:137], v[188:191], v[46:49]
	v_mfma_f32_16x16x32_bf16 v[42:45], v[156:159], v[188:191], v[42:45]
	s_waitcnt lgkmcnt(3)
	v_mfma_f32_16x16x32_bf16 v[30:33], v[134:137], v[196:199], v[30:33]
	v_mfma_f32_16x16x32_bf16 v[26:29], v[156:159], v[196:199], v[26:29]
	s_waitcnt lgkmcnt(1)
	v_mfma_f32_16x16x32_bf16 v[14:17], v[134:137], v[204:207], v[14:17]
	v_mfma_f32_16x16x32_bf16 v[10:13], v[156:159], v[204:207], v[10:13]
	v_mfma_f32_16x16x32_bf16 v[62:65], v[152:155], v[184:187], v[62:65]
	v_mfma_f32_16x16x32_bf16 v[58:61], v[160:163], v[184:187], v[58:61]
	v_mfma_f32_16x16x32_bf16 v[46:49], v[152:155], v[192:195], v[46:49]
	v_mfma_f32_16x16x32_bf16 v[42:45], v[160:163], v[192:195], v[42:45]
	v_mfma_f32_16x16x32_bf16 v[30:33], v[152:155], v[200:203], v[30:33]
	v_mfma_f32_16x16x32_bf16 v[26:29], v[160:163], v[200:203], v[26:29]
	s_waitcnt lgkmcnt(0)
	v_mfma_f32_16x16x32_bf16 v[14:17], v[152:155], v[252:255], v[14:17]
	v_mfma_f32_16x16x32_bf16 v[10:13], v[160:163], v[252:255], v[10:13]
	s_setprio 0
	s_setprio 1
	v_mfma_f32_16x16x32_bf16 v[54:57], v[164:167], v[180:183], v[54:57]
	v_mfma_f32_16x16x32_bf16 v[50:53], v[172:175], v[180:183], v[50:53]
	v_mfma_f32_16x16x32_bf16 v[38:41], v[164:167], v[188:191], v[38:41]
	v_mfma_f32_16x16x32_bf16 v[34:37], v[172:175], v[188:191], v[34:37]
	v_mfma_f32_16x16x32_bf16 v[22:25], v[164:167], v[196:199], v[22:25]
	v_mfma_f32_16x16x32_bf16 v[18:21], v[172:175], v[196:199], v[18:21]
	v_mfma_f32_16x16x32_bf16 v[6:9], v[164:167], v[204:207], v[6:9]
	v_mfma_f32_16x16x32_bf16 v[2:5], v[172:175], v[204:207], v[2:5]
	v_mfma_f32_16x16x32_bf16 v[54:57], v[168:171], v[184:187], v[54:57]
	v_mfma_f32_16x16x32_bf16 v[50:53], v[248:251], v[184:187], v[50:53]
	v_mfma_f32_16x16x32_bf16 v[38:41], v[168:171], v[192:195], v[38:41]
	v_mfma_f32_16x16x32_bf16 v[34:37], v[248:251], v[192:195], v[34:37]
	v_mfma_f32_16x16x32_bf16 v[22:25], v[168:171], v[200:203], v[22:25]
	v_mfma_f32_16x16x32_bf16 v[18:21], v[248:251], v[200:203], v[18:21]
	v_mfma_f32_16x16x32_bf16 v[6:9], v[168:171], v[252:255], v[6:9]
	s_barrier
	v_mfma_f32_16x16x32_bf16 v[2:5], v[248:251], v[252:255], v[2:5]
	s_setprio 0
	s_add_i32 s69, s69, 2
	s_add_u32 s53, s53, 0x100
	s_addc_u32 s58, s58, 0
	s_add_u32 s59, s59, 0x100
	s_addc_u32 s68, s68, 0
	s_add_u32 s42, s42, 0x100
	s_addc_u32 s43, s43, 0
	s_cmp_gt_u32 s69, 61
	s_cbranch_scc0 .LBB0_698
	s_and_b64 vcc, exec, s[14:15]
	s_cbranch_vccz .LBB0_701
	s_barrier

; #define PG8_STAGE(bufoff, gbase, voff) do { _Pragma("unroll") for (int _i = 0; _i < 2; ++_i) \
;         asm volatile("s_mov_b32 m0, %2\n\ts_nop 0\n\tglobal_load_lds_dwordx4 %0, %1" :: "v"((voff)[_i]), "s"((const char*)(gbase)), "s"(ldsbase + (unsigned)(bufoff) + ldsw + (unsigned)_i * 8192u) : "memory", "m0"); } while (0)
; #define PG8_LDA(dst, b, h) do { _Pragma("unroll") for (int m = 0; m < 4; ++m) _Pragma("unroll") for (int k = 0; k < 2; ++k) dst[m][k] = *(const PG8_LAS bf16x8*)(lds + PG8_SA(b, h) + aoff + m * 2048 + k * 1024); } while (0)
; #define PG8_WAIT_V(n) asm volatile("s_waitcnt vmcnt(" #n ")" ::: "memory")
; #define PG8_WAIT_L(n) asm volatile("s_waitcnt lgkmcnt(" #n ")" ::: "memory")
; template <class Epi, class Sched, bool ALIGN_EPI = false, bool SP2 = false>
; __device__ __forceinline__ void gemm_phase(PG8_LAS unsigned char* lds, const Gemm g, const Sched& S, const Epi& E) {
;     ...
;             const char* a1 = cA + (size_t)(t + 1) * kstep;
;             const char* a2 = last ? nA : cA + (size_t)(t + 2) * kstep; const char* b2 = last ? nB : cB + (size_t)(t + 2) * kstep;
;             const char* a3 = a2 + kstep; const char* b3 = b2 + kstep;
;             if (last && has_next) S.a_ready(nxt);
;             if constexpr (epi_has_mid<Epi>::value) { if (t == Epi::MID_T) E.mid(acc, cur, wr, wc, fr, fq); }
;             if constexpr (SP2) {
;             PG8_LDB(B0, 0, 0); PG8_LDB(B1, 0, 1); PG8_SCHED; PG8_LDA(At, 0, 0); PG8_STAGE(PG8_SA(1, 1), a1 + hstep, voffA);
;             PG8_WAIT_V(8); PG8_WAIT_L(0); PG8_BAR; PG8_MMA(0, 0, At, B0); PG8_MMA(0, 1, At, B1); PG8_BAR; PG8_SCHED;
;             PG8_LDA(At, 0, 1); PG8_STAGE(PG8_SB(0, 0), b2, voffB); PG8_STAGE(PG8_SB(0, 1), b2 + hstep, voffB); PG8_STAGE(PG8_SA(0, 0), a2, voffA);
;             PG8_WAIT_V(8); PG8_WAIT_L(0); PG8_BAR; PG8_MMA(1, 0, At, B0); PG8_MMA(1, 1, At, B1); PG8_BAR; PG8_SCHED;
;             PG8_LDB(B0, 1, 0); PG8_LDB(B1, 1, 1); PG8_SCHED; PG8_LDA(At, 1, 0); PG8_STAGE(PG8_SA(0, 1), a2 + hstep, voffA);
;             PG8_WAIT_V(8); PG8_WAIT_L(0); PG8_BAR; PG8_MMA(0, 0, At, B0); PG8_MMA(0, 1, At, B1); PG8_BAR; PG8_SCHED;
;             PG8_LDA(At, 1, 1); PG8_STAGE(PG8_SB(1, 0), b3, voffB); PG8_STAGE(PG8_SB(1, 1), b3 + hstep, voffB); PG8_STAGE(PG8_SA(1, 0), a3, voffA);
;             PG8_WAIT_V(8); PG8_WAIT_L(0); PG8_BAR; PG8_MMA(1, 0, At, B0); PG8_MMA(1, 1, At, B1); PG8_BAR; PG8_SCHED;
.LBB0_789:
	v_add_u32_e32 v164, 0x10000, v149
	v_add_u32_e32 v180, 0x14000, v149
	s_add_u32 s8, s40, 0x100
	s_waitcnt lgkmcnt(0)
	ds_read_b128 v[152:155], v164
	ds_read_b128 v[156:159], v164 offset:1024
	ds_read_b128 v[160:163], v164 offset:2048
	ds_read_b128 v[164:167], v164 offset:3072
	ds_read_b128 v[168:171], v180
	ds_read_b128 v[172:175], v180 offset:1024
	ds_read_b128 v[176:179], v180 offset:2048
	ds_read_b128 v[180:183], v180 offset:3072
	s_addc_u32 s9, s41, 0
	s_and_b64 s[38:39], s[38:39], exec
	s_cselect_b32 s46, s59, s8
	s_cselect_b32 s47, s17, s9
	s_cselect_b32 s39, s15, s75
	s_cselect_b32 s38, s71, s74
	s_add_u32 s42, s46, 0x80
	s_addc_u32 s43, s47, 0
	s_add_u32 s44, s38, 0x80
	s_addc_u32 s45, s39, 0
	ds_read_b128 v[184:187], v150
	ds_read_b128 v[188:191], v150 offset:1024
	ds_read_b128 v[192:195], v150 offset:2048
	ds_read_b128 v[196:199], v150 offset:3072
	ds_read_b128 v[200:203], v150 offset:4096
	ds_read_b128 v[204:207], v150 offset:5120
	ds_read_b128 v[208:211], v150 offset:6144
	ds_read_b128 v[212:215], v150 offset:7168
	s_add_u32 s40, s40, 0x100080
	s_addc_u32 s41, s41, 0
	s_mov_b32 m0, s64
	s_nop 0
	global_load_lds_dwordx4 v139, s[40:41]
	s_nop 0
	s_mov_b32 m0, s65
	s_nop 0
	global_load_lds_dwordx4 v141, s[40:41]
	s_waitcnt vmcnt(8)
	s_waitcnt lgkmcnt(0)
	s_barrier
	s_setprio 1
	s_waitcnt lgkmcnt(7)
	v_mfma_f32_16x16x32_bf16 v[126:129], v[152:155], v[184:187], v[126:129]
	v_mfma_f32_16x16x32_bf16 v[122:125], v[160:163], v[184:187], v[122:125]
	s_waitcnt lgkmcnt(5)
	v_mfma_f32_16x16x32_bf16 v[110:113], v[152:155], v[192:195], v[110:113]
	v_mfma_f32_16x16x32_bf16 v[106:109], v[160:163], v[192:195], v[106:109]
	s_waitcnt lgkmcnt(3)
	v_mfma_f32_16x16x32_bf16 v[94:97], v[152:155], v[200:203], v[94:97]
	v_mfma_f32_16x16x32_bf16 v[90:93], v[160:163], v[200:203], v[90:93]
	s_waitcnt lgkmcnt(1)
	v_mfma_f32_16x16x32_bf16 v[78:81], v[152:155], v[208:211], v[78:81]
	v_mfma_f32_16x16x32_bf16 v[74:77], v[160:163], v[208:211], v[74:77]
	v_mfma_f32_16x16x32_bf16 v[126:129], v[156:159], v[188:191], v[126:129]
	v_mfma_f32_16x16x32_bf16 v[122:125], v[164:167], v[188:191], v[122:125]
	v_mfma_f32_16x16x32_bf16 v[110:113], v[156:159], v[196:199], v[110:113]
	v_mfma_f32_16x16x32_bf16 v[106:109], v[164:167], v[196:199], v[106:109]
	v_mfma_f32_16x16x32_bf16 v[94:97], v[156:159], v[204:207], v[94:97]
	v_mfma_f32_16x16x32_bf16 v[90:93], v[164:167], v[204:207], v[90:93]
	s_waitcnt lgkmcnt(0)
	v_mfma_f32_16x16x32_bf16 v[78:81], v[156:159], v[212:215], v[78:81]
	v_mfma_f32_16x16x32_bf16 v[74:77], v[164:167], v[212:215], v[74:77]
	s_setprio 0
	s_setprio 1
	v_mfma_f32_16x16x32_bf16 v[118:121], v[168:171], v[184:187], v[118:121]
	v_mfma_f32_16x16x32_bf16 v[114:117], v[176:179], v[184:187], v[114:117]
	v_mfma_f32_16x16x32_bf16 v[102:105], v[168:171], v[192:195], v[102:105]
	v_mfma_f32_16x16x32_bf16 v[98:101], v[176:179], v[192:195], v[98:101]
	v_mfma_f32_16x16x32_bf16 v[86:89], v[168:171], v[200:203], v[86:89]
	v_mfma_f32_16x16x32_bf16 v[82:85], v[176:179], v[200:203], v[82:85]
	v_mfma_f32_16x16x32_bf16 v[70:73], v[168:171], v[208:211], v[70:73]
	v_mfma_f32_16x16x32_bf16 v[66:69], v[176:179], v[208:211], v[66:69]
	v_mfma_f32_16x16x32_bf16 v[118:121], v[172:175], v[188:191], v[118:121]
	v_mfma_f32_16x16x32_bf16 v[114:117], v[180:183], v[188:191], v[114:117]
	v_mfma_f32_16x16x32_bf16 v[102:105], v[172:175], v[196:199], v[102:105]
	v_mfma_f32_16x16x32_bf16 v[98:101], v[180:183], v[196:199], v[98:101]
	v_mfma_f32_16x16x32_bf16 v[86:89], v[172:175], v[204:207], v[86:89]
	v_mfma_f32_16x16x32_bf16 v[82:85], v[180:183], v[204:207], v[82:85]
	v_mfma_f32_16x16x32_bf16 v[70:73], v[172:175], v[212:215], v[70:73]
	s_barrier
	v_mfma_f32_16x16x32_bf16 v[66:69], v[180:183], v[212:215], v[66:69]
	s_setprio 0
	ds_read_b128 v[184:187], v150 offset:16384
	ds_read_b128 v[188:191], v150 offset:17408
	ds_read_b128 v[192:195], v150 offset:18432
	ds_read_b128 v[196:199], v150 offset:19456
	ds_read_b128 v[200:203], v150 offset:20480
	ds_read_b128 v[204:207], v150 offset:21504
	ds_read_b128 v[208:211], v150 offset:22528
	ds_read_b128 v[252:255], v150 offset:23552
	s_mov_b32 m0, s49
	s_nop 0
	global_load_lds_dwordx4 v140, s[38:39]
	s_add_u32 s40, s38, 0x100000
	s_mov_b32 m0, s50
	s_nop 0
	global_load_lds_dwordx4 v142, s[38:39]
	s_addc_u32 s41, s39, 0
	s_mov_b32 m0, s51
	s_nop 0
	global_load_lds_dwordx4 v140, s[40:41]
	s_nop 0
	s_mov_b32 m0, s52
	s_nop 0
	global_load_lds_dwordx4 v142, s[40:41]
	s_nop 0
	s_mov_b32 m0, s37
	s_nop 0
	global_load_lds_dwordx4 v139, s[46:47]
	s_nop 0
	s_mov_b32 m0, s53
	s_nop 0
	global_load_lds_dwordx4 v141, s[46:47]
	s_waitcnt vmcnt(8)
	s_waitcnt lgkmcnt(0)
	s_barrier
; #define PG8_STAGE(bufoff, gbase, voff) do { _Pragma("unroll") for (int _i = 0; _i < 2; ++_i) \
;         asm volatile("s_mov_b32 m0, %2\n\ts_nop 0\n\tglobal_load_lds_dwordx4 %0, %1" :: "v"((voff)[_i]), "s"((const char*)(gbase)), "s"(ldsbase + (unsigned)(bufoff) + ldsw + (unsigned)_i * 8192u) : "memory", "m0"); } while (0)
; #define PG8_LDA(dst, b, h) do { _Pragma("unroll") for (int m = 0; m < 4; ++m) _Pragma("unroll") for (int k = 0; k < 2; ++k) dst[m][k] = *(const PG8_LAS bf16x8*)(lds + PG8_SA(b, h) + aoff + m * 2048 + k * 1024); } while (0)
; #define PG8_LDB(dst, b, h) do { _Pragma("unroll") for (int n = 0; n < 2; ++n) _Pragma("unroll") for (int k = 0; k < 2; ++k) dst[n][k] = *(const PG8_LAS bf16x8*)(lds + PG8_SB(b, h) + boff + n * 2048 + k * 1024); } while (0)
; #define PG8_MMA(ai, bj, At, Bt) do { __builtin_amdgcn_s_setprio(1); _Pragma("unroll") for (int m = 0; m < 4; ++m) _Pragma("unroll") for (int n = 0; n < 2; ++n) _Pragma("unroll") for (int k = 0; k < 2; ++k) \
;         acc[ai][bj][m][n] = __builtin_amdgcn_mfma_f32_16x16x32_bf16(Bt[n][k], At[m][k], acc[ai][bj][m][n], 0, 0, 0); __builtin_amdgcn_s_setprio(0); } while (0)
; #define PG8_WAIT_V(n) asm volatile("s_waitcnt vmcnt(" #n ")" ::: "memory")
; #define PG8_BAR __builtin_amdgcn_s_barrier()
; template <class Epi, class Sched, bool ALIGN_EPI = false, bool SP2 = false>
; __device__ __forceinline__ void gemm_phase(PG8_LAS unsigned char* lds, const Gemm g, const Sched& S, const Epi& E) {
;     ...
;             PG8_WAIT_V(8); PG8_WAIT_L(0); PG8_BAR; PG8_MMA(0, 0, At, B0); PG8_MMA(0, 1, At, B1); PG8_BAR; PG8_SCHED;
;             PG8_LDA(At, 0, 1); PG8_STAGE(PG8_SB(0, 0), b2, voffB); PG8_STAGE(PG8_SB(0, 1), b2 + hstep, voffB); PG8_STAGE(PG8_SA(0, 0), a2, voffA);
;             PG8_WAIT_V(8); PG8_WAIT_L(0); PG8_BAR; PG8_MMA(1, 0, At, B0); PG8_MMA(1, 1, At, B1); PG8_BAR; PG8_SCHED;
;             PG8_LDB(B0, 1, 0); PG8_LDB(B1, 1, 1); PG8_SCHED; PG8_LDA(At, 1, 0); PG8_STAGE(PG8_SA(0, 1), a2 + hstep, voffA);
;             PG8_WAIT_V(8); PG8_WAIT_L(0); PG8_BAR; PG8_MMA(0, 0, At, B0); PG8_MMA(0, 1, At, B1); PG8_BAR; PG8_SCHED;
;             PG8_LDA(At, 1, 1); PG8_STAGE(PG8_SB(1, 0), b3, voffB); PG8_STAGE(PG8_SB(1, 1), b3 + hstep, voffB); PG8_STAGE(PG8_SA(1, 0), a3, voffA);
;             PG8_WAIT_V(8); PG8_WAIT_L(0); PG8_BAR; PG8_MMA(1, 0, At, B0); PG8_MMA(1, 1, At, B1); PG8_BAR; PG8_SCHED;
	s_setprio 1
	s_waitcnt lgkmcnt(7)
	v_mfma_f32_16x16x32_bf16 v[62:65], v[152:155], v[184:187], v[62:65]
	v_mfma_f32_16x16x32_bf16 v[58:61], v[160:163], v[184:187], v[58:61]
	s_waitcnt lgkmcnt(5)
	v_mfma_f32_16x16x32_bf16 v[46:49], v[152:155], v[192:195], v[46:49]
	v_mfma_f32_16x16x32_bf16 v[42:45], v[160:163], v[192:195], v[42:45]
	s_waitcnt lgkmcnt(3)
	v_mfma_f32_16x16x32_bf16 v[30:33], v[152:155], v[200:203], v[30:33]
	v_mfma_f32_16x16x32_bf16 v[26:29], v[160:163], v[200:203], v[26:29]
	s_waitcnt lgkmcnt(1)
	v_mfma_f32_16x16x32_bf16 v[14:17], v[152:155], v[208:211], v[14:17]
	v_mfma_f32_16x16x32_bf16 v[10:13], v[160:163], v[208:211], v[10:13]
	v_mfma_f32_16x16x32_bf16 v[62:65], v[156:159], v[188:191], v[62:65]
	v_mfma_f32_16x16x32_bf16 v[58:61], v[164:167], v[188:191], v[58:61]
	v_mfma_f32_16x16x32_bf16 v[46:49], v[156:159], v[196:199], v[46:49]
	v_mfma_f32_16x16x32_bf16 v[42:45], v[164:167], v[196:199], v[42:45]
	v_mfma_f32_16x16x32_bf16 v[30:33], v[156:159], v[204:207], v[30:33]
	v_mfma_f32_16x16x32_bf16 v[26:29], v[164:167], v[204:207], v[26:29]
	s_waitcnt lgkmcnt(0)
	v_mfma_f32_16x16x32_bf16 v[14:17], v[156:159], v[252:255], v[14:17]
	v_mfma_f32_16x16x32_bf16 v[10:13], v[164:167], v[252:255], v[10:13]
	s_setprio 0
	s_setprio 1
	v_mfma_f32_16x16x32_bf16 v[54:57], v[168:171], v[184:187], v[54:57]
	v_mfma_f32_16x16x32_bf16 v[50:53], v[176:179], v[184:187], v[50:53]
	v_mfma_f32_16x16x32_bf16 v[38:41], v[168:171], v[192:195], v[38:41]
	v_mfma_f32_16x16x32_bf16 v[34:37], v[176:179], v[192:195], v[34:37]
	v_mfma_f32_16x16x32_bf16 v[22:25], v[168:171], v[200:203], v[22:25]
	v_mfma_f32_16x16x32_bf16 v[18:21], v[176:179], v[200:203], v[18:21]
	v_mfma_f32_16x16x32_bf16 v[6:9], v[168:171], v[208:211], v[6:9]
	v_mfma_f32_16x16x32_bf16 v[2:5], v[176:179], v[208:211], v[2:5]
	v_mfma_f32_16x16x32_bf16 v[54:57], v[172:175], v[188:191], v[54:57]
	v_mfma_f32_16x16x32_bf16 v[50:53], v[180:183], v[188:191], v[50:53]
	v_mfma_f32_16x16x32_bf16 v[38:41], v[172:175], v[196:199], v[38:41]
	v_mfma_f32_16x16x32_bf16 v[34:37], v[180:183], v[196:199], v[34:37]
	v_mfma_f32_16x16x32_bf16 v[22:25], v[172:175], v[204:207], v[22:25]
	v_mfma_f32_16x16x32_bf16 v[18:21], v[180:183], v[204:207], v[18:21]
	v_mfma_f32_16x16x32_bf16 v[6:9], v[172:175], v[252:255], v[6:9]
	s_barrier
	v_mfma_f32_16x16x32_bf16 v[2:5], v[180:183], v[252:255], v[2:5]
	s_setprio 0
	v_add_u32_e32 v164, 0x18000, v149
	v_add_u32_e32 v180, 0x1c000, v149
	ds_read_b128 v[152:155], v164
	ds_read_b128 v[156:159], v164 offset:1024
	ds_read_b128 v[160:163], v164 offset:2048
	ds_read_b128 v[164:167], v164 offset:3072
	ds_read_b128 v[168:171], v180
	ds_read_b128 v[172:175], v180 offset:1024
	ds_read_b128 v[176:179], v180 offset:2048
	ds_read_b128 v[248:251], v180 offset:3072
	ds_read_b128 v[184:187], v150 offset:32768
	ds_read_b128 v[188:191], v150 offset:33792
	ds_read_b128 v[192:195], v150 offset:34816
	ds_read_b128 v[196:199], v150 offset:35840
	ds_read_b128 v[200:203], v150 offset:36864
	ds_read_b128 v[204:207], v150 offset:37888
	ds_read_b128 v[208:211], v150 offset:38912
	ds_read_b128 v[212:215], v150 offset:39936
	s_add_u32 s40, s46, 0x100000
	s_addc_u32 s41, s47, 0
	s_mov_b32 m0, s54
	s_nop 0
	global_load_lds_dwordx4 v139, s[40:41]
	s_nop 0
	s_mov_b32 m0, s55
	s_nop 0
	global_load_lds_dwordx4 v141, s[40:41]
	s_waitcnt vmcnt(8)
	s_waitcnt lgkmcnt(0)
	s_barrier
	s_setprio 1
	s_waitcnt lgkmcnt(7)
	v_mfma_f32_16x16x32_bf16 v[126:129], v[152:155], v[184:187], v[126:129]
	v_mfma_f32_16x16x32_bf16 v[122:125], v[160:163], v[184:187], v[122:125]
	s_waitcnt lgkmcnt(5)
	v_mfma_f32_16x16x32_bf16 v[110:113], v[152:155], v[192:195], v[110:113]
	v_mfma_f32_16x16x32_bf16 v[106:109], v[160:163], v[192:195], v[106:109]
	s_waitcnt lgkmcnt(3)
	v_mfma_f32_16x16x32_bf16 v[94:97], v[152:155], v[200:203], v[94:97]
	v_mfma_f32_16x16x32_bf16 v[90:93], v[160:163], v[200:203], v[90:93]
	s_waitcnt lgkmcnt(1)
	v_mfma_f32_16x16x32_bf16 v[78:81], v[152:155], v[208:211], v[78:81]
	v_mfma_f32_16x16x32_bf16 v[74:77], v[160:163], v[208:211], v[74:77]
	v_mfma_f32_16x16x32_bf16 v[126:129], v[156:159], v[188:191], v[126:129]
	v_mfma_f32_16x16x32_bf16 v[122:125], v[164:167], v[188:191], v[122:125]
	v_mfma_f32_16x16x32_bf16 v[110:113], v[156:159], v[196:199], v[110:113]
	v_mfma_f32_16x16x32_bf16 v[106:109], v[164:167], v[196:199], v[106:109]
	v_mfma_f32_16x16x32_bf16 v[94:97], v[156:159], v[204:207], v[94:97]
	v_mfma_f32_16x16x32_bf16 v[90:93], v[164:167], v[204:207], v[90:93]
	s_waitcnt lgkmcnt(0)
	v_mfma_f32_16x16x32_bf16 v[78:81], v[156:159], v[212:215], v[78:81]
	v_mfma_f32_16x16x32_bf16 v[74:77], v[164:167], v[212:215], v[74:77]
	s_setprio 0
	s_setprio 1
	v_mfma_f32_16x16x32_bf16 v[118:121], v[168:171], v[184:187], v[118:121]
	v_mfma_f32_16x16x32_bf16 v[114:117], v[176:179], v[184:187], v[114:117]
	v_mfma_f32_16x16x32_bf16 v[102:105], v[168:171], v[192:195], v[102:105]
	v_mfma_f32_16x16x32_bf16 v[98:101], v[176:179], v[192:195], v[98:101]
	v_mfma_f32_16x16x32_bf16 v[86:89], v[168:171], v[200:203], v[86:89]
	v_mfma_f32_16x16x32_bf16 v[82:85], v[176:179], v[200:203], v[82:85]
	v_mfma_f32_16x16x32_bf16 v[70:73], v[168:171], v[208:211], v[70:73]
	v_mfma_f32_16x16x32_bf16 v[66:69], v[176:179], v[208:211], v[66:69]
	v_mfma_f32_16x16x32_bf16 v[118:121], v[172:175], v[188:191], v[118:121]
	v_mfma_f32_16x16x32_bf16 v[114:117], v[248:251], v[188:191], v[114:117]
	v_mfma_f32_16x16x32_bf16 v[102:105], v[172:175], v[196:199], v[102:105]
	v_mfma_f32_16x16x32_bf16 v[98:101], v[248:251], v[196:199], v[98:101]
	v_mfma_f32_16x16x32_bf16 v[86:89], v[172:175], v[204:207], v[86:89]
	v_mfma_f32_16x16x32_bf16 v[82:85], v[248:251], v[204:207], v[82:85]
	v_mfma_f32_16x16x32_bf16 v[70:73], v[172:175], v[212:215], v[70:73]
	s_barrier
; #define PG8_STAGE(bufoff, gbase, voff) do { _Pragma("unroll") for (int _i = 0; _i < 2; ++_i) \
;         asm volatile("s_mov_b32 m0, %2\n\ts_nop 0\n\tglobal_load_lds_dwordx4 %0, %1" :: "v"((voff)[_i]), "s"((const char*)(gbase)), "s"(ldsbase + (unsigned)(bufoff) + ldsw + (unsigned)_i * 8192u) : "memory", "m0"); } while (0)
; #define PG8_LDA(dst, b, h) do { _Pragma("unroll") for (int m = 0; m < 4; ++m) _Pragma("unroll") for (int k = 0; k < 2; ++k) dst[m][k] = *(const PG8_LAS bf16x8*)(lds + PG8_SA(b, h) + aoff + m * 2048 + k * 1024); } while (0)
; #define PG8_MMA(ai, bj, At, Bt) do { __builtin_amdgcn_s_setprio(1); _Pragma("unroll") for (int m = 0; m < 4; ++m) _Pragma("unroll") for (int n = 0; n < 2; ++n) _Pragma("unroll") for (int k = 0; k < 2; ++k) \
;         acc[ai][bj][m][n] = __builtin_amdgcn_mfma_f32_16x16x32_bf16(Bt[n][k], At[m][k], acc[ai][bj][m][n], 0, 0, 0); __builtin_amdgcn_s_setprio(0); } while (0)
; #define PG8_WAIT_V(n) asm volatile("s_waitcnt vmcnt(" #n ")" ::: "memory")
; #define PG8_WAIT_L(n) asm volatile("s_waitcnt lgkmcnt(" #n ")" ::: "memory")
; #define PG8_BAR __builtin_amdgcn_s_barrier()
; #define PG8_SCHED __builtin_amdgcn_sched_barrier(0)
; template <class Epi, class Sched, bool ALIGN_EPI = false, bool SP2 = false>
; __device__ __forceinline__ void gemm_phase(PG8_LAS unsigned char* lds, const Gemm g, const Sched& S, const Epi& E) {
;     ...
;         for (int t = 0; t < nt; t += 2) {
;     ...
;             PG8_LDA(At, 1, 1); PG8_STAGE(PG8_SB(1, 0), b3, voffB); PG8_STAGE(PG8_SB(1, 1), b3 + hstep, voffB); PG8_STAGE(PG8_SA(1, 0), a3, voffA);
;             PG8_WAIT_V(8); PG8_WAIT_L(0); PG8_BAR; PG8_MMA(1, 0, At, B0); PG8_MMA(1, 1, At, B1); PG8_BAR; PG8_SCHED;
	v_mfma_f32_16x16x32_bf16 v[66:69], v[248:251], v[212:215], v[66:69]
	s_setprio 0
	ds_read_b128 v[184:187], v150 offset:49152
	ds_read_b128 v[188:191], v150 offset:50176
	ds_read_b128 v[192:195], v150 offset:51200
	ds_read_b128 v[196:199], v150 offset:52224
	ds_read_b128 v[200:203], v150 offset:53248
	ds_read_b128 v[204:207], v150 offset:54272
	ds_read_b128 v[208:211], v150 offset:55296
	ds_read_b128 v[252:255], v150 offset:56320
	s_mov_b32 m0, s56
	s_nop 0
	global_load_lds_dwordx4 v140, s[44:45]
	s_add_u32 s38, s38, 0x100080
	s_mov_b32 m0, s57
	s_nop 0
	global_load_lds_dwordx4 v142, s[44:45]
	s_addc_u32 s39, s39, 0
	s_mov_b32 m0, s62
	s_nop 0
	global_load_lds_dwordx4 v140, s[38:39]
	s_nop 0
	s_mov_b32 m0, s63
	s_nop 0
	global_load_lds_dwordx4 v142, s[38:39]
	s_nop 0
	s_mov_b32 m0, s60
	s_nop 0
	global_load_lds_dwordx4 v139, s[42:43]
	s_nop 0
	s_mov_b32 m0, s61
	s_nop 0
	global_load_lds_dwordx4 v141, s[42:43]
	s_waitcnt vmcnt(8)
	s_waitcnt lgkmcnt(0)
	s_barrier
	s_setprio 1
	s_waitcnt lgkmcnt(7)
	v_mfma_f32_16x16x32_bf16 v[62:65], v[152:155], v[184:187], v[62:65]
	v_mfma_f32_16x16x32_bf16 v[58:61], v[160:163], v[184:187], v[58:61]
	s_waitcnt lgkmcnt(5)
	v_mfma_f32_16x16x32_bf16 v[46:49], v[152:155], v[192:195], v[46:49]
	v_mfma_f32_16x16x32_bf16 v[42:45], v[160:163], v[192:195], v[42:45]
	s_waitcnt lgkmcnt(3)
	v_mfma_f32_16x16x32_bf16 v[30:33], v[152:155], v[200:203], v[30:33]
	v_mfma_f32_16x16x32_bf16 v[26:29], v[160:163], v[200:203], v[26:29]
	s_waitcnt lgkmcnt(1)
	v_mfma_f32_16x16x32_bf16 v[14:17], v[152:155], v[208:211], v[14:17]
	v_mfma_f32_16x16x32_bf16 v[10:13], v[160:163], v[208:211], v[10:13]
	v_mfma_f32_16x16x32_bf16 v[62:65], v[156:159], v[188:191], v[62:65]
	v_mfma_f32_16x16x32_bf16 v[58:61], v[164:167], v[188:191], v[58:61]
	v_mfma_f32_16x16x32_bf16 v[46:49], v[156:159], v[196:199], v[46:49]
	v_mfma_f32_16x16x32_bf16 v[42:45], v[164:167], v[196:199], v[42:45]
	v_mfma_f32_16x16x32_bf16 v[30:33], v[156:159], v[204:207], v[30:33]
	v_mfma_f32_16x16x32_bf16 v[26:29], v[164:167], v[204:207], v[26:29]
	s_waitcnt lgkmcnt(0)
	v_mfma_f32_16x16x32_bf16 v[14:17], v[156:159], v[252:255], v[14:17]
	v_mfma_f32_16x16x32_bf16 v[10:13], v[164:167], v[252:255], v[10:13]
	s_setprio 0
	s_setprio 1
	v_mfma_f32_16x16x32_bf16 v[54:57], v[168:171], v[184:187], v[54:57]
	v_mfma_f32_16x16x32_bf16 v[50:53], v[176:179], v[184:187], v[50:53]
	v_mfma_f32_16x16x32_bf16 v[38:41], v[168:171], v[192:195], v[38:41]
	v_mfma_f32_16x16x32_bf16 v[34:37], v[176:179], v[192:195], v[34:37]
	v_mfma_f32_16x16x32_bf16 v[22:25], v[168:171], v[200:203], v[22:25]
	v_mfma_f32_16x16x32_bf16 v[18:21], v[176:179], v[200:203], v[18:21]
	v_mfma_f32_16x16x32_bf16 v[6:9], v[168:171], v[208:211], v[6:9]
	v_mfma_f32_16x16x32_bf16 v[2:5], v[176:179], v[208:211], v[2:5]
	v_mfma_f32_16x16x32_bf16 v[54:57], v[172:175], v[188:191], v[54:57]
	v_mfma_f32_16x16x32_bf16 v[50:53], v[248:251], v[188:191], v[50:53]
	v_mfma_f32_16x16x32_bf16 v[38:41], v[172:175], v[196:199], v[38:41]
	v_mfma_f32_16x16x32_bf16 v[34:37], v[248:251], v[196:199], v[34:37]
	v_mfma_f32_16x16x32_bf16 v[22:25], v[172:175], v[204:207], v[22:25]
	v_mfma_f32_16x16x32_bf16 v[18:21], v[248:251], v[204:207], v[18:21]
	v_mfma_f32_16x16x32_bf16 v[6:9], v[172:175], v[252:255], v[6:9]
	s_barrier
	v_mfma_f32_16x16x32_bf16 v[2:5], v[248:251], v[252:255], v[2:5]
	s_setprio 0
	s_add_i32 s76, s76, 2
	s_add_u32 s74, s74, 0x100
	s_addc_u32 s75, s75, 0
	s_cmp_gt_u32 s76, 61
	s_cbranch_scc1 .LBB0_780
	s_mov_b64 s[40:41], s[8:9]
	s_branch .LBB0_784

; #define PG8_STAGE(bufoff, gbase, voff) do { _Pragma("unroll") for (int _i = 0; _i < 2; ++_i) \
;         asm volatile("s_mov_b32 m0, %2\n\ts_nop 0\n\tglobal_load_lds_dwordx4 %0, %1" :: "v"((voff)[_i]), "s"((const char*)(gbase)), "s"(ldsbase + (unsigned)(bufoff) + ldsw + (unsigned)_i * 8192u) : "memory", "m0"); } while (0)
; #define PG8_LDA(dst, b, h) do { _Pragma("unroll") for (int m = 0; m < 4; ++m) _Pragma("unroll") for (int k = 0; k < 2; ++k) dst[m][k] = *(const PG8_LAS bf16x8*)(lds + PG8_SA(b, h) + aoff + m * 2048 + k * 1024); } while (0)
; #define PG8_WAIT_V(n) asm volatile("s_waitcnt vmcnt(" #n ")" ::: "memory")
; #define PG8_WAIT_L(n) asm volatile("s_waitcnt lgkmcnt(" #n ")" ::: "memory")
; template <class Epi, class Sched, bool ALIGN_EPI = false, bool SP2 = false>
; __device__ __forceinline__ void gemm_phase(PG8_LAS unsigned char* lds, const Gemm g, const Sched& S, const Epi& E) {
;     ...
;             const char* a1 = cA + (size_t)(t + 1) * kstep;
;             const char* a2 = last ? nA : cA + (size_t)(t + 2) * kstep; const char* b2 = last ? nB : cB + (size_t)(t + 2) * kstep;
;             const char* a3 = a2 + kstep; const char* b3 = b2 + kstep;
;             if (last && has_next) S.a_ready(nxt);
;             if constexpr (epi_has_mid<Epi>::value) { if (t == Epi::MID_T) E.mid(acc, cur, wr, wc, fr, fq); }
;             if constexpr (SP2) {
;             PG8_LDB(B0, 0, 0); PG8_LDB(B1, 0, 1); PG8_SCHED; PG8_LDA(At, 0, 0); PG8_STAGE(PG8_SA(1, 1), a1 + hstep, voffA);
;             PG8_WAIT_V(8); PG8_WAIT_L(0); PG8_BAR; PG8_MMA(0, 0, At, B0); PG8_MMA(0, 1, At, B1); PG8_BAR; PG8_SCHED;
;             PG8_LDA(At, 0, 1); PG8_STAGE(PG8_SB(0, 0), b2, voffB); PG8_STAGE(PG8_SB(0, 1), b2 + hstep, voffB); PG8_STAGE(PG8_SA(0, 0), a2, voffA);
;             PG8_WAIT_V(8); PG8_WAIT_L(0); PG8_BAR; PG8_MMA(1, 0, At, B0); PG8_MMA(1, 1, At, B1); PG8_BAR; PG8_SCHED;
;             PG8_LDB(B0, 1, 0); PG8_LDB(B1, 1, 1); PG8_SCHED; PG8_LDA(At, 1, 0); PG8_STAGE(PG8_SA(0, 1), a2 + hstep, voffA);
;             PG8_WAIT_V(8); PG8_WAIT_L(0); PG8_BAR; PG8_MMA(0, 0, At, B0); PG8_MMA(0, 1, At, B1); PG8_BAR; PG8_SCHED;
;             PG8_LDA(At, 1, 1); PG8_STAGE(PG8_SB(1, 0), b3, voffB); PG8_STAGE(PG8_SB(1, 1), b3 + hstep, voffB); PG8_STAGE(PG8_SA(1, 0), a3, voffA);
;             PG8_WAIT_V(8); PG8_WAIT_L(0); PG8_BAR; PG8_MMA(1, 0, At, B0); PG8_MMA(1, 1, At, B1); PG8_BAR; PG8_SCHED;
.LBB0_873:
	ds_read_b128 v[134:137], v145
	ds_read_b128 v[150:153], v145 offset:1024
	ds_read_b128 v[154:157], v145 offset:2048
	ds_read_b128 v[158:161], v145 offset:3072
	ds_read_b128 v[162:165], v146
	ds_read_b128 v[166:169], v146 offset:1024
	ds_read_b128 v[170:173], v146 offset:2048
	ds_read_b128 v[174:177], v146 offset:3072
	s_add_u32 s38, s36, 0x100
	s_addc_u32 s39, s37, 0
	s_cmpk_eq_i32 s69, 0xa8
	s_cselect_b32 s44, s4, s38
	s_cselect_b32 s45, s5, s39
	s_cselect_b32 s42, s22, s67
	s_cselect_b32 s43, s23, s68
	s_add_u32 s40, s44, 0x80
	s_addc_u32 s41, s45, 0
	ds_read_b128 v[178:181], v147
	ds_read_b128 v[182:185], v147 offset:1024
	ds_read_b128 v[186:189], v147 offset:2048
	ds_read_b128 v[190:193], v147 offset:3072
	ds_read_b128 v[194:197], v147 offset:4096
	ds_read_b128 v[198:201], v147 offset:5120
	ds_read_b128 v[202:205], v147 offset:6144
	ds_read_b128 v[206:209], v147 offset:7168
	s_add_u32 s36, s36, 0x2b0080
	s_addc_u32 s37, s37, 0
	s_mov_b32 m0, s60
	s_nop 0
	global_load_lds_dwordx4 v1, s[36:37]
	s_nop 0
	s_mov_b32 m0, s61
	s_nop 0
	global_load_lds_dwordx4 v141, s[36:37]
	s_waitcnt vmcnt(8)
	s_waitcnt lgkmcnt(0)
	s_barrier
	s_setprio 1
	s_waitcnt lgkmcnt(7)
	v_mfma_f32_16x16x32_bf16 v[126:129], v[134:137], v[178:181], v[126:129]
	v_mfma_f32_16x16x32_bf16 v[122:125], v[154:157], v[178:181], v[122:125]
	s_waitcnt lgkmcnt(5)
	v_mfma_f32_16x16x32_bf16 v[110:113], v[134:137], v[186:189], v[110:113]
	v_mfma_f32_16x16x32_bf16 v[106:109], v[154:157], v[186:189], v[106:109]
	s_waitcnt lgkmcnt(3)
	v_mfma_f32_16x16x32_bf16 v[94:97], v[134:137], v[194:197], v[94:97]
	v_mfma_f32_16x16x32_bf16 v[90:93], v[154:157], v[194:197], v[90:93]
	s_waitcnt lgkmcnt(1)
	v_mfma_f32_16x16x32_bf16 v[78:81], v[134:137], v[202:205], v[78:81]
	v_mfma_f32_16x16x32_bf16 v[74:77], v[154:157], v[202:205], v[74:77]
	v_mfma_f32_16x16x32_bf16 v[126:129], v[150:153], v[182:185], v[126:129]
	v_mfma_f32_16x16x32_bf16 v[122:125], v[158:161], v[182:185], v[122:125]
	v_mfma_f32_16x16x32_bf16 v[110:113], v[150:153], v[190:193], v[110:113]
	v_mfma_f32_16x16x32_bf16 v[106:109], v[158:161], v[190:193], v[106:109]
	v_mfma_f32_16x16x32_bf16 v[94:97], v[150:153], v[198:201], v[94:97]
	v_mfma_f32_16x16x32_bf16 v[90:93], v[158:161], v[198:201], v[90:93]
	s_waitcnt lgkmcnt(0)
	v_mfma_f32_16x16x32_bf16 v[78:81], v[150:153], v[206:209], v[78:81]
	v_mfma_f32_16x16x32_bf16 v[74:77], v[158:161], v[206:209], v[74:77]
	s_setprio 0
	s_setprio 1
	v_mfma_f32_16x16x32_bf16 v[118:121], v[162:165], v[178:181], v[118:121]
	v_mfma_f32_16x16x32_bf16 v[114:117], v[170:173], v[178:181], v[114:117]
	v_mfma_f32_16x16x32_bf16 v[102:105], v[162:165], v[186:189], v[102:105]
	v_mfma_f32_16x16x32_bf16 v[98:101], v[170:173], v[186:189], v[98:101]
	v_mfma_f32_16x16x32_bf16 v[86:89], v[162:165], v[194:197], v[86:89]
	v_mfma_f32_16x16x32_bf16 v[82:85], v[170:173], v[194:197], v[82:85]
	v_mfma_f32_16x16x32_bf16 v[70:73], v[162:165], v[202:205], v[70:73]
	v_mfma_f32_16x16x32_bf16 v[66:69], v[170:173], v[202:205], v[66:69]
	v_mfma_f32_16x16x32_bf16 v[118:121], v[166:169], v[182:185], v[118:121]
	v_mfma_f32_16x16x32_bf16 v[114:117], v[174:177], v[182:185], v[114:117]
	v_mfma_f32_16x16x32_bf16 v[102:105], v[166:169], v[190:193], v[102:105]
	v_mfma_f32_16x16x32_bf16 v[98:101], v[174:177], v[190:193], v[98:101]
	v_mfma_f32_16x16x32_bf16 v[86:89], v[166:169], v[198:201], v[86:89]
	v_mfma_f32_16x16x32_bf16 v[82:85], v[174:177], v[198:201], v[82:85]
	v_mfma_f32_16x16x32_bf16 v[70:73], v[166:169], v[206:209], v[70:73]
	s_barrier
	v_mfma_f32_16x16x32_bf16 v[66:69], v[174:177], v[206:209], v[66:69]
	s_setprio 0
	ds_read_b128 v[178:181], v147 offset:16384
	ds_read_b128 v[182:185], v147 offset:17408
	ds_read_b128 v[186:189], v147 offset:18432
	ds_read_b128 v[190:193], v147 offset:19456
	ds_read_b128 v[194:197], v147 offset:20480
	ds_read_b128 v[198:201], v147 offset:21504
	ds_read_b128 v[202:205], v147 offset:22528
	ds_read_b128 v[252:255], v147 offset:23552
	s_mov_b32 m0, s47
	s_nop 0
	global_load_lds_dwordx4 v140, s[42:43]
	s_add_u32 s36, s42, 0x2b0000
	s_mov_b32 m0, s48
	s_nop 0
	global_load_lds_dwordx4 v142, s[42:43]
	s_addc_u32 s37, s43, 0
	s_mov_b32 m0, s49
	s_nop 0
	global_load_lds_dwordx4 v140, s[36:37]
	s_nop 0
	s_mov_b32 m0, s50
	s_nop 0
	global_load_lds_dwordx4 v142, s[36:37]
	s_nop 0
	s_mov_b32 m0, s46
	s_nop 0
	global_load_lds_dwordx4 v1, s[44:45]
	s_nop 0
	s_mov_b32 m0, s51
	s_nop 0
	global_load_lds_dwordx4 v141, s[44:45]
	s_waitcnt vmcnt(8)
	s_waitcnt lgkmcnt(0)
	s_barrier
	s_setprio 1
	s_waitcnt lgkmcnt(7)
	v_mfma_f32_16x16x32_bf16 v[62:65], v[134:137], v[178:181], v[62:65]
	v_mfma_f32_16x16x32_bf16 v[58:61], v[154:157], v[178:181], v[58:61]
	s_waitcnt lgkmcnt(5)
	v_mfma_f32_16x16x32_bf16 v[46:49], v[134:137], v[186:189], v[46:49]
	v_mfma_f32_16x16x32_bf16 v[42:45], v[154:157], v[186:189], v[42:45]
	s_waitcnt lgkmcnt(3)
	v_mfma_f32_16x16x32_bf16 v[30:33], v[134:137], v[194:197], v[30:33]
	v_mfma_f32_16x16x32_bf16 v[26:29], v[154:157], v[194:197], v[26:29]
	s_waitcnt lgkmcnt(1)
	v_mfma_f32_16x16x32_bf16 v[14:17], v[134:137], v[202:205], v[14:17]
	v_mfma_f32_16x16x32_bf16 v[10:13], v[154:157], v[202:205], v[10:13]
	v_mfma_f32_16x16x32_bf16 v[62:65], v[150:153], v[182:185], v[62:65]
	v_mfma_f32_16x16x32_bf16 v[58:61], v[158:161], v[182:185], v[58:61]
	v_mfma_f32_16x16x32_bf16 v[46:49], v[150:153], v[190:193], v[46:49]
	v_mfma_f32_16x16x32_bf16 v[42:45], v[158:161], v[190:193], v[42:45]
	v_mfma_f32_16x16x32_bf16 v[30:33], v[150:153], v[198:201], v[30:33]
	v_mfma_f32_16x16x32_bf16 v[26:29], v[158:161], v[198:201], v[26:29]
	s_waitcnt lgkmcnt(0)
	v_mfma_f32_16x16x32_bf16 v[14:17], v[150:153], v[252:255], v[14:17]
	v_mfma_f32_16x16x32_bf16 v[10:13], v[158:161], v[252:255], v[10:13]
	s_setprio 0
	s_setprio 1
	v_mfma_f32_16x16x32_bf16 v[54:57], v[162:165], v[178:181], v[54:57]
	v_mfma_f32_16x16x32_bf16 v[50:53], v[170:173], v[178:181], v[50:53]
	v_mfma_f32_16x16x32_bf16 v[38:41], v[162:165], v[186:189], v[38:41]
	v_mfma_f32_16x16x32_bf16 v[34:37], v[170:173], v[186:189], v[34:37]
	v_mfma_f32_16x16x32_bf16 v[22:25], v[162:165], v[194:197], v[22:25]
	v_mfma_f32_16x16x32_bf16 v[18:21], v[170:173], v[194:197], v[18:21]
	v_mfma_f32_16x16x32_bf16 v[6:9], v[162:165], v[202:205], v[6:9]
	v_mfma_f32_16x16x32_bf16 v[2:5], v[170:173], v[202:205], v[2:5]
	v_mfma_f32_16x16x32_bf16 v[54:57], v[166:169], v[182:185], v[54:57]
	v_mfma_f32_16x16x32_bf16 v[50:53], v[174:177], v[182:185], v[50:53]
	v_mfma_f32_16x16x32_bf16 v[38:41], v[166:169], v[190:193], v[38:41]
	v_mfma_f32_16x16x32_bf16 v[34:37], v[174:177], v[190:193], v[34:37]
	v_mfma_f32_16x16x32_bf16 v[22:25], v[166:169], v[198:201], v[22:25]
	v_mfma_f32_16x16x32_bf16 v[18:21], v[174:177], v[198:201], v[18:21]
	v_mfma_f32_16x16x32_bf16 v[6:9], v[166:169], v[252:255], v[6:9]
	s_barrier
; #define PG8_STAGE(bufoff, gbase, voff) do { _Pragma("unroll") for (int _i = 0; _i < 2; ++_i) \
;         asm volatile("s_mov_b32 m0, %2\n\ts_nop 0\n\tglobal_load_lds_dwordx4 %0, %1" :: "v"((voff)[_i]), "s"((const char*)(gbase)), "s"(ldsbase + (unsigned)(bufoff) + ldsw + (unsigned)_i * 8192u) : "memory", "m0"); } while (0)
; #define PG8_LDA(dst, b, h) do { _Pragma("unroll") for (int m = 0; m < 4; ++m) _Pragma("unroll") for (int k = 0; k < 2; ++k) dst[m][k] = *(const PG8_LAS bf16x8*)(lds + PG8_SA(b, h) + aoff + m * 2048 + k * 1024); } while (0)
; #define PG8_LDB(dst, b, h) do { _Pragma("unroll") for (int n = 0; n < 2; ++n) _Pragma("unroll") for (int k = 0; k < 2; ++k) dst[n][k] = *(const PG8_LAS bf16x8*)(lds + PG8_SB(b, h) + boff + n * 2048 + k * 1024); } while (0)
; #define PG8_MMA(ai, bj, At, Bt) do { __builtin_amdgcn_s_setprio(1); _Pragma("unroll") for (int m = 0; m < 4; ++m) _Pragma("unroll") for (int n = 0; n < 2; ++n) _Pragma("unroll") for (int k = 0; k < 2; ++k) \
;         acc[ai][bj][m][n] = __builtin_amdgcn_mfma_f32_16x16x32_bf16(Bt[n][k], At[m][k], acc[ai][bj][m][n], 0, 0, 0); __builtin_amdgcn_s_setprio(0); } while (0)
; #define PG8_WAIT_V(n) asm volatile("s_waitcnt vmcnt(" #n ")" ::: "memory")
; #define PG8_WAIT_L(n) asm volatile("s_waitcnt lgkmcnt(" #n ")" ::: "memory")
; #define PG8_BAR __builtin_amdgcn_s_barrier()
; #define PG8_SCHED __builtin_amdgcn_sched_barrier(0)
; template <class Epi, class Sched, bool ALIGN_EPI = false, bool SP2 = false>
; __device__ __forceinline__ void gemm_phase(PG8_LAS unsigned char* lds, const Gemm g, const Sched& S, const Epi& E) {
;     ...
;         for (int t = 0; t < nt; t += 2) {
;     ...
;             PG8_LDB(B0, 1, 0); PG8_LDB(B1, 1, 1); PG8_SCHED; PG8_LDA(At, 1, 0); PG8_STAGE(PG8_SA(0, 1), a2 + hstep, voffA);
;             PG8_WAIT_V(8); PG8_WAIT_L(0); PG8_BAR; PG8_MMA(0, 0, At, B0); PG8_MMA(0, 1, At, B1); PG8_BAR; PG8_SCHED;
;             PG8_LDA(At, 1, 1); PG8_STAGE(PG8_SB(1, 0), b3, voffB); PG8_STAGE(PG8_SB(1, 1), b3 + hstep, voffB); PG8_STAGE(PG8_SA(1, 0), a3, voffA);
;             PG8_WAIT_V(8); PG8_WAIT_L(0); PG8_BAR; PG8_MMA(1, 0, At, B0); PG8_MMA(1, 1, At, B1); PG8_BAR; PG8_SCHED;
;     ...
;         if constexpr (ALIGN_EPI) { if (wr == 0) PG8_BAR; }
	v_mfma_f32_16x16x32_bf16 v[2:5], v[174:177], v[252:255], v[2:5]
	s_setprio 0
	ds_read_b128 v[134:137], v148
	ds_read_b128 v[150:153], v148 offset:1024
	ds_read_b128 v[154:157], v148 offset:2048
	ds_read_b128 v[158:161], v148 offset:3072
	ds_read_b128 v[162:165], v149
	ds_read_b128 v[166:169], v149 offset:1024
	ds_read_b128 v[170:173], v149 offset:2048
	ds_read_b128 v[248:251], v149 offset:3072
	ds_read_b128 v[178:181], v147 offset:32768
	ds_read_b128 v[182:185], v147 offset:33792
	ds_read_b128 v[186:189], v147 offset:34816
	ds_read_b128 v[190:193], v147 offset:35840
	ds_read_b128 v[194:197], v147 offset:36864
	ds_read_b128 v[198:201], v147 offset:37888
	ds_read_b128 v[202:205], v147 offset:38912
	ds_read_b128 v[206:209], v147 offset:39936
	s_add_u32 s36, s44, 0x2b0000
	s_addc_u32 s37, s45, 0
	s_mov_b32 m0, s52
	s_nop 0
	global_load_lds_dwordx4 v1, s[36:37]
	s_nop 0
	s_mov_b32 m0, s53
	s_nop 0
	global_load_lds_dwordx4 v141, s[36:37]
	s_waitcnt vmcnt(8)
	s_waitcnt lgkmcnt(0)
	s_barrier
	s_setprio 1
	s_waitcnt lgkmcnt(7)
	v_mfma_f32_16x16x32_bf16 v[126:129], v[134:137], v[178:181], v[126:129]
	v_mfma_f32_16x16x32_bf16 v[122:125], v[154:157], v[178:181], v[122:125]
	s_waitcnt lgkmcnt(5)
	v_mfma_f32_16x16x32_bf16 v[110:113], v[134:137], v[186:189], v[110:113]
	v_mfma_f32_16x16x32_bf16 v[106:109], v[154:157], v[186:189], v[106:109]
	s_waitcnt lgkmcnt(3)
	v_mfma_f32_16x16x32_bf16 v[94:97], v[134:137], v[194:197], v[94:97]
	v_mfma_f32_16x16x32_bf16 v[90:93], v[154:157], v[194:197], v[90:93]
	s_waitcnt lgkmcnt(1)
	v_mfma_f32_16x16x32_bf16 v[78:81], v[134:137], v[202:205], v[78:81]
	v_mfma_f32_16x16x32_bf16 v[74:77], v[154:157], v[202:205], v[74:77]
	v_mfma_f32_16x16x32_bf16 v[126:129], v[150:153], v[182:185], v[126:129]
	v_mfma_f32_16x16x32_bf16 v[122:125], v[158:161], v[182:185], v[122:125]
	v_mfma_f32_16x16x32_bf16 v[110:113], v[150:153], v[190:193], v[110:113]
	v_mfma_f32_16x16x32_bf16 v[106:109], v[158:161], v[190:193], v[106:109]
	v_mfma_f32_16x16x32_bf16 v[94:97], v[150:153], v[198:201], v[94:97]
	v_mfma_f32_16x16x32_bf16 v[90:93], v[158:161], v[198:201], v[90:93]
	s_waitcnt lgkmcnt(0)
	v_mfma_f32_16x16x32_bf16 v[78:81], v[150:153], v[206:209], v[78:81]
	v_mfma_f32_16x16x32_bf16 v[74:77], v[158:161], v[206:209], v[74:77]
	s_setprio 0
	s_setprio 1
	v_mfma_f32_16x16x32_bf16 v[118:121], v[162:165], v[178:181], v[118:121]
	v_mfma_f32_16x16x32_bf16 v[114:117], v[170:173], v[178:181], v[114:117]
	v_mfma_f32_16x16x32_bf16 v[102:105], v[162:165], v[186:189], v[102:105]
	v_mfma_f32_16x16x32_bf16 v[98:101], v[170:173], v[186:189], v[98:101]
	v_mfma_f32_16x16x32_bf16 v[86:89], v[162:165], v[194:197], v[86:89]
	v_mfma_f32_16x16x32_bf16 v[82:85], v[170:173], v[194:197], v[82:85]
	v_mfma_f32_16x16x32_bf16 v[70:73], v[162:165], v[202:205], v[70:73]
	v_mfma_f32_16x16x32_bf16 v[66:69], v[170:173], v[202:205], v[66:69]
	v_mfma_f32_16x16x32_bf16 v[118:121], v[166:169], v[182:185], v[118:121]
	v_mfma_f32_16x16x32_bf16 v[114:117], v[248:251], v[182:185], v[114:117]
	v_mfma_f32_16x16x32_bf16 v[102:105], v[166:169], v[190:193], v[102:105]
	v_mfma_f32_16x16x32_bf16 v[98:101], v[248:251], v[190:193], v[98:101]
	v_mfma_f32_16x16x32_bf16 v[86:89], v[166:169], v[198:201], v[86:89]
	v_mfma_f32_16x16x32_bf16 v[82:85], v[248:251], v[198:201], v[82:85]
	v_mfma_f32_16x16x32_bf16 v[70:73], v[166:169], v[206:209], v[70:73]
	s_barrier
	v_mfma_f32_16x16x32_bf16 v[66:69], v[248:251], v[206:209], v[66:69]
	s_setprio 0
	ds_read_b128 v[178:181], v147 offset:49152
	ds_read_b128 v[182:185], v147 offset:50176
	ds_read_b128 v[186:189], v147 offset:51200
	ds_read_b128 v[190:193], v147 offset:52224
	ds_read_b128 v[194:197], v147 offset:53248
	ds_read_b128 v[198:201], v147 offset:54272
	ds_read_b128 v[202:205], v147 offset:55296
	ds_read_b128 v[252:255], v147 offset:56320
	s_add_u32 s36, s42, 0x80
	s_addc_u32 s37, s43, 0
	s_mov_b32 m0, s54
	s_nop 0
	global_load_lds_dwordx4 v140, s[36:37]
	s_nop 0
	s_mov_b32 m0, s55
	s_nop 0
	global_load_lds_dwordx4 v142, s[36:37]
	s_add_u32 s36, s42, 0x2b0080
	s_addc_u32 s37, s43, 0
	s_mov_b32 m0, s58
	s_nop 0
	global_load_lds_dwordx4 v140, s[36:37]
	s_nop 0
	s_mov_b32 m0, s59
	s_nop 0
	global_load_lds_dwordx4 v142, s[36:37]
	s_nop 0
	s_mov_b32 m0, s56
	s_nop 0
	global_load_lds_dwordx4 v1, s[40:41]
	s_nop 0
	s_mov_b32 m0, s57
	s_nop 0
	global_load_lds_dwordx4 v141, s[40:41]
	s_waitcnt vmcnt(8)
	s_waitcnt lgkmcnt(0)
	s_barrier
	s_setprio 1
	s_waitcnt lgkmcnt(7)
	v_mfma_f32_16x16x32_bf16 v[62:65], v[134:137], v[178:181], v[62:65]
	v_mfma_f32_16x16x32_bf16 v[58:61], v[154:157], v[178:181], v[58:61]
	s_waitcnt lgkmcnt(5)
	v_mfma_f32_16x16x32_bf16 v[46:49], v[134:137], v[186:189], v[46:49]
	v_mfma_f32_16x16x32_bf16 v[42:45], v[154:157], v[186:189], v[42:45]
	s_waitcnt lgkmcnt(3)
	v_mfma_f32_16x16x32_bf16 v[30:33], v[134:137], v[194:197], v[30:33]
	v_mfma_f32_16x16x32_bf16 v[26:29], v[154:157], v[194:197], v[26:29]
	s_waitcnt lgkmcnt(1)
	v_mfma_f32_16x16x32_bf16 v[14:17], v[134:137], v[202:205], v[14:17]
	v_mfma_f32_16x16x32_bf16 v[10:13], v[154:157], v[202:205], v[10:13]
	v_mfma_f32_16x16x32_bf16 v[62:65], v[150:153], v[182:185], v[62:65]
	v_mfma_f32_16x16x32_bf16 v[58:61], v[158:161], v[182:185], v[58:61]
	v_mfma_f32_16x16x32_bf16 v[46:49], v[150:153], v[190:193], v[46:49]
	v_mfma_f32_16x16x32_bf16 v[42:45], v[158:161], v[190:193], v[42:45]
	v_mfma_f32_16x16x32_bf16 v[30:33], v[150:153], v[198:201], v[30:33]
	v_mfma_f32_16x16x32_bf16 v[26:29], v[158:161], v[198:201], v[26:29]
	s_waitcnt lgkmcnt(0)
	v_mfma_f32_16x16x32_bf16 v[14:17], v[150:153], v[252:255], v[14:17]
	v_mfma_f32_16x16x32_bf16 v[10:13], v[158:161], v[252:255], v[10:13]
	s_setprio 0
	s_setprio 1
	v_mfma_f32_16x16x32_bf16 v[54:57], v[162:165], v[178:181], v[54:57]
	v_mfma_f32_16x16x32_bf16 v[50:53], v[170:173], v[178:181], v[50:53]
	v_mfma_f32_16x16x32_bf16 v[38:41], v[162:165], v[186:189], v[38:41]
	v_mfma_f32_16x16x32_bf16 v[34:37], v[170:173], v[186:189], v[34:37]
	v_mfma_f32_16x16x32_bf16 v[22:25], v[162:165], v[194:197], v[22:25]
	v_mfma_f32_16x16x32_bf16 v[18:21], v[170:173], v[194:197], v[18:21]
	v_mfma_f32_16x16x32_bf16 v[6:9], v[162:165], v[202:205], v[6:9]
	v_mfma_f32_16x16x32_bf16 v[2:5], v[170:173], v[202:205], v[2:5]
	v_mfma_f32_16x16x32_bf16 v[54:57], v[166:169], v[182:185], v[54:57]
	v_mfma_f32_16x16x32_bf16 v[50:53], v[248:251], v[182:185], v[50:53]
	v_mfma_f32_16x16x32_bf16 v[38:41], v[166:169], v[190:193], v[38:41]
	v_mfma_f32_16x16x32_bf16 v[34:37], v[248:251], v[190:193], v[34:37]
	v_mfma_f32_16x16x32_bf16 v[22:25], v[166:169], v[198:201], v[22:25]
	v_mfma_f32_16x16x32_bf16 v[18:21], v[248:251], v[198:201], v[18:21]
	v_mfma_f32_16x16x32_bf16 v[6:9], v[166:169], v[252:255], v[6:9]
	s_barrier
	v_mfma_f32_16x16x32_bf16 v[2:5], v[248:251], v[252:255], v[2:5]
	s_setprio 0
	s_add_i32 s69, s69, 2
	s_add_u32 s67, s67, 0x100
	s_addc_u32 s68, s68, 0
	s_cmpk_gt_u32 s69, 0xa9
	s_mov_b64 s[36:37], s[38:39]
	s_cbranch_scc0 .LBB0_873
	s_and_b64 vcc, exec, s[10:11]
	s_cbranch_vccz .LBB0_876
	s_barrier
